# HgIn f-gate epilogue: removed the dead denormal-input scaling and inf-select of the two logf calls whose argument is always in [1,2] (exact for all finite inputs)
# baseline (speedup 1.0000x reference)
.LBB0_1148:
	global_load_dwordx4 v[48:51], v[78:79], off
	global_load_dwordx4 v[44:47], v[82:83], off
	global_load_dwordx4 v[40:43], v[84:85], off
	v_mul_f32_e64 v58, |v56|, s69
	v_max_f32_e32 v59, v56, v56
	v_mul_f32_e64 v60, |v57|, s69
	v_exp_f32_e32 v67, v58
	v_min_f32_e32 v62, 0, v59
	v_exp_f32_e32 v59, v60
	v_max_f32_e32 v61, v57, v57
	v_mul_f32_e64 v66, |v55|, s69
	v_cmp_lt_f32_e32 vcc, 0, v57
	v_min_f32_e32 v63, 0, v61
	v_exp_f32_e32 v69, v66
	v_add_f32_e32 v66, 1.0, v67
	v_cndmask_b32_e32 v61, 1.0, v59, vcc
	v_cmp_lt_f32_e32 vcc, 0, v56
	v_add_f32_e32 v70, 1.0, v59
	s_nop 0
	v_cndmask_b32_e32 v60, 1.0, v67, vcc
	v_mov_b32_e32 v67, v70
	v_mov_b32_e32 v59, v66
	v_log_f32_e32 v59, v59
	v_log_f32_e32 v67, v67
	v_mul_f32_e64 v64, |v54|, s69
	v_exp_f32_e32 v68, v64
	v_mul_f32_e32 v75, 0x3f317217, v59
	v_mul_f32_e32 v87, 0x3f317217, v67
	v_fma_f32 v75, v59, s75, -v75
	v_fma_f32 v87, v67, s75, -v87
	v_fmac_f32_e32 v75, 0x3377d1cf, v59
	v_rcp_f32_e32 v64, v66
	v_fmac_f32_e32 v87, 0x3377d1cf, v67
	v_fmac_f32_e32 v75, 0x3f317217, v59
	v_max_f32_e32 v65, v54, v54
	v_add_f32_e32 v71, 1.0, v68
	v_fmac_f32_e32 v87, 0x3f317217, v67
	v_mov_b32_e32 v59, v75
	v_min_f32_e32 v58, 0, v65
	v_rcp_f32_e32 v65, v70
	v_mov_b32_e32 v67, v87
	v_mov_b32_e32 v66, v59
	v_mov_b32_e32 v73, v71
	v_pk_add_f32 v[62:63], v[62:63], v[66:67] neg_lo:[0,1] neg_hi:[0,1]
	v_log_f32_e32 v73, v73
	v_add_f32_e32 v72, 1.0, v69
	v_mul_f32_e32 v88, 0x3f317217, v73
	v_fma_f32 v88, v73, s75, -v88
	v_fmac_f32_e32 v88, 0x3377d1cf, v73
	v_fmac_f32_e32 v88, 0x3f317217, v73
	s_waitcnt vmcnt(2)
	v_pk_add_f32 v[62:63], v[62:63], v[48:49]
	s_waitcnt vmcnt(1)
	v_pk_add_f32 v[48:49], v[62:63], v[44:45] neg_lo:[0,1] neg_hi:[0,1]
	v_max_f32_e32 v59, v44, v44
	v_mul_f32_e64 v44, |v48|, s69
	v_max_f32_e32 v66, v45, v45
	v_mul_f32_e64 v45, |v49|, s69
	v_exp_f32_e32 v67, v44
	v_exp_f32_e32 v70, v45
	v_max_f32_e32 v44, v62, v59
	v_mov_b32_e32 v73, v88
	v_add_f32_e32 v59, 1.0, v67
	v_add_f32_e32 v62, 1.0, v70
	v_max_f32_e32 v45, v63, v66
	v_log_f32_e32 v59, v59
	v_log_f32_e32 v62, v62
	v_mul_f32_e32 v67, 0x3f317217, v59
	v_mul_f32_e32 v70, 0x3f317217, v62
	v_fma_f32 v67, v59, s75, -v67
	v_fma_f32 v70, v62, s75, -v70
	v_fmac_f32_e32 v67, 0x3377d1cf, v59
	v_fmac_f32_e32 v70, 0x3377d1cf, v62
	v_fmac_f32_e32 v67, 0x3f317217, v59
	v_fmac_f32_e32 v70, 0x3f317217, v62
	s_waitcnt vmcnt(0)
	v_pk_mul_f32 v[40:41], v[60:61], v[40:41]
	v_mov_b32_e32 v59, v67
	v_mov_b32_e32 v67, v59
	v_pk_mul_f32 v[40:41], v[64:65], v[40:41]
	v_mov_b32_e32 v62, v70
	v_mov_b32_e32 v66, v62
	v_mov_b32_e32 v62, v73
	v_mov_b32_e32 v59, v72
	v_log_f32_e32 v63, v59
	v_max_f32_e32 v59, v55, v55
	v_min_f32_e32 v59, 0, v59
	v_rcp_f32_e32 v60, v71
	v_mul_f32_e32 v70, 0x3f317217, v63
	v_fma_f32 v70, v63, s75, -v70
	v_fmac_f32_e32 v70, 0x3377d1cf, v63
	v_fmac_f32_e32 v70, 0x3f317217, v63
	v_cvt_pk_bf16_f32 v40, v40, v41
	s_nop 0
	v_mov_b32_e32 v63, v70
	v_pk_add_f32 v[58:59], v[58:59], v[62:63] neg_lo:[0,1] neg_hi:[0,1]
	s_nop 0
	v_pk_add_f32 v[50:51], v[58:59], v[50:51]
	s_nop 0
	v_pk_add_f32 v[58:59], v[50:51], v[46:47] neg_lo:[0,1] neg_hi:[0,1]
	v_mul_f32_e64 v62, |v58|, s69
	v_exp_f32_e32 v62, v62
	v_mul_f32_e64 v63, |v59|, s69
	v_exp_f32_e32 v63, v63
	v_max_f32_e32 v46, v50, v46
	v_add_f32_e32 v61, 1.0, v62
	v_add_f32_e32 v63, 1.0, v63
	s_nop 0
	v_log_f32_e32 v62, v61
	v_max_f32_e32 v47, v51, v47
	v_rcp_f32_e32 v61, v72
	v_mul_f32_e32 v50, 0x3f317217, v62
	v_fma_f32 v50, v62, s75, -v50
	v_fmac_f32_e32 v50, 0x3377d1cf, v62
	v_fmac_f32_e32 v50, 0x3f317217, v62
	s_nop 1
	s_nop 0
	v_log_f32_e32 v63, v63
	v_cmp_lt_f32_e64 vcc, |v49|, s49
	v_mul_f32_e32 v51, 0x3f317217, v63
	v_fma_f32 v51, v63, s75, -v51
	v_fmac_f32_e32 v51, 0x3377d1cf, v63
	v_fmac_f32_e32 v51, 0x3f317217, v63
	v_cndmask_b32_e32 v49, 0, v66, vcc
	v_cmp_lt_f32_e64 vcc, |v48|, s49
	s_nop 1
	v_cndmask_b32_e32 v48, 0, v67, vcc
	v_cmp_lt_f32_e64 vcc, |v59|, s49
	v_pk_add_f32 v[44:45], v[44:45], v[48:49]
	s_nop 0
	v_cndmask_b32_e32 v51, 0, v51, vcc
	v_cmp_lt_f32_e64 vcc, |v58|, s49
	s_nop 1
	v_cndmask_b32_e32 v50, 0, v50, vcc
	v_cmp_lt_f32_e32 vcc, 0, v55
	v_pk_add_f32 v[46:47], v[46:47], v[50:51]
	s_nop 0
	v_cndmask_b32_e32 v49, 1.0, v69, vcc
	v_cmp_lt_f32_e32 vcc, 0, v54
	s_nop 1
	v_cndmask_b32_e32 v48, 1.0, v68, vcc
	v_pk_mul_f32 v[42:43], v[48:49], v[42:43]
	v_lshl_add_u64 v[48:49], v[52:53], 2, s[94:95]
	v_pk_mul_f32 v[42:43], v[60:61], v[42:43]
	global_store_dwordx4 v[48:49], v[44:47], off
	v_cvt_pk_bf16_f32 v41, v42, v43
	s_nop 0
	v_lshl_add_u64 v[44:45], v[52:53], 1, s[84:85]
	global_store_dwordx2 v[44:45], v[40:41], off

.LBB0_1213:
	v_mov_b32_e32 v195, v2
	v_or_b32_e32 v170, 4, v194
	v_or_b32_e32 v169, 8, v194
	v_or_b32_e32 v168, 12, v194
	s_and_b64 vcc, exec, s[2:3]
	s_cbranch_vccz .LBB0_1230
	s_mov_b64 s[0:1], -1
	s_and_b64 vcc, exec, s[14:15]
	s_cbranch_vccz .LBB0_1216
	v_lshlrev_b32_e32 v124, 2, v194
	global_load_dwordx4 v[160:163], v124, s[86:87]
	global_load_dwordx4 v[156:159], v124, s[66:67]
	global_load_dwordx4 v[164:167], v124, s[56:57]
	v_mul_f32_e64 v125, |v152|, s69
	v_mul_f32_e64 v129, |v153|, s69
	v_exp_f32_e32 v125, v125
	v_exp_f32_e32 v146, v129
	v_mul_f32_e64 v137, |v154|, s69
	v_max_f32_e32 v142, v154, v154
	v_cmp_lt_f32_e32 vcc, 0, v153
	v_max_f32_e32 v136, v153, v153
	v_mul_f32_e64 v143, |v155|, s69
	v_exp_f32_e32 v171, v137
	v_min_f32_e32 v124, 0, v142
	v_add_f32_e32 v142, 1.0, v125
	v_cndmask_b32_e32 v137, 1.0, v146, vcc
	v_cmp_lt_f32_e32 vcc, 0, v152
	v_min_f32_e32 v129, 0, v136
	v_exp_f32_e32 v180, v143
	v_add_f32_e32 v143, 1.0, v146
	v_cndmask_b32_e32 v136, 1.0, v125, vcc
	v_rcp_f32_e32 v147, v143
	v_mov_b32_e32 v125, v142
	v_log_f32_e32 v125, v125
	v_log_f32_e32 v143, v143
	v_rcp_f32_e32 v146, v142
	v_mul_f32_e32 v184, 0x3f317217, v125
	v_mul_f32_e32 v185, 0x3f317217, v143
	v_fma_f32 v184, v125, s75, -v184
	v_fma_f32 v185, v143, s75, -v185
	v_fmac_f32_e32 v184, 0x3377d1cf, v125
	v_fmac_f32_e32 v185, 0x3377d1cf, v143
	v_fmac_f32_e32 v184, 0x3f317217, v125
	v_add_f32_e32 v181, 1.0, v171
	v_fmac_f32_e32 v185, 0x3f317217, v143
	v_mov_b32_e32 v125, v184
	v_max_f32_e32 v128, v152, v152
	v_mov_b32_e32 v143, v185
	v_min_f32_e32 v128, 0, v128
	v_mov_b32_e32 v142, v125
	v_mov_b32_e32 v151, v181
	v_pk_add_f32 v[128:129], v[128:129], v[142:143] neg_lo:[0,1] neg_hi:[0,1]
	v_log_f32_e32 v151, v151
	v_add_f32_e32 v182, 1.0, v180
	v_mov_b32_e32 v183, 0
	s_mov_b64 s[0:1], 0
	v_mul_f32_e32 v186, 0x3f317217, v151
	v_fma_f32 v186, v151, s75, -v186
	v_fmac_f32_e32 v186, 0x3377d1cf, v151
	v_fmac_f32_e32 v186, 0x3f317217, v151
	s_waitcnt vmcnt(0)
	v_pk_add_f32 v[128:129], v[128:129], v[160:161]
	s_nop 0
	v_pk_add_f32 v[142:143], v[128:129], v[156:157] neg_lo:[0,1] neg_hi:[0,1]
	v_max_f32_e32 v125, v156, v156
	v_mul_f32_e64 v156, |v142|, s69
	v_max_f32_e32 v150, v157, v157
	v_mul_f32_e64 v157, |v143|, s69
	v_exp_f32_e32 v156, v156
	v_exp_f32_e32 v157, v157
	v_max_f32_e32 v128, v128, v125
	v_mov_b32_e32 v151, v186
	v_add_f32_e32 v125, 1.0, v156
	v_max_f32_e32 v129, v129, v150
	v_add_f32_e32 v150, 1.0, v157
	s_nop 0
	v_log_f32_e32 v125, v125
	v_log_f32_e32 v150, v150
	v_mul_f32_e32 v160, 0x3f317217, v125
	v_mul_f32_e32 v161, 0x3f317217, v150
	v_fma_f32 v160, v125, s75, -v160
	v_fma_f32 v161, v150, s75, -v161
	v_fmac_f32_e32 v160, 0x3377d1cf, v125
	v_fmac_f32_e32 v161, 0x3377d1cf, v150
	v_fmac_f32_e32 v160, 0x3f317217, v125
	v_fmac_f32_e32 v161, 0x3f317217, v150
	s_nop 0
	v_mov_b32_e32 v125, v160
	v_mov_b32_e32 v160, v125
	s_nop 0
	v_mov_b32_e32 v150, v161
	v_mov_b32_e32 v161, v150
	v_mov_b32_e32 v150, v151
	v_mov_b32_e32 v125, v182
	v_log_f32_e32 v156, v125
	v_max_f32_e32 v125, v155, v155
	v_min_f32_e32 v125, 0, v125
	v_mul_f32_e32 v151, 0x3f317217, v156
	v_fma_f32 v151, v156, s75, -v151
	v_fmac_f32_e32 v151, 0x3377d1cf, v156
	v_fmac_f32_e32 v151, 0x3f317217, v156
	s_nop 1
	v_pk_add_f32 v[124:125], v[124:125], v[150:151] neg_lo:[0,1] neg_hi:[0,1]
	s_nop 0
	v_pk_add_f32 v[150:151], v[124:125], v[162:163]
	s_nop 0
	v_pk_add_f32 v[156:157], v[150:151], v[158:159] neg_lo:[0,1] neg_hi:[0,1]
	s_nop 0
	v_mul_f32_e64 v124, |v156|, s69
	v_exp_f32_e32 v162, v124
	v_pk_mul_f32 v[124:125], v[136:137], v[164:165]
	v_rcp_f32_e32 v136, v181
	v_pk_mul_f32 v[124:125], v[146:147], v[124:125]
	v_add_f32_e32 v137, 1.0, v162
	s_nop 1
	v_log_f32_e32 v147, v137
	v_max_f32_e32 v146, v158, v158
	v_mul_f32_e64 v158, |v157|, s69
	v_exp_f32_e32 v158, v158
	v_max_f32_e32 v146, v150, v146
	v_mul_f32_e32 v150, 0x3f317217, v147
	v_fma_f32 v150, v147, s75, -v150
	v_fmac_f32_e32 v150, 0x3377d1cf, v147
	v_fmac_f32_e32 v150, 0x3f317217, v147
	v_add_f32_e32 v158, 1.0, v158
	v_rcp_f32_e32 v137, v182
	v_mov_b32_e32 v147, v150
	v_mov_b32_e32 v150, v147
	s_nop 0
	v_mov_b32_e32 v162, 0
	v_log_f32_e32 v158, v158
	v_max_f32_e32 v147, v151, v159
	v_mul_f32_e32 v151, 0x3f317217, v158
	v_fma_f32 v151, v158, s75, -v151
	v_fmac_f32_e32 v151, 0x3377d1cf, v158
	v_fmac_f32_e32 v151, 0x3f317217, v158
	s_nop 1
	v_cmp_lt_f32_e64 vcc, |v143|, s49
	s_nop 0
	s_nop 0
	v_cndmask_b32_e32 v143, 0, v161, vcc
	v_cmp_lt_f32_e64 vcc, |v142|, s49
	s_nop 1
	v_cndmask_b32_e32 v142, 0, v160, vcc
	v_cmp_lt_f32_e64 vcc, |v157|, s49
	s_nop 1
	v_cndmask_b32_e32 v151, 0, v151, vcc
	v_cmp_lt_f32_e64 vcc, |v156|, s49
	v_pk_add_f32 v[156:157], v[128:129], v[142:143]
	s_nop 0
	v_cndmask_b32_e32 v150, 0, v150, vcc
	v_cmp_lt_f32_e32 vcc, 0, v155
	v_pk_add_f32 v[158:159], v[146:147], v[150:151]
	s_nop 0
	v_cndmask_b32_e32 v129, 1.0, v180, vcc
	v_cmp_lt_f32_e32 vcc, 0, v154
	s_nop 1
	v_cndmask_b32_e32 v128, 1.0, v171, vcc
	v_pk_mul_f32 v[128:129], v[128:129], v[166:167]
	s_nop 0
	v_pk_mul_f32 v[128:129], v[136:137], v[128:129]
	v_lshl_add_u64 v[136:137], v[210:211], 2, s[94:95]
	global_store_dwordx4 v[136:137], v[156:159], off

.LBB0_1218:
	s_add_u32 s0, s22, s0
	s_addc_u32 s1, s23, s1
	v_lshl_add_u64 v[136:137], v[210:211], 1, s[0:1]
	v_cvt_pk_bf16_f32 v124, v124, v125
	v_cvt_pk_bf16_f32 v125, v128, v129
	v_mov_b32_e32 v209, v208
	global_store_dwordx2 v[136:137], v[124:125], off
	v_pk_mul_f32 v[124:125], v[138:139], v[208:209]
	s_mov_b64 s[0:1], -1
	s_and_b64 vcc, exec, s[14:15]
	s_cbranch_vccz .LBB0_1220
	v_lshlrev_b32_e32 v128, 2, v194
	v_lshlrev_b32_e32 v142, 2, v170
	global_load_dwordx4 v[150:153], v128, s[86:87] offset:16
	global_load_dwordx4 v[136:139], v142, s[66:67]
	global_load_dwordx4 v[154:157], v142, s[56:57]
	v_mul_f32_e64 v143, |v148|, s69
	v_max_f32_e32 v146, v148, v148
	v_mul_f32_e64 v147, |v149|, s69
	v_exp_f32_e32 v143, v143
	v_min_f32_e32 v158, 0, v146
	v_exp_f32_e32 v146, v147
	v_mul_f32_e64 v162, |v125|, s69
	v_exp_f32_e32 v165, v162
	v_add_f32_e32 v162, 1.0, v143
	v_cmp_lt_f32_e32 vcc, 0, v149
	v_add_f32_e32 v163, 1.0, v146
	s_nop 0
	v_cndmask_b32_e32 v147, 1.0, v146, vcc
	v_cmp_lt_f32_e32 vcc, 0, v148
	v_max_f32_e32 v161, v124, v124
	s_nop 0
	v_cndmask_b32_e32 v146, 1.0, v143, vcc
	v_mov_b32_e32 v143, v162
	v_min_f32_e32 v142, 0, v161
	v_rcp_f32_e32 v161, v163
	v_log_f32_e32 v143, v143
	v_mul_f32_e64 v160, |v124|, s69
	v_log_f32_e32 v163, v163
	v_exp_f32_e32 v164, v160
	v_mul_f32_e32 v180, 0x3f317217, v143
	v_fma_f32 v180, v143, s75, -v180
	v_mul_f32_e32 v181, 0x3f317217, v163
	v_add_f32_e32 v166, 1.0, v164
	v_fma_f32 v181, v163, s75, -v181
	v_fmac_f32_e32 v180, 0x3377d1cf, v143
	v_rcp_f32_e32 v160, v162
	v_fmac_f32_e32 v181, 0x3377d1cf, v163
	v_fmac_f32_e32 v180, 0x3f317217, v143
	v_fmac_f32_e32 v181, 0x3f317217, v163
	v_mov_b32_e32 v143, v180
	v_max_f32_e32 v159, v149, v149
	v_mov_b32_e32 v167, v166
	v_mov_b32_e32 v163, v181
	v_min_f32_e32 v159, 0, v159
	v_mov_b32_e32 v162, v143
	v_pk_add_f32 v[158:159], v[158:159], v[162:163] neg_lo:[0,1] neg_hi:[0,1]
	v_log_f32_e32 v167, v167
	v_or_b32_e32 v128, v206, v170
	v_mov_b32_e32 v129, v207
	v_lshl_add_u64 v[128:129], v[128:129], 2, s[94:95]
	v_mul_f32_e32 v182, 0x3f317217, v167
	v_fma_f32 v182, v167, s75, -v182
	v_fmac_f32_e32 v182, 0x3377d1cf, v167
	v_fmac_f32_e32 v182, 0x3f317217, v167
	s_mov_b64 s[0:1], 0
	s_waitcnt vmcnt(0)
	v_pk_add_f32 v[150:151], v[158:159], v[150:151]
	s_nop 0
	v_pk_add_f32 v[158:159], v[150:151], v[136:137] neg_lo:[0,1] neg_hi:[0,1]
	v_max_f32_e32 v143, v136, v136
	v_mul_f32_e64 v136, |v158|, s69
	v_max_f32_e32 v162, v137, v137
	v_mul_f32_e64 v137, |v159|, s69
	v_exp_f32_e32 v136, v136
	v_exp_f32_e32 v137, v137
	v_mov_b32_e32 v167, v182
	v_max_f32_e32 v150, v150, v143
	v_add_f32_e32 v136, 1.0, v136
	v_add_f32_e32 v137, 1.0, v137
	v_max_f32_e32 v151, v151, v162
	v_log_f32_e32 v136, v136
	v_log_f32_e32 v137, v137
	v_mul_f32_e32 v163, 0x3f317217, v136
	v_mul_f32_e32 v171, 0x3f317217, v137
	v_fma_f32 v163, v136, s75, -v163
	v_fma_f32 v171, v137, s75, -v171
	v_fmac_f32_e32 v163, 0x3377d1cf, v136
	v_fmac_f32_e32 v171, 0x3377d1cf, v137
	v_fmac_f32_e32 v163, 0x3f317217, v136
	v_fmac_f32_e32 v171, 0x3f317217, v137
	s_nop 0
	v_mov_b32_e32 v136, v163
	v_mov_b32_e32 v163, v136
	v_mov_b32_e32 v137, v171
	v_add_f32_e32 v171, 1.0, v165
	v_mov_b32_e32 v162, v137
	v_mov_b32_e32 v136, v167
	v_mov_b32_e32 v137, v171
	v_log_f32_e32 v137, v137
	v_max_f32_e32 v143, v125, v125
	v_min_f32_e32 v143, 0, v143
	v_mul_f32_e32 v167, 0x3f317217, v137
	v_fma_f32 v167, v137, s75, -v167
	v_fmac_f32_e32 v167, 0x3377d1cf, v137
	v_fmac_f32_e32 v167, 0x3f317217, v137
	s_nop 1
	v_mov_b32_e32 v137, v167
	v_pk_add_f32 v[136:137], v[142:143], v[136:137] neg_lo:[0,1] neg_hi:[0,1]
	s_nop 0
	v_pk_add_f32 v[142:143], v[136:137], v[152:153]
	s_nop 0
	v_pk_add_f32 v[152:153], v[142:143], v[138:139] neg_lo:[0,1] neg_hi:[0,1]
	v_mul_f32_e64 v136, |v152|, s69
	v_exp_f32_e32 v167, v136
	v_pk_mul_f32 v[136:137], v[146:147], v[154:155]
	v_mul_f32_e64 v155, |v153|, s69
	v_exp_f32_e32 v155, v155
	v_add_f32_e32 v147, 1.0, v167
	v_max_f32_e32 v138, v142, v138
	v_add_f32_e32 v155, 1.0, v155
	v_log_f32_e32 v154, v147
	v_pk_mul_f32 v[136:137], v[160:161], v[136:137]
	v_max_f32_e32 v139, v143, v139
	v_mul_f32_e32 v142, 0x3f317217, v154
	v_fma_f32 v142, v154, s75, -v142
	v_fmac_f32_e32 v142, 0x3377d1cf, v154
	v_fmac_f32_e32 v142, 0x3f317217, v154
	v_rcp_f32_e32 v146, v166
	v_rcp_f32_e32 v147, v171
	v_mov_b32_e32 v154, v142
	s_nop 0
	v_mov_b32_e32 v160, 0
	v_log_f32_e32 v155, v155
	v_cmp_lt_f32_e64 vcc, |v159|, s49
	v_mul_f32_e32 v142, 0x3f317217, v155
	v_fma_f32 v142, v155, s75, -v142
	v_fmac_f32_e32 v142, 0x3377d1cf, v155
	v_fmac_f32_e32 v142, 0x3f317217, v155
	s_nop 1
	v_mov_b32_e32 v155, v142
	v_cndmask_b32_e32 v143, 0, v162, vcc
	v_cmp_lt_f32_e64 vcc, |v158|, s49
	s_nop 1
	v_cndmask_b32_e32 v142, 0, v163, vcc
	v_cmp_lt_f32_e64 vcc, |v153|, s49
	v_pk_add_f32 v[150:151], v[150:151], v[142:143]
	s_nop 0
	v_cndmask_b32_e32 v153, 0, v155, vcc
	v_cmp_lt_f32_e64 vcc, |v152|, s49
	s_nop 1
	v_cndmask_b32_e32 v152, 0, v154, vcc
	v_cmp_lt_f32_e32 vcc, 0, v125
	v_pk_add_f32 v[152:153], v[138:139], v[152:153]
	global_store_dwordx4 v[128:129], v[150:153], off
	v_cndmask_b32_e32 v139, 1.0, v165, vcc
	v_cmp_lt_f32_e32 vcc, 0, v124
	s_nop 1
	v_cndmask_b32_e32 v138, 1.0, v164, vcc
	v_pk_mul_f32 v[138:139], v[138:139], v[156:157]
	s_nop 0
	v_pk_mul_f32 v[138:139], v[146:147], v[138:139]

.LBB0_1222:
	s_add_u32 s0, s22, s0
	s_addc_u32 s1, s23, s1
	v_lshl_add_u64 v[124:125], v[206:207], 0, v[194:195]
	v_mov_b32_e32 v209, v208
	v_lshl_add_u64 v[128:129], v[124:125], 1, s[0:1]
	v_cvt_pk_bf16_f32 v136, v136, v137
	v_cvt_pk_bf16_f32 v137, v138, v139
	v_pk_mul_f32 v[142:143], v[130:131], v[208:209]
	s_mov_b64 s[0:1], -1
	s_and_b64 vcc, exec, s[14:15]
	global_store_dwordx2 v[128:129], v[136:137], off offset:8
	s_cbranch_vccz .LBB0_1224
	v_lshlrev_b32_e32 v128, 2, v194
	v_lshlrev_b32_e32 v146, 2, v169
	global_load_dwordx4 v[136:139], v128, s[86:87] offset:32
	s_nop 0
	global_load_dwordx4 v[128:131], v146, s[66:67]
	v_mul_f32_e64 v152, |v144|, s69
	global_load_dwordx4 v[146:149], v146, s[56:57]
	v_max_f32_e32 v153, v144, v144
	v_mul_f32_e64 v154, |v145|, s69
	v_exp_f32_e32 v161, v152
	v_min_f32_e32 v156, 0, v153
	v_exp_f32_e32 v153, v154
	v_mul_f32_e64 v160, |v143|, s69
	v_exp_f32_e32 v163, v160
	v_add_f32_e32 v160, 1.0, v161
	v_max_f32_e32 v155, v145, v145
	v_add_f32_e32 v164, 1.0, v153
	v_cmp_lt_f32_e32 vcc, 0, v145
	v_min_f32_e32 v157, 0, v155
	s_nop 0
	v_cndmask_b32_e32 v155, 1.0, v153, vcc
	v_cmp_lt_f32_e32 vcc, 0, v144
	s_nop 1
	v_cndmask_b32_e32 v154, 1.0, v161, vcc
	v_mov_b32_e32 v153, v160
	v_mov_b32_e32 v161, v164
	v_log_f32_e32 v153, v153
	v_mul_f32_e64 v158, |v142|, s69
	v_log_f32_e32 v161, v161
	v_exp_f32_e32 v162, v158
	v_mul_f32_e32 v167, 0x3f317217, v153
	v_fma_f32 v167, v153, s75, -v167
	v_mul_f32_e32 v171, 0x3f317217, v161
	v_add_f32_e32 v165, 1.0, v162
	v_fma_f32 v171, v161, s75, -v171
	v_fmac_f32_e32 v167, 0x3377d1cf, v153
	v_rcp_f32_e32 v158, v160
	v_fmac_f32_e32 v171, 0x3377d1cf, v161
	v_fmac_f32_e32 v167, 0x3f317217, v153
	v_max_f32_e32 v159, v142, v142
	v_fmac_f32_e32 v171, 0x3f317217, v161
	v_mov_b32_e32 v153, v167
	v_min_f32_e32 v152, 0, v159
	v_rcp_f32_e32 v159, v164
	v_mov_b32_e32 v164, v165
	v_mov_b32_e32 v161, v171
	v_mov_b32_e32 v160, v153
	v_pk_add_f32 v[156:157], v[156:157], v[160:161] neg_lo:[0,1] neg_hi:[0,1]
	v_log_f32_e32 v164, v164
	v_or_b32_e32 v150, v206, v169
	v_mov_b32_e32 v151, v207
	s_mov_b64 s[0:1], 0
	v_mul_f32_e32 v180, 0x3f317217, v164
	v_fma_f32 v180, v164, s75, -v180
	v_fmac_f32_e32 v180, 0x3377d1cf, v164
	v_fmac_f32_e32 v180, 0x3f317217, v164
	s_waitcnt vmcnt(0)
	v_pk_add_f32 v[136:137], v[156:157], v[136:137]
	s_nop 0
	v_pk_add_f32 v[156:157], v[136:137], v[128:129] neg_lo:[0,1] neg_hi:[0,1]
	v_max_f32_e32 v153, v128, v128
	v_mul_f32_e64 v128, |v156|, s69
	v_max_f32_e32 v160, v129, v129
	v_mul_f32_e64 v129, |v157|, s69
	v_exp_f32_e32 v128, v128
	v_exp_f32_e32 v129, v129
	v_mov_b32_e32 v164, v180
	v_max_f32_e32 v136, v136, v153
	v_add_f32_e32 v128, 1.0, v128
	v_add_f32_e32 v129, 1.0, v129
	v_max_f32_e32 v137, v137, v160
	v_log_f32_e32 v128, v128
	v_log_f32_e32 v129, v129
	v_mul_f32_e32 v161, 0x3f317217, v128
	v_mul_f32_e32 v166, 0x3f317217, v129
	v_fma_f32 v161, v128, s75, -v161
	v_fma_f32 v166, v129, s75, -v166
	v_fmac_f32_e32 v161, 0x3377d1cf, v128
	v_fmac_f32_e32 v166, 0x3377d1cf, v129
	v_fmac_f32_e32 v161, 0x3f317217, v128
	v_fmac_f32_e32 v166, 0x3f317217, v129
	s_nop 0
	v_mov_b32_e32 v128, v161
	v_mov_b32_e32 v161, v128
	v_mov_b32_e32 v129, v166
	v_add_f32_e32 v166, 1.0, v163
	v_mov_b32_e32 v160, v129
	v_mov_b32_e32 v128, v164
	v_mov_b32_e32 v129, v166
	v_log_f32_e32 v129, v129
	v_max_f32_e32 v153, v143, v143
	v_min_f32_e32 v153, 0, v153
	v_mul_f32_e32 v164, 0x3f317217, v129
	v_fma_f32 v164, v129, s75, -v164
	v_fmac_f32_e32 v164, 0x3377d1cf, v129
	v_fmac_f32_e32 v164, 0x3f317217, v129
	s_nop 1
	v_mov_b32_e32 v129, v164
	v_pk_add_f32 v[128:129], v[152:153], v[128:129] neg_lo:[0,1] neg_hi:[0,1]
	s_nop 0
	v_pk_add_f32 v[138:139], v[128:129], v[138:139]
	s_nop 0
	v_pk_add_f32 v[152:153], v[138:139], v[130:131] neg_lo:[0,1] neg_hi:[0,1]
	v_mul_f32_e64 v128, |v152|, s69
	v_exp_f32_e32 v164, v128
	v_pk_mul_f32 v[128:129], v[154:155], v[146:147]
	v_mul_f32_e64 v155, |v153|, s69
	v_exp_f32_e32 v155, v155
	v_add_f32_e32 v147, 1.0, v164
	v_max_f32_e32 v130, v138, v130
	v_add_f32_e32 v155, 1.0, v155
	v_log_f32_e32 v154, v147
	v_pk_mul_f32 v[128:129], v[158:159], v[128:129]
	v_max_f32_e32 v131, v139, v131
	v_mul_f32_e32 v138, 0x3f317217, v154
	v_fma_f32 v138, v154, s75, -v138
	v_fmac_f32_e32 v138, 0x3377d1cf, v154
	v_fmac_f32_e32 v138, 0x3f317217, v154
	v_rcp_f32_e32 v146, v165
	v_rcp_f32_e32 v147, v166
	s_nop 0
	v_mov_b32_e32 v158, 0
	v_log_f32_e32 v155, v155
	v_cmp_lt_f32_e64 vcc, |v157|, s49
	v_mul_f32_e32 v139, 0x3f317217, v155
	v_fma_f32 v139, v155, s75, -v139
	v_fmac_f32_e32 v139, 0x3377d1cf, v155
	v_fmac_f32_e32 v139, 0x3f317217, v155
	s_nop 1
	v_cndmask_b32_e32 v155, 0, v160, vcc
	v_cmp_lt_f32_e64 vcc, |v156|, s49
	s_nop 0
	s_nop 0
	v_cndmask_b32_e32 v154, 0, v161, vcc
	v_cmp_lt_f32_e64 vcc, |v153|, s49
	v_pk_add_f32 v[136:137], v[136:137], v[154:155]
	s_nop 0
	v_cndmask_b32_e32 v139, 0, v139, vcc
	v_cmp_lt_f32_e64 vcc, |v152|, s49
	s_nop 1
	v_cndmask_b32_e32 v138, 0, v138, vcc
	v_cmp_lt_f32_e32 vcc, 0, v143
	v_pk_add_f32 v[138:139], v[130:131], v[138:139]
	s_nop 0
	v_cndmask_b32_e32 v131, 1.0, v163, vcc
	v_cmp_lt_f32_e32 vcc, 0, v142
	s_nop 1
	v_cndmask_b32_e32 v130, 1.0, v162, vcc
	v_pk_mul_f32 v[130:131], v[130:131], v[148:149]
	s_nop 0
	v_pk_mul_f32 v[130:131], v[146:147], v[130:131]
	v_lshl_add_u64 v[146:147], v[150:151], 2, s[94:95]
	global_store_dwordx4 v[146:147], v[136:139], off

.LBB0_1226:
	s_add_u32 s0, s22, s0
	s_addc_u32 s1, s23, s1
	v_mov_b32_e32 v209, v208
	v_lshl_add_u64 v[124:125], v[124:125], 1, s[0:1]
	v_cvt_pk_bf16_f32 v128, v128, v129
	v_cvt_pk_bf16_f32 v129, v130, v131
	v_or_b32_e32 v206, v206, v168
	v_pk_mul_f32 v[142:143], v[126:127], v[208:209]
	s_mov_b64 s[0:1], -1
	s_and_b64 vcc, exec, s[14:15]
	global_store_dwordx2 v[124:125], v[128:129], off offset:16
	s_cbranch_vccz .LBB0_1228
	v_lshlrev_b32_e32 v124, 2, v194
	v_lshlrev_b32_e32 v136, 2, v168
	global_load_dwordx4 v[128:131], v124, s[86:87] offset:48
	s_nop 0
	global_load_dwordx4 v[124:127], v136, s[66:67]
	v_mul_f32_e64 v144, |v140|, s69
	global_load_dwordx4 v[136:139], v136, s[56:57]
	v_max_f32_e32 v145, v140, v140
	v_mul_f32_e64 v146, |v141|, s69
	v_exp_f32_e32 v153, v144
	v_min_f32_e32 v148, 0, v145
	v_exp_f32_e32 v145, v146
	v_max_f32_e32 v147, v141, v141
	v_mul_f32_e64 v152, |v143|, s69
	v_cmp_lt_f32_e32 vcc, 0, v141
	v_min_f32_e32 v149, 0, v147
	v_exp_f32_e32 v155, v152
	v_add_f32_e32 v152, 1.0, v153
	v_cndmask_b32_e32 v147, 1.0, v145, vcc
	v_cmp_lt_f32_e32 vcc, 0, v140
	v_add_f32_e32 v156, 1.0, v145
	s_nop 0
	v_cndmask_b32_e32 v146, 1.0, v153, vcc
	v_mov_b32_e32 v153, v156
	v_mov_b32_e32 v145, v152
	v_log_f32_e32 v145, v145
	v_log_f32_e32 v153, v153
	v_mul_f32_e64 v150, |v142|, s69
	v_exp_f32_e32 v154, v150
	v_mul_f32_e32 v161, 0x3f317217, v145
	v_mul_f32_e32 v162, 0x3f317217, v153
	v_fma_f32 v161, v145, s75, -v161
	v_fma_f32 v162, v153, s75, -v162
	v_fmac_f32_e32 v161, 0x3377d1cf, v145
	v_rcp_f32_e32 v150, v152
	v_fmac_f32_e32 v162, 0x3377d1cf, v153
	v_fmac_f32_e32 v161, 0x3f317217, v145
	v_max_f32_e32 v151, v142, v142
	v_add_f32_e32 v157, 1.0, v154
	v_fmac_f32_e32 v162, 0x3f317217, v153
	v_mov_b32_e32 v145, v161
	v_min_f32_e32 v144, 0, v151
	v_rcp_f32_e32 v151, v156
	v_mov_b32_e32 v153, v162
	v_mov_b32_e32 v152, v145
	v_mov_b32_e32 v159, v157
	v_pk_add_f32 v[148:149], v[148:149], v[152:153] neg_lo:[0,1] neg_hi:[0,1]
	v_log_f32_e32 v159, v159
	v_add_f32_e32 v158, 1.0, v155
	v_mov_b32_e32 v160, 0
	s_mov_b64 s[0:1], 0
	v_mul_f32_e32 v163, 0x3f317217, v159
	v_fma_f32 v163, v159, s75, -v163
	v_fmac_f32_e32 v163, 0x3377d1cf, v159
	v_fmac_f32_e32 v163, 0x3f317217, v159
	s_waitcnt vmcnt(0)
	v_pk_add_f32 v[148:149], v[148:149], v[128:129]
	s_nop 0
	v_pk_add_f32 v[128:129], v[148:149], v[124:125] neg_lo:[0,1] neg_hi:[0,1]
	v_max_f32_e32 v145, v124, v124
	v_mul_f32_e64 v124, |v128|, s69
	v_max_f32_e32 v152, v125, v125
	v_mul_f32_e64 v125, |v129|, s69
	v_exp_f32_e32 v153, v124
	v_exp_f32_e32 v156, v125
	v_max_f32_e32 v124, v148, v145
	v_mov_b32_e32 v159, v163
	v_add_f32_e32 v145, 1.0, v153
	v_add_f32_e32 v148, 1.0, v156
	v_max_f32_e32 v125, v149, v152
	v_log_f32_e32 v145, v145
	v_log_f32_e32 v148, v148
	v_mul_f32_e32 v153, 0x3f317217, v145
	v_mul_f32_e32 v156, 0x3f317217, v148
	v_fma_f32 v153, v145, s75, -v153
	v_fma_f32 v156, v148, s75, -v156
	v_fmac_f32_e32 v153, 0x3377d1cf, v145
	v_fmac_f32_e32 v156, 0x3377d1cf, v148
	v_fmac_f32_e32 v153, 0x3f317217, v145
	v_fmac_f32_e32 v156, 0x3f317217, v148
	v_pk_mul_f32 v[136:137], v[146:147], v[136:137]
	v_mov_b32_e32 v145, v153
	v_mov_b32_e32 v153, v145
	v_pk_mul_f32 v[136:137], v[150:151], v[136:137]
	v_mov_b32_e32 v148, v156
	v_mov_b32_e32 v152, v148
	v_mov_b32_e32 v148, v159
	v_mov_b32_e32 v145, v158
	v_log_f32_e32 v149, v145
	v_max_f32_e32 v145, v143, v143
	v_min_f32_e32 v145, 0, v145
	v_rcp_f32_e32 v146, v157
	v_mul_f32_e32 v156, 0x3f317217, v149
	v_fma_f32 v156, v149, s75, -v156
	v_fmac_f32_e32 v156, 0x3377d1cf, v149
	v_fmac_f32_e32 v156, 0x3f317217, v149
	s_nop 1
	v_mov_b32_e32 v149, v156
	v_pk_add_f32 v[144:145], v[144:145], v[148:149] neg_lo:[0,1] neg_hi:[0,1]
	s_nop 0
	v_pk_add_f32 v[130:131], v[144:145], v[130:131]
	s_nop 0
	v_pk_add_f32 v[144:145], v[130:131], v[126:127] neg_lo:[0,1] neg_hi:[0,1]
	v_mul_f32_e64 v148, |v144|, s69
	v_exp_f32_e32 v148, v148
	v_mul_f32_e64 v149, |v145|, s69
	v_exp_f32_e32 v149, v149
	v_max_f32_e32 v126, v130, v126
	v_add_f32_e32 v147, 1.0, v148
	v_add_f32_e32 v149, 1.0, v149
	s_nop 0
	v_log_f32_e32 v148, v147
	v_max_f32_e32 v127, v131, v127
	v_rcp_f32_e32 v147, v158
	v_mul_f32_e32 v130, 0x3f317217, v148
	v_fma_f32 v130, v148, s75, -v130
	v_fmac_f32_e32 v130, 0x3377d1cf, v148
	v_fmac_f32_e32 v130, 0x3f317217, v148
	s_nop 1
	s_nop 0
	v_mov_b32_e32 v150, 0
	v_log_f32_e32 v149, v149
	v_mov_b32_e32 v148, 0
	v_cmp_lt_f32_e64 vcc, |v129|, s49
	v_mul_f32_e32 v131, 0x3f317217, v149
	v_fma_f32 v131, v149, s75, -v131
	v_fmac_f32_e32 v131, 0x3377d1cf, v149
	v_fmac_f32_e32 v131, 0x3f317217, v149
	v_cndmask_b32_e32 v129, 0, v152, vcc
	v_cmp_lt_f32_e64 vcc, |v128|, s49
	s_nop 1
	v_cndmask_b32_e32 v128, 0, v153, vcc
	v_cmp_lt_f32_e64 vcc, |v145|, s49
	v_pk_add_f32 v[124:125], v[124:125], v[128:129]
	s_nop 0
	v_cndmask_b32_e32 v131, 0, v131, vcc
	v_cmp_lt_f32_e64 vcc, |v144|, s49
	s_nop 1
	v_cndmask_b32_e32 v130, 0, v130, vcc
	v_cmp_lt_f32_e32 vcc, 0, v143
	v_pk_add_f32 v[126:127], v[126:127], v[130:131]
	v_lshl_add_u64 v[130:131], v[206:207], 2, s[94:95]
	v_cndmask_b32_e32 v129, 1.0, v155, vcc
	v_cmp_lt_f32_e32 vcc, 0, v142
	global_store_dwordx4 v[130:131], v[124:127], off
	s_nop 0
	v_cndmask_b32_e32 v128, 1.0, v154, vcc
	v_pk_mul_f32 v[128:129], v[128:129], v[138:139]
	v_lshl_add_u64 v[124:125], v[206:207], 1, s[84:85]
	v_pk_mul_f32 v[128:129], v[146:147], v[128:129]
	v_cvt_pk_bf16_f32 v126, v136, v137
	v_cvt_pk_bf16_f32 v127, v128, v129
	global_store_dwordx2 v[124:125], v[126:127], off

.LBB0_1249:
	v_cndmask_b32_e64 v104, 0, 1, s[14:15]
	s_and_b64 vcc, exec, s[0:1]
	v_cmp_ne_u32_e64 s[10:11], 1, v104
	s_cbranch_vccz .LBB0_1266
	s_and_b64 vcc, exec, s[10:11]
	s_mov_b64 s[0:1], -1
	s_cbranch_vccnz .LBB0_1252
	v_lshlrev_b32_e32 v104, 2, v194
	global_load_dwordx4 v[140:143], v104, s[86:87]
	global_load_dwordx4 v[136:139], v104, s[66:67]
	global_load_dwordx4 v[144:147], v104, s[56:57]
	v_mul_f32_e64 v105, |v132|, s69
	v_mul_f32_e64 v109, |v133|, s69
	v_exp_f32_e32 v105, v105
	v_exp_f32_e32 v126, v109
	v_mul_f32_e64 v113, |v134|, s69
	v_max_f32_e32 v122, v134, v134
	v_cmp_lt_f32_e32 vcc, 0, v133
	v_max_f32_e32 v112, v133, v133
	v_mul_f32_e64 v123, |v135|, s69
	v_exp_f32_e32 v148, v113
	v_min_f32_e32 v104, 0, v122
	v_add_f32_e32 v122, 1.0, v105
	v_cndmask_b32_e32 v113, 1.0, v126, vcc
	v_cmp_lt_f32_e32 vcc, 0, v132
	v_min_f32_e32 v109, 0, v112
	v_exp_f32_e32 v149, v123
	v_add_f32_e32 v123, 1.0, v126
	v_cndmask_b32_e32 v112, 1.0, v105, vcc
	v_rcp_f32_e32 v127, v123
	v_mov_b32_e32 v105, v122
	v_log_f32_e32 v105, v105
	v_log_f32_e32 v123, v123
	v_rcp_f32_e32 v126, v122
	v_mul_f32_e32 v158, 0x3f317217, v105
	v_mul_f32_e32 v159, 0x3f317217, v123
	v_fma_f32 v158, v105, s75, -v158
	v_fma_f32 v159, v123, s75, -v159
	v_fmac_f32_e32 v158, 0x3377d1cf, v105
	v_fmac_f32_e32 v159, 0x3377d1cf, v123
	v_fmac_f32_e32 v158, 0x3f317217, v105
	v_add_f32_e32 v150, 1.0, v148
	v_fmac_f32_e32 v159, 0x3f317217, v123
	v_mov_b32_e32 v105, v158
	v_max_f32_e32 v108, v132, v132
	v_mov_b32_e32 v123, v159
	v_min_f32_e32 v108, 0, v108
	v_mov_b32_e32 v122, v105
	v_mov_b32_e32 v131, v150
	v_pk_add_f32 v[108:109], v[108:109], v[122:123] neg_lo:[0,1] neg_hi:[0,1]
	v_log_f32_e32 v131, v131
	v_add_f32_e32 v151, 1.0, v149
	s_mov_b64 s[0:1], 0
	v_mul_f32_e32 v160, 0x3f317217, v131
	v_fma_f32 v160, v131, s75, -v160
	v_fmac_f32_e32 v160, 0x3377d1cf, v131
	v_fmac_f32_e32 v160, 0x3f317217, v131
	s_waitcnt vmcnt(0)
	v_pk_add_f32 v[108:109], v[108:109], v[140:141]
	s_nop 0
	v_pk_add_f32 v[122:123], v[108:109], v[136:137] neg_lo:[0,1] neg_hi:[0,1]
	v_max_f32_e32 v105, v136, v136
	v_mul_f32_e64 v136, |v122|, s69
	v_max_f32_e32 v130, v137, v137
	v_mul_f32_e64 v137, |v123|, s69
	v_exp_f32_e32 v136, v136
	v_exp_f32_e32 v137, v137
	v_max_f32_e32 v108, v108, v105
	v_mov_b32_e32 v131, v160
	v_add_f32_e32 v105, 1.0, v136
	v_max_f32_e32 v109, v109, v130
	v_add_f32_e32 v130, 1.0, v137
	s_nop 0
	v_log_f32_e32 v105, v105
	v_log_f32_e32 v130, v130
	v_mul_f32_e32 v140, 0x3f317217, v105
	v_mul_f32_e32 v141, 0x3f317217, v130
	v_fma_f32 v140, v105, s75, -v140
	v_fma_f32 v141, v130, s75, -v141
	v_fmac_f32_e32 v140, 0x3377d1cf, v105
	v_fmac_f32_e32 v141, 0x3377d1cf, v130
	v_fmac_f32_e32 v140, 0x3f317217, v105
	v_fmac_f32_e32 v141, 0x3f317217, v130
	s_nop 0
	v_mov_b32_e32 v105, v140
	v_mov_b32_e32 v140, v105
	s_nop 0
	v_mov_b32_e32 v130, v141
	v_mov_b32_e32 v141, v130
	v_mov_b32_e32 v130, v131
	v_mov_b32_e32 v105, v151
	v_log_f32_e32 v136, v105
	v_max_f32_e32 v105, v135, v135
	v_min_f32_e32 v105, 0, v105
	v_mul_f32_e32 v131, 0x3f317217, v136
	v_fma_f32 v131, v136, s75, -v131
	v_fmac_f32_e32 v131, 0x3377d1cf, v136
	v_fmac_f32_e32 v131, 0x3f317217, v136
	s_nop 1
	v_pk_add_f32 v[104:105], v[104:105], v[130:131] neg_lo:[0,1] neg_hi:[0,1]
	s_nop 0
	v_pk_add_f32 v[130:131], v[104:105], v[142:143]
	s_nop 0
	v_pk_add_f32 v[136:137], v[130:131], v[138:139] neg_lo:[0,1] neg_hi:[0,1]
	s_nop 0
	v_mul_f32_e64 v104, |v136|, s69
	v_exp_f32_e32 v142, v104
	v_pk_mul_f32 v[104:105], v[112:113], v[144:145]
	v_rcp_f32_e32 v112, v150
	v_pk_mul_f32 v[104:105], v[126:127], v[104:105]
	v_add_f32_e32 v113, 1.0, v142
	s_nop 1
	v_log_f32_e32 v127, v113
	v_max_f32_e32 v126, v138, v138
	v_mul_f32_e64 v138, |v137|, s69
	v_exp_f32_e32 v138, v138
	v_max_f32_e32 v126, v130, v126
	v_mul_f32_e32 v130, 0x3f317217, v127
	v_fma_f32 v130, v127, s75, -v130
	v_fmac_f32_e32 v130, 0x3377d1cf, v127
	v_fmac_f32_e32 v130, 0x3f317217, v127
	v_add_f32_e32 v138, 1.0, v138
	v_rcp_f32_e32 v113, v151
	v_mov_b32_e32 v127, v130
	v_mov_b32_e32 v130, v127
	s_nop 0
	v_mov_b32_e32 v142, 0
	v_log_f32_e32 v138, v138
	v_max_f32_e32 v127, v131, v139
	v_mul_f32_e32 v131, 0x3f317217, v138
	v_fma_f32 v131, v138, s75, -v131
	v_fmac_f32_e32 v131, 0x3377d1cf, v138
	v_fmac_f32_e32 v131, 0x3f317217, v138
	s_nop 1
	v_cmp_lt_f32_e64 vcc, |v123|, s49
	s_nop 0
	s_nop 0
	v_cndmask_b32_e32 v123, 0, v141, vcc
	v_cmp_lt_f32_e64 vcc, |v122|, s49
	s_nop 1
	v_cndmask_b32_e32 v122, 0, v140, vcc
	v_cmp_lt_f32_e64 vcc, |v137|, s49
	s_nop 1
	v_cndmask_b32_e32 v131, 0, v131, vcc
	v_cmp_lt_f32_e64 vcc, |v136|, s49
	v_pk_add_f32 v[136:137], v[108:109], v[122:123]
	s_nop 0
	v_cndmask_b32_e32 v130, 0, v130, vcc
	v_cmp_lt_f32_e32 vcc, 0, v135
	v_pk_add_f32 v[138:139], v[126:127], v[130:131]
	s_nop 0
	v_cndmask_b32_e32 v109, 1.0, v149, vcc
	v_cmp_lt_f32_e32 vcc, 0, v134
	s_nop 1
	v_cndmask_b32_e32 v108, 1.0, v148, vcc
	v_pk_mul_f32 v[108:109], v[108:109], v[146:147]
	s_nop 0
	v_pk_mul_f32 v[108:109], v[112:113], v[108:109]
	v_lshl_add_u64 v[112:113], v[156:157], 2, s[94:95]
	global_store_dwordx4 v[112:113], v[136:139], off

.LBB0_1254:
	s_add_u32 s0, s22, s0
	s_addc_u32 s1, s23, s1
	v_lshl_add_u64 v[112:113], v[156:157], 1, s[0:1]
	v_cvt_pk_bf16_f32 v104, v104, v105
	v_cvt_pk_bf16_f32 v105, v108, v109
	v_mov_b32_e32 v155, v154
	global_store_dwordx2 v[112:113], v[104:105], off
	v_pk_mul_f32 v[104:105], v[114:115], v[154:155]
	s_and_b64 vcc, exec, s[10:11]
	s_mov_b64 s[0:1], -1
	s_cbranch_vccnz .LBB0_1256
	v_lshlrev_b32_e32 v108, 2, v194
	v_lshlrev_b32_e32 v122, 2, v170
	global_load_dwordx4 v[130:133], v108, s[86:87] offset:16
	global_load_dwordx4 v[112:115], v122, s[66:67]
	global_load_dwordx4 v[134:137], v122, s[56:57]
	v_mul_f32_e64 v123, |v128|, s69
	v_max_f32_e32 v126, v128, v128
	v_mul_f32_e64 v127, |v129|, s69
	v_exp_f32_e32 v123, v123
	v_min_f32_e32 v138, 0, v126
	v_exp_f32_e32 v126, v127
	v_mul_f32_e64 v142, |v105|, s69
	v_exp_f32_e32 v145, v142
	v_add_f32_e32 v142, 1.0, v123
	v_cmp_lt_f32_e32 vcc, 0, v129
	v_add_f32_e32 v143, 1.0, v126
	s_nop 0
	v_cndmask_b32_e32 v127, 1.0, v126, vcc
	v_cmp_lt_f32_e32 vcc, 0, v128
	v_max_f32_e32 v141, v104, v104
	s_nop 0
	v_cndmask_b32_e32 v126, 1.0, v123, vcc
	v_mov_b32_e32 v123, v142
	v_min_f32_e32 v122, 0, v141
	v_rcp_f32_e32 v141, v143
	v_log_f32_e32 v123, v123
	v_mul_f32_e64 v140, |v104|, s69
	v_log_f32_e32 v143, v143
	v_exp_f32_e32 v144, v140
	v_mul_f32_e32 v149, 0x3f317217, v123
	v_fma_f32 v149, v123, s75, -v149
	v_mul_f32_e32 v150, 0x3f317217, v143
	v_add_f32_e32 v146, 1.0, v144
	v_fma_f32 v150, v143, s75, -v150
	v_fmac_f32_e32 v149, 0x3377d1cf, v123
	v_rcp_f32_e32 v140, v142
	v_fmac_f32_e32 v150, 0x3377d1cf, v143
	v_fmac_f32_e32 v149, 0x3f317217, v123
	v_fmac_f32_e32 v150, 0x3f317217, v143
	v_mov_b32_e32 v123, v149
	v_max_f32_e32 v139, v129, v129
	v_mov_b32_e32 v147, v146
	v_mov_b32_e32 v143, v150
	v_min_f32_e32 v139, 0, v139
	v_mov_b32_e32 v142, v123
	v_pk_add_f32 v[138:139], v[138:139], v[142:143] neg_lo:[0,1] neg_hi:[0,1]
	v_log_f32_e32 v147, v147
	v_or_b32_e32 v108, v152, v170
	v_mov_b32_e32 v109, v153
	v_lshl_add_u64 v[108:109], v[108:109], 2, s[94:95]
	v_mul_f32_e32 v151, 0x3f317217, v147
	v_fma_f32 v151, v147, s75, -v151
	v_fmac_f32_e32 v151, 0x3377d1cf, v147
	v_fmac_f32_e32 v151, 0x3f317217, v147
	s_mov_b64 s[0:1], 0
	s_waitcnt vmcnt(0)
	v_pk_add_f32 v[130:131], v[138:139], v[130:131]
	s_nop 0
	v_pk_add_f32 v[138:139], v[130:131], v[112:113] neg_lo:[0,1] neg_hi:[0,1]
	v_max_f32_e32 v123, v112, v112
	v_mul_f32_e64 v112, |v138|, s69
	v_max_f32_e32 v142, v113, v113
	v_mul_f32_e64 v113, |v139|, s69
	v_exp_f32_e32 v112, v112
	v_exp_f32_e32 v113, v113
	v_mov_b32_e32 v147, v151
	v_max_f32_e32 v130, v130, v123
	v_add_f32_e32 v112, 1.0, v112
	v_add_f32_e32 v113, 1.0, v113
	v_max_f32_e32 v131, v131, v142
	v_log_f32_e32 v112, v112
	v_log_f32_e32 v113, v113
	v_mul_f32_e32 v143, 0x3f317217, v112
	v_mul_f32_e32 v148, 0x3f317217, v113
	v_fma_f32 v143, v112, s75, -v143
	v_fma_f32 v148, v113, s75, -v148
	v_fmac_f32_e32 v143, 0x3377d1cf, v112
	v_fmac_f32_e32 v148, 0x3377d1cf, v113
	v_fmac_f32_e32 v143, 0x3f317217, v112
	v_fmac_f32_e32 v148, 0x3f317217, v113
	s_nop 0
	v_mov_b32_e32 v112, v143
	v_mov_b32_e32 v143, v112
	v_mov_b32_e32 v113, v148
	v_add_f32_e32 v148, 1.0, v145
	v_mov_b32_e32 v142, v113
	v_mov_b32_e32 v112, v147
	v_mov_b32_e32 v113, v148
	v_log_f32_e32 v113, v113
	v_max_f32_e32 v123, v105, v105
	v_min_f32_e32 v123, 0, v123
	v_mul_f32_e32 v147, 0x3f317217, v113
	v_fma_f32 v147, v113, s75, -v147
	v_fmac_f32_e32 v147, 0x3377d1cf, v113
	v_fmac_f32_e32 v147, 0x3f317217, v113
	s_nop 1
	v_mov_b32_e32 v113, v147
	v_pk_add_f32 v[112:113], v[122:123], v[112:113] neg_lo:[0,1] neg_hi:[0,1]
	s_nop 0
	v_pk_add_f32 v[122:123], v[112:113], v[132:133]
	s_nop 0
	v_pk_add_f32 v[132:133], v[122:123], v[114:115] neg_lo:[0,1] neg_hi:[0,1]
	v_mul_f32_e64 v112, |v132|, s69
	v_exp_f32_e32 v147, v112
	v_pk_mul_f32 v[112:113], v[126:127], v[134:135]
	v_mul_f32_e64 v135, |v133|, s69
	v_exp_f32_e32 v135, v135
	v_add_f32_e32 v127, 1.0, v147
	v_max_f32_e32 v114, v122, v114
	v_add_f32_e32 v135, 1.0, v135
	v_log_f32_e32 v134, v127
	v_pk_mul_f32 v[112:113], v[140:141], v[112:113]
	v_max_f32_e32 v115, v123, v115
	v_mul_f32_e32 v122, 0x3f317217, v134
	v_fma_f32 v122, v134, s75, -v122
	v_fmac_f32_e32 v122, 0x3377d1cf, v134
	v_fmac_f32_e32 v122, 0x3f317217, v134
	v_rcp_f32_e32 v126, v146
	v_rcp_f32_e32 v127, v148
	v_mov_b32_e32 v134, v122
	s_nop 0
	v_mov_b32_e32 v140, 0
	v_log_f32_e32 v135, v135
	v_cmp_lt_f32_e64 vcc, |v139|, s49
	v_mul_f32_e32 v122, 0x3f317217, v135
	v_fma_f32 v122, v135, s75, -v122
	v_fmac_f32_e32 v122, 0x3377d1cf, v135
	v_fmac_f32_e32 v122, 0x3f317217, v135
	s_nop 1
	v_mov_b32_e32 v135, v122
	v_cndmask_b32_e32 v123, 0, v142, vcc
	v_cmp_lt_f32_e64 vcc, |v138|, s49
	s_nop 1
	v_cndmask_b32_e32 v122, 0, v143, vcc
	v_cmp_lt_f32_e64 vcc, |v133|, s49
	v_pk_add_f32 v[130:131], v[130:131], v[122:123]
	s_nop 0
	v_cndmask_b32_e32 v133, 0, v135, vcc
	v_cmp_lt_f32_e64 vcc, |v132|, s49
	s_nop 1
	v_cndmask_b32_e32 v132, 0, v134, vcc
	v_cmp_lt_f32_e32 vcc, 0, v105
	v_pk_add_f32 v[132:133], v[114:115], v[132:133]
	global_store_dwordx4 v[108:109], v[130:133], off
	v_cndmask_b32_e32 v115, 1.0, v145, vcc
	v_cmp_lt_f32_e32 vcc, 0, v104
	s_nop 1
	v_cndmask_b32_e32 v114, 1.0, v144, vcc
	v_pk_mul_f32 v[114:115], v[114:115], v[136:137]
	s_nop 0
	v_pk_mul_f32 v[114:115], v[126:127], v[114:115]

.LBB0_1258:
	s_add_u32 s0, s22, s0
	s_addc_u32 s1, s23, s1
	v_lshl_add_u64 v[104:105], v[152:153], 0, v[194:195]
	v_mov_b32_e32 v155, v154
	v_lshl_add_u64 v[108:109], v[104:105], 1, s[0:1]
	v_cvt_pk_bf16_f32 v112, v112, v113
	v_cvt_pk_bf16_f32 v113, v114, v115
	v_pk_mul_f32 v[122:123], v[110:111], v[154:155]
	s_and_b64 vcc, exec, s[10:11]
	s_mov_b64 s[0:1], -1
	global_store_dwordx2 v[108:109], v[112:113], off offset:8
	s_cbranch_vccnz .LBB0_1260
	v_lshlrev_b32_e32 v108, 2, v194
	v_lshlrev_b32_e32 v126, 2, v169
	global_load_dwordx4 v[112:115], v108, s[86:87] offset:32
	s_nop 0
	global_load_dwordx4 v[108:111], v126, s[66:67]
	v_mul_f32_e64 v132, |v124|, s69
	global_load_dwordx4 v[126:129], v126, s[56:57]
	v_max_f32_e32 v133, v124, v124
	v_mul_f32_e64 v134, |v125|, s69
	v_exp_f32_e32 v141, v132
	v_min_f32_e32 v136, 0, v133
	v_exp_f32_e32 v133, v134
	v_mul_f32_e64 v140, |v123|, s69
	v_exp_f32_e32 v143, v140
	v_add_f32_e32 v140, 1.0, v141
	v_max_f32_e32 v135, v125, v125
	v_add_f32_e32 v144, 1.0, v133
	v_cmp_lt_f32_e32 vcc, 0, v125
	v_min_f32_e32 v137, 0, v135
	s_nop 0
	v_cndmask_b32_e32 v135, 1.0, v133, vcc
	v_cmp_lt_f32_e32 vcc, 0, v124
	s_nop 1
	v_cndmask_b32_e32 v134, 1.0, v141, vcc
	v_mov_b32_e32 v133, v140
	v_mov_b32_e32 v141, v144
	v_log_f32_e32 v133, v133
	v_mul_f32_e64 v138, |v122|, s69
	v_log_f32_e32 v141, v141
	v_exp_f32_e32 v142, v138
	v_mul_f32_e32 v147, 0x3f317217, v133
	v_fma_f32 v147, v133, s75, -v147
	v_mul_f32_e32 v148, 0x3f317217, v141
	v_add_f32_e32 v145, 1.0, v142
	v_fma_f32 v148, v141, s75, -v148
	v_fmac_f32_e32 v147, 0x3377d1cf, v133
	v_rcp_f32_e32 v138, v140
	v_fmac_f32_e32 v148, 0x3377d1cf, v141
	v_fmac_f32_e32 v147, 0x3f317217, v133
	v_max_f32_e32 v139, v122, v122
	v_fmac_f32_e32 v148, 0x3f317217, v141
	v_mov_b32_e32 v133, v147
	v_min_f32_e32 v132, 0, v139
	v_rcp_f32_e32 v139, v144
	v_mov_b32_e32 v144, v145
	v_mov_b32_e32 v141, v148
	v_mov_b32_e32 v140, v133
	v_pk_add_f32 v[136:137], v[136:137], v[140:141] neg_lo:[0,1] neg_hi:[0,1]
	v_log_f32_e32 v144, v144
	v_or_b32_e32 v130, v152, v169
	v_mov_b32_e32 v131, v153
	s_mov_b64 s[0:1], 0
	v_mul_f32_e32 v149, 0x3f317217, v144
	v_fma_f32 v149, v144, s75, -v149
	v_fmac_f32_e32 v149, 0x3377d1cf, v144
	v_fmac_f32_e32 v149, 0x3f317217, v144
	s_waitcnt vmcnt(0)
	v_pk_add_f32 v[112:113], v[136:137], v[112:113]
	s_nop 0
	v_pk_add_f32 v[136:137], v[112:113], v[108:109] neg_lo:[0,1] neg_hi:[0,1]
	v_max_f32_e32 v133, v108, v108
	v_mul_f32_e64 v108, |v136|, s69
	v_max_f32_e32 v140, v109, v109
	v_mul_f32_e64 v109, |v137|, s69
	v_exp_f32_e32 v108, v108
	v_exp_f32_e32 v109, v109
	v_mov_b32_e32 v144, v149
	v_max_f32_e32 v112, v112, v133
	v_add_f32_e32 v108, 1.0, v108
	v_add_f32_e32 v109, 1.0, v109
	v_max_f32_e32 v113, v113, v140
	v_log_f32_e32 v108, v108
	v_log_f32_e32 v109, v109
	v_mul_f32_e32 v141, 0x3f317217, v108
	v_mul_f32_e32 v146, 0x3f317217, v109
	v_fma_f32 v141, v108, s75, -v141
	v_fma_f32 v146, v109, s75, -v146
	v_fmac_f32_e32 v141, 0x3377d1cf, v108
	v_fmac_f32_e32 v146, 0x3377d1cf, v109
	v_fmac_f32_e32 v141, 0x3f317217, v108
	v_fmac_f32_e32 v146, 0x3f317217, v109
	s_nop 0
	v_mov_b32_e32 v108, v141
	v_mov_b32_e32 v141, v108
	v_mov_b32_e32 v109, v146
	v_add_f32_e32 v146, 1.0, v143
	v_mov_b32_e32 v140, v109
	v_mov_b32_e32 v108, v144
	v_mov_b32_e32 v109, v146
	v_log_f32_e32 v109, v109
	v_max_f32_e32 v133, v123, v123
	v_min_f32_e32 v133, 0, v133
	v_mul_f32_e32 v144, 0x3f317217, v109
	v_fma_f32 v144, v109, s75, -v144
	v_fmac_f32_e32 v144, 0x3377d1cf, v109
	v_fmac_f32_e32 v144, 0x3f317217, v109
	s_nop 1
	v_mov_b32_e32 v109, v144
	v_pk_add_f32 v[108:109], v[132:133], v[108:109] neg_lo:[0,1] neg_hi:[0,1]
	s_nop 0
	v_pk_add_f32 v[114:115], v[108:109], v[114:115]
	s_nop 0
	v_pk_add_f32 v[132:133], v[114:115], v[110:111] neg_lo:[0,1] neg_hi:[0,1]
	v_mul_f32_e64 v108, |v132|, s69
	v_exp_f32_e32 v144, v108
	v_pk_mul_f32 v[108:109], v[134:135], v[126:127]
	v_mul_f32_e64 v135, |v133|, s69
	v_exp_f32_e32 v135, v135
	v_add_f32_e32 v127, 1.0, v144
	v_max_f32_e32 v110, v114, v110
	v_add_f32_e32 v135, 1.0, v135
	v_log_f32_e32 v134, v127
	v_pk_mul_f32 v[108:109], v[138:139], v[108:109]
	v_max_f32_e32 v111, v115, v111
	v_mul_f32_e32 v114, 0x3f317217, v134
	v_fma_f32 v114, v134, s75, -v114
	v_fmac_f32_e32 v114, 0x3377d1cf, v134
	v_fmac_f32_e32 v114, 0x3f317217, v134
	v_rcp_f32_e32 v126, v145
	v_rcp_f32_e32 v127, v146
	s_nop 0
	v_log_f32_e32 v135, v135
	v_cmp_lt_f32_e64 vcc, |v137|, s49
	v_mul_f32_e32 v115, 0x3f317217, v135
	v_fma_f32 v115, v135, s75, -v115
	v_fmac_f32_e32 v115, 0x3377d1cf, v135
	v_fmac_f32_e32 v115, 0x3f317217, v135
	s_nop 1
	v_cndmask_b32_e32 v135, 0, v140, vcc
	v_cmp_lt_f32_e64 vcc, |v136|, s49
	s_nop 0
	s_nop 0
	v_cndmask_b32_e32 v134, 0, v141, vcc
	v_cmp_lt_f32_e64 vcc, |v133|, s49
	v_pk_add_f32 v[112:113], v[112:113], v[134:135]
	s_nop 0
	v_cndmask_b32_e32 v115, 0, v115, vcc
	v_cmp_lt_f32_e64 vcc, |v132|, s49
	s_nop 1
	v_cndmask_b32_e32 v114, 0, v114, vcc
	v_cmp_lt_f32_e32 vcc, 0, v123
	v_pk_add_f32 v[114:115], v[110:111], v[114:115]
	s_nop 0
	v_cndmask_b32_e32 v111, 1.0, v143, vcc
	v_cmp_lt_f32_e32 vcc, 0, v122
	s_nop 1
	v_cndmask_b32_e32 v110, 1.0, v142, vcc
	v_pk_mul_f32 v[110:111], v[110:111], v[128:129]
	s_nop 0
	v_pk_mul_f32 v[110:111], v[126:127], v[110:111]
	v_lshl_add_u64 v[126:127], v[130:131], 2, s[94:95]
	global_store_dwordx4 v[126:127], v[112:115], off

.LBB0_1262:
	s_add_u32 s0, s22, s0
	s_addc_u32 s1, s23, s1
	v_mov_b32_e32 v155, v154
	v_lshl_add_u64 v[104:105], v[104:105], 1, s[0:1]
	v_cvt_pk_bf16_f32 v108, v108, v109
	v_cvt_pk_bf16_f32 v109, v110, v111
	v_or_b32_e32 v152, v152, v168
	v_pk_mul_f32 v[122:123], v[106:107], v[154:155]
	s_and_b64 vcc, exec, s[10:11]
	s_mov_b64 s[0:1], -1
	global_store_dwordx2 v[104:105], v[108:109], off offset:16
	s_cbranch_vccnz .LBB0_1264
	v_lshlrev_b32_e32 v104, 2, v194
	v_lshlrev_b32_e32 v112, 2, v168
	global_load_dwordx4 v[108:111], v104, s[86:87] offset:48
	s_nop 0
	global_load_dwordx4 v[104:107], v112, s[66:67]
	v_mul_f32_e64 v124, |v120|, s69
	global_load_dwordx4 v[112:115], v112, s[56:57]
	v_max_f32_e32 v125, v120, v120
	v_mul_f32_e64 v126, |v121|, s69
	v_exp_f32_e32 v133, v124
	v_min_f32_e32 v128, 0, v125
	v_exp_f32_e32 v125, v126
	v_max_f32_e32 v127, v121, v121
	v_mul_f32_e64 v132, |v123|, s69
	v_cmp_lt_f32_e32 vcc, 0, v121
	v_min_f32_e32 v129, 0, v127
	v_exp_f32_e32 v135, v132
	v_add_f32_e32 v132, 1.0, v133
	v_cndmask_b32_e32 v127, 1.0, v125, vcc
	v_cmp_lt_f32_e32 vcc, 0, v120
	v_add_f32_e32 v136, 1.0, v125
	s_nop 0
	v_cndmask_b32_e32 v126, 1.0, v133, vcc
	v_mov_b32_e32 v133, v136
	v_mov_b32_e32 v125, v132
	v_log_f32_e32 v125, v125
	v_log_f32_e32 v133, v133
	v_mul_f32_e64 v130, |v122|, s69
	v_exp_f32_e32 v134, v130
	v_mul_f32_e32 v141, 0x3f317217, v125
	v_mul_f32_e32 v142, 0x3f317217, v133
	v_fma_f32 v141, v125, s75, -v141
	v_fma_f32 v142, v133, s75, -v142
	v_fmac_f32_e32 v141, 0x3377d1cf, v125
	v_rcp_f32_e32 v130, v132
	v_fmac_f32_e32 v142, 0x3377d1cf, v133
	v_fmac_f32_e32 v141, 0x3f317217, v125
	v_max_f32_e32 v131, v122, v122
	v_add_f32_e32 v137, 1.0, v134
	v_fmac_f32_e32 v142, 0x3f317217, v133
	v_mov_b32_e32 v125, v141
	v_min_f32_e32 v124, 0, v131
	v_rcp_f32_e32 v131, v136
	v_mov_b32_e32 v133, v142
	v_mov_b32_e32 v132, v125
	v_mov_b32_e32 v139, v137
	v_pk_add_f32 v[128:129], v[128:129], v[132:133] neg_lo:[0,1] neg_hi:[0,1]
	v_log_f32_e32 v139, v139
	v_add_f32_e32 v138, 1.0, v135
	v_mov_b32_e32 v140, 0
	s_mov_b64 s[0:1], 0
	v_mul_f32_e32 v143, 0x3f317217, v139
	v_fma_f32 v143, v139, s75, -v143
	v_fmac_f32_e32 v143, 0x3377d1cf, v139
	v_fmac_f32_e32 v143, 0x3f317217, v139
	s_waitcnt vmcnt(0)
	v_pk_add_f32 v[128:129], v[128:129], v[108:109]
	s_nop 0
	v_pk_add_f32 v[108:109], v[128:129], v[104:105] neg_lo:[0,1] neg_hi:[0,1]
	v_max_f32_e32 v125, v104, v104
	v_mul_f32_e64 v104, |v108|, s69
	v_max_f32_e32 v132, v105, v105
	v_mul_f32_e64 v105, |v109|, s69
	v_exp_f32_e32 v133, v104
	v_exp_f32_e32 v136, v105
	v_max_f32_e32 v104, v128, v125
	v_mov_b32_e32 v139, v143
	v_add_f32_e32 v125, 1.0, v133
	v_add_f32_e32 v128, 1.0, v136
	v_max_f32_e32 v105, v129, v132
	v_log_f32_e32 v125, v125
	v_log_f32_e32 v128, v128
	v_mul_f32_e32 v133, 0x3f317217, v125
	v_mul_f32_e32 v136, 0x3f317217, v128
	v_fma_f32 v133, v125, s75, -v133
	v_fma_f32 v136, v128, s75, -v136
	v_fmac_f32_e32 v133, 0x3377d1cf, v125
	v_fmac_f32_e32 v136, 0x3377d1cf, v128
	v_fmac_f32_e32 v133, 0x3f317217, v125
	v_fmac_f32_e32 v136, 0x3f317217, v128
	v_pk_mul_f32 v[112:113], v[126:127], v[112:113]
	v_mov_b32_e32 v125, v133
	v_mov_b32_e32 v133, v125
	v_pk_mul_f32 v[112:113], v[130:131], v[112:113]
	v_mov_b32_e32 v128, v136
	v_mov_b32_e32 v132, v128
	v_mov_b32_e32 v128, v139
	v_mov_b32_e32 v125, v138
	v_log_f32_e32 v129, v125
	v_max_f32_e32 v125, v123, v123
	v_min_f32_e32 v125, 0, v125
	v_rcp_f32_e32 v126, v137
	v_mul_f32_e32 v136, 0x3f317217, v129
	v_fma_f32 v136, v129, s75, -v136
	v_fmac_f32_e32 v136, 0x3377d1cf, v129
	v_fmac_f32_e32 v136, 0x3f317217, v129
	s_nop 1
	v_mov_b32_e32 v129, v136
	v_pk_add_f32 v[124:125], v[124:125], v[128:129] neg_lo:[0,1] neg_hi:[0,1]
	s_nop 0
	v_pk_add_f32 v[110:111], v[124:125], v[110:111]
	s_nop 0
	v_pk_add_f32 v[124:125], v[110:111], v[106:107] neg_lo:[0,1] neg_hi:[0,1]
	v_mul_f32_e64 v128, |v124|, s69
	v_exp_f32_e32 v128, v128
	v_mul_f32_e64 v129, |v125|, s69
	v_exp_f32_e32 v129, v129
	v_max_f32_e32 v106, v110, v106
	v_add_f32_e32 v127, 1.0, v128
	v_add_f32_e32 v129, 1.0, v129
	s_nop 0
	v_log_f32_e32 v128, v127
	v_max_f32_e32 v107, v111, v107
	v_rcp_f32_e32 v127, v138
	v_mul_f32_e32 v110, 0x3f317217, v128
	v_fma_f32 v110, v128, s75, -v110
	v_fmac_f32_e32 v110, 0x3377d1cf, v128
	v_fmac_f32_e32 v110, 0x3f317217, v128
	s_nop 1
	s_nop 0
	v_log_f32_e32 v129, v129
	v_cmp_lt_f32_e64 vcc, |v109|, s49
	v_mul_f32_e32 v111, 0x3f317217, v129
	v_fma_f32 v111, v129, s75, -v111
	v_fmac_f32_e32 v111, 0x3377d1cf, v129
	v_fmac_f32_e32 v111, 0x3f317217, v129
	v_cndmask_b32_e32 v109, 0, v132, vcc
	v_cmp_lt_f32_e64 vcc, |v108|, s49
	s_nop 1
	v_cndmask_b32_e32 v108, 0, v133, vcc
	v_cmp_lt_f32_e64 vcc, |v125|, s49
	v_pk_add_f32 v[104:105], v[104:105], v[108:109]
	s_nop 0
	v_cndmask_b32_e32 v111, 0, v111, vcc
	v_cmp_lt_f32_e64 vcc, |v124|, s49
	s_nop 1
	v_cndmask_b32_e32 v110, 0, v110, vcc
	v_cmp_lt_f32_e32 vcc, 0, v123
	v_pk_add_f32 v[106:107], v[106:107], v[110:111]
	v_lshl_add_u64 v[110:111], v[152:153], 2, s[94:95]
	v_cndmask_b32_e32 v109, 1.0, v135, vcc
	v_cmp_lt_f32_e32 vcc, 0, v122
	global_store_dwordx4 v[110:111], v[104:107], off
	s_nop 0
	v_cndmask_b32_e32 v108, 1.0, v134, vcc
	v_pk_mul_f32 v[108:109], v[108:109], v[114:115]
	v_lshl_add_u64 v[104:105], v[152:153], 1, s[84:85]
	v_pk_mul_f32 v[108:109], v[126:127], v[108:109]
	v_cvt_pk_bf16_f32 v106, v112, v113
	v_cvt_pk_bf16_f32 v107, v108, v109
	global_store_dwordx2 v[104:105], v[106:107], off

.LBB0_1285:
	s_and_b64 vcc, exec, s[0:1]
	s_cbranch_vccz .LBB0_1302
	s_and_b64 vcc, exec, s[10:11]
	s_mov_b64 s[0:1], -1
	s_cbranch_vccnz .LBB0_1288
	v_lshlrev_b32_e32 v84, 2, v194
	global_load_dwordx4 v[120:123], v84, s[86:87]
	global_load_dwordx4 v[116:119], v84, s[66:67]
	global_load_dwordx4 v[124:127], v84, s[56:57]
	v_mul_f32_e64 v85, |v112|, s69
	v_mul_f32_e64 v89, |v113|, s69
	v_exp_f32_e32 v85, v85
	v_exp_f32_e32 v106, v89
	v_mul_f32_e64 v93, |v114|, s69
	v_max_f32_e32 v102, v114, v114
	v_cmp_lt_f32_e32 vcc, 0, v113
	v_max_f32_e32 v92, v113, v113
	v_mul_f32_e64 v103, |v115|, s69
	v_exp_f32_e32 v128, v93
	v_min_f32_e32 v84, 0, v102
	v_add_f32_e32 v102, 1.0, v85
	v_cndmask_b32_e32 v93, 1.0, v106, vcc
	v_cmp_lt_f32_e32 vcc, 0, v112
	v_min_f32_e32 v89, 0, v92
	v_exp_f32_e32 v129, v103
	v_add_f32_e32 v103, 1.0, v106
	v_cndmask_b32_e32 v92, 1.0, v85, vcc
	v_rcp_f32_e32 v107, v103
	v_mov_b32_e32 v85, v102
	v_log_f32_e32 v85, v85
	v_log_f32_e32 v103, v103
	v_rcp_f32_e32 v106, v102
	v_mul_f32_e32 v138, 0x3f317217, v85
	v_mul_f32_e32 v139, 0x3f317217, v103
	v_fma_f32 v138, v85, s75, -v138
	v_fma_f32 v139, v103, s75, -v139
	v_fmac_f32_e32 v138, 0x3377d1cf, v85
	v_fmac_f32_e32 v139, 0x3377d1cf, v103
	v_fmac_f32_e32 v138, 0x3f317217, v85
	v_add_f32_e32 v130, 1.0, v128
	v_fmac_f32_e32 v139, 0x3f317217, v103
	v_mov_b32_e32 v85, v138
	v_max_f32_e32 v88, v112, v112
	v_mov_b32_e32 v103, v139
	v_min_f32_e32 v88, 0, v88
	v_mov_b32_e32 v102, v85
	v_mov_b32_e32 v111, v130
	v_pk_add_f32 v[88:89], v[88:89], v[102:103] neg_lo:[0,1] neg_hi:[0,1]
	v_log_f32_e32 v111, v111
	v_add_f32_e32 v131, 1.0, v129
	s_mov_b64 s[0:1], 0
	v_mul_f32_e32 v140, 0x3f317217, v111
	v_fma_f32 v140, v111, s75, -v140
	v_fmac_f32_e32 v140, 0x3377d1cf, v111
	v_fmac_f32_e32 v140, 0x3f317217, v111
	s_waitcnt vmcnt(0)
	v_pk_add_f32 v[88:89], v[88:89], v[120:121]
	s_nop 0
	v_pk_add_f32 v[102:103], v[88:89], v[116:117] neg_lo:[0,1] neg_hi:[0,1]
	v_max_f32_e32 v85, v116, v116
	v_mul_f32_e64 v116, |v102|, s69
	v_max_f32_e32 v110, v117, v117
	v_mul_f32_e64 v117, |v103|, s69
	v_exp_f32_e32 v116, v116
	v_exp_f32_e32 v117, v117
	v_max_f32_e32 v88, v88, v85
	v_mov_b32_e32 v111, v140
	v_add_f32_e32 v85, 1.0, v116
	v_max_f32_e32 v89, v89, v110
	v_add_f32_e32 v110, 1.0, v117
	s_nop 0
	v_log_f32_e32 v85, v85
	v_log_f32_e32 v110, v110
	v_mul_f32_e32 v120, 0x3f317217, v85
	v_mul_f32_e32 v121, 0x3f317217, v110
	v_fma_f32 v120, v85, s75, -v120
	v_fma_f32 v121, v110, s75, -v121
	v_fmac_f32_e32 v120, 0x3377d1cf, v85
	v_fmac_f32_e32 v121, 0x3377d1cf, v110
	v_fmac_f32_e32 v120, 0x3f317217, v85
	v_fmac_f32_e32 v121, 0x3f317217, v110
	s_nop 0
	v_mov_b32_e32 v85, v120
	v_mov_b32_e32 v120, v85
	s_nop 0
	v_mov_b32_e32 v110, v121
	v_mov_b32_e32 v121, v110
	v_mov_b32_e32 v110, v111
	v_mov_b32_e32 v85, v131
	v_log_f32_e32 v116, v85
	v_max_f32_e32 v85, v115, v115
	v_min_f32_e32 v85, 0, v85
	v_mul_f32_e32 v111, 0x3f317217, v116
	v_fma_f32 v111, v116, s75, -v111
	v_fmac_f32_e32 v111, 0x3377d1cf, v116
	v_fmac_f32_e32 v111, 0x3f317217, v116
	s_nop 1
	v_pk_add_f32 v[84:85], v[84:85], v[110:111] neg_lo:[0,1] neg_hi:[0,1]
	s_nop 0
	v_pk_add_f32 v[110:111], v[84:85], v[122:123]
	s_nop 0
	v_pk_add_f32 v[116:117], v[110:111], v[118:119] neg_lo:[0,1] neg_hi:[0,1]
	s_nop 0
	v_mul_f32_e64 v84, |v116|, s69
	v_exp_f32_e32 v122, v84
	v_pk_mul_f32 v[84:85], v[92:93], v[124:125]
	v_rcp_f32_e32 v92, v130
	v_pk_mul_f32 v[84:85], v[106:107], v[84:85]
	v_add_f32_e32 v93, 1.0, v122
	s_nop 1
	v_log_f32_e32 v107, v93
	v_max_f32_e32 v106, v118, v118
	v_mul_f32_e64 v118, |v117|, s69
	v_exp_f32_e32 v118, v118
	v_max_f32_e32 v106, v110, v106
	v_mul_f32_e32 v110, 0x3f317217, v107
	v_fma_f32 v110, v107, s75, -v110
	v_fmac_f32_e32 v110, 0x3377d1cf, v107
	v_fmac_f32_e32 v110, 0x3f317217, v107
	v_add_f32_e32 v118, 1.0, v118
	v_rcp_f32_e32 v93, v131
	v_mov_b32_e32 v107, v110
	v_mov_b32_e32 v110, v107
	s_nop 0
	v_log_f32_e32 v118, v118
	v_max_f32_e32 v107, v111, v119
	v_mul_f32_e32 v111, 0x3f317217, v118
	v_fma_f32 v111, v118, s75, -v111
	v_fmac_f32_e32 v111, 0x3377d1cf, v118
	v_fmac_f32_e32 v111, 0x3f317217, v118
	s_nop 1
	v_cmp_lt_f32_e64 vcc, |v103|, s49
	s_nop 0
	s_nop 0
	v_cndmask_b32_e32 v103, 0, v121, vcc
	v_cmp_lt_f32_e64 vcc, |v102|, s49
	s_nop 1
	v_cndmask_b32_e32 v102, 0, v120, vcc
	v_cmp_lt_f32_e64 vcc, |v117|, s49
	s_nop 1
	v_cndmask_b32_e32 v111, 0, v111, vcc
	v_cmp_lt_f32_e64 vcc, |v116|, s49
	v_pk_add_f32 v[116:117], v[88:89], v[102:103]
	s_nop 0
	v_cndmask_b32_e32 v110, 0, v110, vcc
	v_cmp_lt_f32_e32 vcc, 0, v115
	v_pk_add_f32 v[118:119], v[106:107], v[110:111]
	s_nop 0
	v_cndmask_b32_e32 v89, 1.0, v129, vcc
	v_cmp_lt_f32_e32 vcc, 0, v114
	s_nop 1
	v_cndmask_b32_e32 v88, 1.0, v128, vcc
	v_pk_mul_f32 v[88:89], v[88:89], v[126:127]
	s_nop 0
	v_pk_mul_f32 v[88:89], v[92:93], v[88:89]
	v_lshl_add_u64 v[92:93], v[136:137], 2, s[94:95]
	global_store_dwordx4 v[92:93], v[116:119], off

.LBB0_1290:
	s_add_u32 s0, s22, s0
	s_addc_u32 s1, s23, s1
	v_lshl_add_u64 v[92:93], v[136:137], 1, s[0:1]
	v_cvt_pk_bf16_f32 v84, v84, v85
	v_cvt_pk_bf16_f32 v85, v88, v89
	v_mov_b32_e32 v135, v134
	global_store_dwordx2 v[92:93], v[84:85], off
	v_pk_mul_f32 v[84:85], v[94:95], v[134:135]
	s_and_b64 vcc, exec, s[10:11]
	s_mov_b64 s[0:1], -1
	s_cbranch_vccnz .LBB0_1292
	v_lshlrev_b32_e32 v88, 2, v194
	v_lshlrev_b32_e32 v102, 2, v170
	global_load_dwordx4 v[110:113], v88, s[86:87] offset:16
	global_load_dwordx4 v[92:95], v102, s[66:67]
	global_load_dwordx4 v[114:117], v102, s[56:57]
	v_mul_f32_e64 v103, |v108|, s69
	v_max_f32_e32 v106, v108, v108
	v_mul_f32_e64 v107, |v109|, s69
	v_exp_f32_e32 v103, v103
	v_min_f32_e32 v118, 0, v106
	v_exp_f32_e32 v106, v107
	v_mul_f32_e64 v122, |v85|, s69
	v_exp_f32_e32 v125, v122
	v_add_f32_e32 v122, 1.0, v103
	v_cmp_lt_f32_e32 vcc, 0, v109
	v_add_f32_e32 v123, 1.0, v106
	s_nop 0
	v_cndmask_b32_e32 v107, 1.0, v106, vcc
	v_cmp_lt_f32_e32 vcc, 0, v108
	v_max_f32_e32 v121, v84, v84
	s_nop 0
	v_cndmask_b32_e32 v106, 1.0, v103, vcc
	v_mov_b32_e32 v103, v122
	v_min_f32_e32 v102, 0, v121
	v_rcp_f32_e32 v121, v123
	v_log_f32_e32 v103, v103
	v_mul_f32_e64 v120, |v84|, s69
	v_log_f32_e32 v123, v123
	v_exp_f32_e32 v124, v120
	v_mul_f32_e32 v129, 0x3f317217, v103
	v_fma_f32 v129, v103, s75, -v129
	v_mul_f32_e32 v130, 0x3f317217, v123
	v_add_f32_e32 v126, 1.0, v124
	v_fma_f32 v130, v123, s75, -v130
	v_fmac_f32_e32 v129, 0x3377d1cf, v103
	v_rcp_f32_e32 v120, v122
	v_fmac_f32_e32 v130, 0x3377d1cf, v123
	v_fmac_f32_e32 v129, 0x3f317217, v103
	v_fmac_f32_e32 v130, 0x3f317217, v123
	v_mov_b32_e32 v103, v129
	v_max_f32_e32 v119, v109, v109
	v_mov_b32_e32 v127, v126
	v_mov_b32_e32 v123, v130
	v_min_f32_e32 v119, 0, v119
	v_mov_b32_e32 v122, v103
	v_pk_add_f32 v[118:119], v[118:119], v[122:123] neg_lo:[0,1] neg_hi:[0,1]
	v_log_f32_e32 v127, v127
	v_or_b32_e32 v88, v132, v170
	v_mov_b32_e32 v89, v133
	v_lshl_add_u64 v[88:89], v[88:89], 2, s[94:95]
	v_mul_f32_e32 v131, 0x3f317217, v127
	v_fma_f32 v131, v127, s75, -v131
	v_fmac_f32_e32 v131, 0x3377d1cf, v127
	v_fmac_f32_e32 v131, 0x3f317217, v127
	s_mov_b64 s[0:1], 0
	s_waitcnt vmcnt(0)
	v_pk_add_f32 v[110:111], v[118:119], v[110:111]
	s_nop 0
	v_pk_add_f32 v[118:119], v[110:111], v[92:93] neg_lo:[0,1] neg_hi:[0,1]
	v_max_f32_e32 v103, v92, v92
	v_mul_f32_e64 v92, |v118|, s69
	v_max_f32_e32 v122, v93, v93
	v_mul_f32_e64 v93, |v119|, s69
	v_exp_f32_e32 v92, v92
	v_exp_f32_e32 v93, v93
	v_mov_b32_e32 v127, v131
	v_max_f32_e32 v110, v110, v103
	v_add_f32_e32 v92, 1.0, v92
	v_add_f32_e32 v93, 1.0, v93
	v_max_f32_e32 v111, v111, v122
	v_log_f32_e32 v92, v92
	v_log_f32_e32 v93, v93
	v_mul_f32_e32 v123, 0x3f317217, v92
	v_mul_f32_e32 v128, 0x3f317217, v93
	v_fma_f32 v123, v92, s75, -v123
	v_fma_f32 v128, v93, s75, -v128
	v_fmac_f32_e32 v123, 0x3377d1cf, v92
	v_fmac_f32_e32 v128, 0x3377d1cf, v93
	v_fmac_f32_e32 v123, 0x3f317217, v92
	v_fmac_f32_e32 v128, 0x3f317217, v93
	s_nop 0
	v_mov_b32_e32 v92, v123
	v_mov_b32_e32 v123, v92
	v_mov_b32_e32 v93, v128
	v_add_f32_e32 v128, 1.0, v125
	v_mov_b32_e32 v122, v93
	v_mov_b32_e32 v92, v127
	v_mov_b32_e32 v93, v128
	v_log_f32_e32 v93, v93
	v_max_f32_e32 v103, v85, v85
	v_min_f32_e32 v103, 0, v103
	v_mul_f32_e32 v127, 0x3f317217, v93
	v_fma_f32 v127, v93, s75, -v127
	v_fmac_f32_e32 v127, 0x3377d1cf, v93
	v_fmac_f32_e32 v127, 0x3f317217, v93
	s_nop 1
	v_mov_b32_e32 v93, v127
	v_pk_add_f32 v[92:93], v[102:103], v[92:93] neg_lo:[0,1] neg_hi:[0,1]
	s_nop 0
	v_pk_add_f32 v[102:103], v[92:93], v[112:113]
	s_nop 0
	v_pk_add_f32 v[112:113], v[102:103], v[94:95] neg_lo:[0,1] neg_hi:[0,1]
	v_mul_f32_e64 v92, |v112|, s69
	v_exp_f32_e32 v127, v92
	v_pk_mul_f32 v[92:93], v[106:107], v[114:115]
	v_mul_f32_e64 v115, |v113|, s69
	v_exp_f32_e32 v115, v115
	v_add_f32_e32 v107, 1.0, v127
	v_max_f32_e32 v94, v102, v94
	v_add_f32_e32 v115, 1.0, v115
	v_log_f32_e32 v114, v107
	v_pk_mul_f32 v[92:93], v[120:121], v[92:93]
	v_max_f32_e32 v95, v103, v95
	v_mul_f32_e32 v102, 0x3f317217, v114
	v_fma_f32 v102, v114, s75, -v102
	v_fmac_f32_e32 v102, 0x3377d1cf, v114
	v_fmac_f32_e32 v102, 0x3f317217, v114
	v_rcp_f32_e32 v106, v126
	v_rcp_f32_e32 v107, v128
	v_mov_b32_e32 v114, v102
	s_nop 0
	v_log_f32_e32 v115, v115
	v_cmp_lt_f32_e64 vcc, |v119|, s49
	v_mul_f32_e32 v102, 0x3f317217, v115
	v_fma_f32 v102, v115, s75, -v102
	v_fmac_f32_e32 v102, 0x3377d1cf, v115
	v_fmac_f32_e32 v102, 0x3f317217, v115
	s_nop 1
	v_mov_b32_e32 v115, v102
	v_cndmask_b32_e32 v103, 0, v122, vcc
	v_cmp_lt_f32_e64 vcc, |v118|, s49
	s_nop 1
	v_cndmask_b32_e32 v102, 0, v123, vcc
	v_cmp_lt_f32_e64 vcc, |v113|, s49
	v_pk_add_f32 v[110:111], v[110:111], v[102:103]
	s_nop 0
	v_cndmask_b32_e32 v113, 0, v115, vcc
	v_cmp_lt_f32_e64 vcc, |v112|, s49
	s_nop 1
	v_cndmask_b32_e32 v112, 0, v114, vcc
	v_cmp_lt_f32_e32 vcc, 0, v85
	v_pk_add_f32 v[112:113], v[94:95], v[112:113]
	global_store_dwordx4 v[88:89], v[110:113], off
	v_cndmask_b32_e32 v95, 1.0, v125, vcc
	v_cmp_lt_f32_e32 vcc, 0, v84
	s_nop 1
	v_cndmask_b32_e32 v94, 1.0, v124, vcc
	v_pk_mul_f32 v[94:95], v[94:95], v[116:117]
	s_nop 0
	v_pk_mul_f32 v[94:95], v[106:107], v[94:95]

.LBB0_1294:
	s_add_u32 s0, s22, s0
	s_addc_u32 s1, s23, s1
	v_lshl_add_u64 v[84:85], v[132:133], 0, v[194:195]
	v_mov_b32_e32 v135, v134
	v_lshl_add_u64 v[88:89], v[84:85], 1, s[0:1]
	v_cvt_pk_bf16_f32 v92, v92, v93
	v_cvt_pk_bf16_f32 v93, v94, v95
	v_pk_mul_f32 v[102:103], v[90:91], v[134:135]
	s_and_b64 vcc, exec, s[10:11]
	s_mov_b64 s[0:1], -1
	global_store_dwordx2 v[88:89], v[92:93], off offset:8
	s_cbranch_vccnz .LBB0_1296
	v_lshlrev_b32_e32 v88, 2, v194
	v_lshlrev_b32_e32 v106, 2, v169
	global_load_dwordx4 v[92:95], v88, s[86:87] offset:32
	s_nop 0
	global_load_dwordx4 v[88:91], v106, s[66:67]
	v_mul_f32_e64 v112, |v104|, s69
	global_load_dwordx4 v[106:109], v106, s[56:57]
	v_max_f32_e32 v113, v104, v104
	v_mul_f32_e64 v114, |v105|, s69
	v_exp_f32_e32 v121, v112
	v_min_f32_e32 v116, 0, v113
	v_exp_f32_e32 v113, v114
	v_mul_f32_e64 v120, |v103|, s69
	v_exp_f32_e32 v123, v120
	v_add_f32_e32 v120, 1.0, v121
	v_max_f32_e32 v115, v105, v105
	v_add_f32_e32 v124, 1.0, v113
	v_cmp_lt_f32_e32 vcc, 0, v105
	v_min_f32_e32 v117, 0, v115
	s_nop 0
	v_cndmask_b32_e32 v115, 1.0, v113, vcc
	v_cmp_lt_f32_e32 vcc, 0, v104
	s_nop 1
	v_cndmask_b32_e32 v114, 1.0, v121, vcc
	v_mov_b32_e32 v113, v120
	v_mov_b32_e32 v121, v124
	v_log_f32_e32 v113, v113
	v_mul_f32_e64 v118, |v102|, s69
	v_log_f32_e32 v121, v121
	v_exp_f32_e32 v122, v118
	v_mul_f32_e32 v127, 0x3f317217, v113
	v_fma_f32 v127, v113, s75, -v127
	v_mul_f32_e32 v128, 0x3f317217, v121
	v_add_f32_e32 v125, 1.0, v122
	v_fma_f32 v128, v121, s75, -v128
	v_fmac_f32_e32 v127, 0x3377d1cf, v113
	v_rcp_f32_e32 v118, v120
	v_fmac_f32_e32 v128, 0x3377d1cf, v121
	v_fmac_f32_e32 v127, 0x3f317217, v113
	v_max_f32_e32 v119, v102, v102
	v_fmac_f32_e32 v128, 0x3f317217, v121
	v_mov_b32_e32 v113, v127
	v_min_f32_e32 v112, 0, v119
	v_rcp_f32_e32 v119, v124
	v_mov_b32_e32 v124, v125
	v_mov_b32_e32 v121, v128
	v_mov_b32_e32 v120, v113
	v_pk_add_f32 v[116:117], v[116:117], v[120:121] neg_lo:[0,1] neg_hi:[0,1]
	v_log_f32_e32 v124, v124
	v_or_b32_e32 v110, v132, v169
	v_mov_b32_e32 v111, v133
	s_mov_b64 s[0:1], 0
	v_mul_f32_e32 v129, 0x3f317217, v124
	v_fma_f32 v129, v124, s75, -v129
	v_fmac_f32_e32 v129, 0x3377d1cf, v124
	v_fmac_f32_e32 v129, 0x3f317217, v124
	s_waitcnt vmcnt(0)
	v_pk_add_f32 v[92:93], v[116:117], v[92:93]
	s_nop 0
	v_pk_add_f32 v[116:117], v[92:93], v[88:89] neg_lo:[0,1] neg_hi:[0,1]
	v_max_f32_e32 v113, v88, v88
	v_mul_f32_e64 v88, |v116|, s69
	v_max_f32_e32 v120, v89, v89
	v_mul_f32_e64 v89, |v117|, s69
	v_exp_f32_e32 v88, v88
	v_exp_f32_e32 v89, v89
	v_mov_b32_e32 v124, v129
	v_max_f32_e32 v92, v92, v113
	v_add_f32_e32 v88, 1.0, v88
	v_add_f32_e32 v89, 1.0, v89
	v_max_f32_e32 v93, v93, v120
	v_log_f32_e32 v88, v88
	v_log_f32_e32 v89, v89
	v_mul_f32_e32 v121, 0x3f317217, v88
	v_mul_f32_e32 v126, 0x3f317217, v89
	v_fma_f32 v121, v88, s75, -v121
	v_fma_f32 v126, v89, s75, -v126
	v_fmac_f32_e32 v121, 0x3377d1cf, v88
	v_fmac_f32_e32 v126, 0x3377d1cf, v89
	v_fmac_f32_e32 v121, 0x3f317217, v88
	v_fmac_f32_e32 v126, 0x3f317217, v89
	s_nop 0
	v_mov_b32_e32 v88, v121
	v_mov_b32_e32 v121, v88
	v_mov_b32_e32 v89, v126
	v_add_f32_e32 v126, 1.0, v123
	v_mov_b32_e32 v120, v89
	v_mov_b32_e32 v88, v124
	v_mov_b32_e32 v89, v126
	v_log_f32_e32 v89, v89
	v_max_f32_e32 v113, v103, v103
	v_min_f32_e32 v113, 0, v113
	v_mul_f32_e32 v124, 0x3f317217, v89
	v_fma_f32 v124, v89, s75, -v124
	v_fmac_f32_e32 v124, 0x3377d1cf, v89
	v_fmac_f32_e32 v124, 0x3f317217, v89
	s_nop 1
	v_mov_b32_e32 v89, v124
	v_pk_add_f32 v[88:89], v[112:113], v[88:89] neg_lo:[0,1] neg_hi:[0,1]
	s_nop 0
	v_pk_add_f32 v[94:95], v[88:89], v[94:95]
	s_nop 0
	v_pk_add_f32 v[112:113], v[94:95], v[90:91] neg_lo:[0,1] neg_hi:[0,1]
	v_mul_f32_e64 v88, |v112|, s69
	v_exp_f32_e32 v124, v88
	v_pk_mul_f32 v[88:89], v[114:115], v[106:107]
	v_mul_f32_e64 v115, |v113|, s69
	v_exp_f32_e32 v115, v115
	v_add_f32_e32 v107, 1.0, v124
	v_max_f32_e32 v90, v94, v90
	v_add_f32_e32 v115, 1.0, v115
	v_log_f32_e32 v114, v107
	v_pk_mul_f32 v[88:89], v[118:119], v[88:89]
	v_max_f32_e32 v91, v95, v91
	v_mul_f32_e32 v94, 0x3f317217, v114
	v_fma_f32 v94, v114, s75, -v94
	v_fmac_f32_e32 v94, 0x3377d1cf, v114
	v_fmac_f32_e32 v94, 0x3f317217, v114
	v_rcp_f32_e32 v106, v125
	v_rcp_f32_e32 v107, v126
	s_nop 0
	v_log_f32_e32 v115, v115
	v_cmp_lt_f32_e64 vcc, |v117|, s49
	v_mul_f32_e32 v95, 0x3f317217, v115
	v_fma_f32 v95, v115, s75, -v95
	v_fmac_f32_e32 v95, 0x3377d1cf, v115
	v_fmac_f32_e32 v95, 0x3f317217, v115
	s_nop 1
	v_cndmask_b32_e32 v115, 0, v120, vcc
	v_cmp_lt_f32_e64 vcc, |v116|, s49
	s_nop 0
	s_nop 0
	v_cndmask_b32_e32 v114, 0, v121, vcc
	v_cmp_lt_f32_e64 vcc, |v113|, s49
	v_pk_add_f32 v[92:93], v[92:93], v[114:115]
	s_nop 0
	v_cndmask_b32_e32 v95, 0, v95, vcc
	v_cmp_lt_f32_e64 vcc, |v112|, s49
	s_nop 1
	v_cndmask_b32_e32 v94, 0, v94, vcc
	v_cmp_lt_f32_e32 vcc, 0, v103
	v_pk_add_f32 v[94:95], v[90:91], v[94:95]
	s_nop 0
	v_cndmask_b32_e32 v91, 1.0, v123, vcc
	v_cmp_lt_f32_e32 vcc, 0, v102
	s_nop 1
	v_cndmask_b32_e32 v90, 1.0, v122, vcc
	v_pk_mul_f32 v[90:91], v[90:91], v[108:109]
	s_nop 0
	v_pk_mul_f32 v[90:91], v[106:107], v[90:91]
	v_lshl_add_u64 v[106:107], v[110:111], 2, s[94:95]
	global_store_dwordx4 v[106:107], v[92:95], off

.LBB0_1298:
	s_add_u32 s0, s22, s0
	s_addc_u32 s1, s23, s1
	v_mov_b32_e32 v135, v134
	v_lshl_add_u64 v[84:85], v[84:85], 1, s[0:1]
	v_cvt_pk_bf16_f32 v88, v88, v89
	v_cvt_pk_bf16_f32 v89, v90, v91
	v_or_b32_e32 v132, v132, v168
	v_pk_mul_f32 v[102:103], v[86:87], v[134:135]
	s_and_b64 vcc, exec, s[10:11]
	s_mov_b64 s[0:1], -1
	global_store_dwordx2 v[84:85], v[88:89], off offset:16
	s_cbranch_vccnz .LBB0_1300
	v_lshlrev_b32_e32 v84, 2, v194
	v_lshlrev_b32_e32 v92, 2, v168
	global_load_dwordx4 v[88:91], v84, s[86:87] offset:48
	s_nop 0
	global_load_dwordx4 v[84:87], v92, s[66:67]
	v_mul_f32_e64 v104, |v100|, s69
	global_load_dwordx4 v[92:95], v92, s[56:57]
	v_max_f32_e32 v105, v100, v100
	v_mul_f32_e64 v106, |v101|, s69
	v_exp_f32_e32 v113, v104
	v_min_f32_e32 v108, 0, v105
	v_exp_f32_e32 v105, v106
	v_max_f32_e32 v107, v101, v101
	v_mul_f32_e64 v112, |v103|, s69
	v_cmp_lt_f32_e32 vcc, 0, v101
	v_min_f32_e32 v109, 0, v107
	v_exp_f32_e32 v115, v112
	v_add_f32_e32 v112, 1.0, v113
	v_cndmask_b32_e32 v107, 1.0, v105, vcc
	v_cmp_lt_f32_e32 vcc, 0, v100
	v_add_f32_e32 v116, 1.0, v105
	s_nop 0
	v_cndmask_b32_e32 v106, 1.0, v113, vcc
	v_mov_b32_e32 v113, v116
	v_mov_b32_e32 v105, v112
	v_log_f32_e32 v105, v105
	v_log_f32_e32 v113, v113
	v_mul_f32_e64 v110, |v102|, s69
	v_exp_f32_e32 v114, v110
	v_mul_f32_e32 v121, 0x3f317217, v105
	v_mul_f32_e32 v122, 0x3f317217, v113
	v_fma_f32 v121, v105, s75, -v121
	v_fma_f32 v122, v113, s75, -v122
	v_fmac_f32_e32 v121, 0x3377d1cf, v105
	v_rcp_f32_e32 v110, v112
	v_fmac_f32_e32 v122, 0x3377d1cf, v113
	v_fmac_f32_e32 v121, 0x3f317217, v105
	v_max_f32_e32 v111, v102, v102
	v_add_f32_e32 v117, 1.0, v114
	v_fmac_f32_e32 v122, 0x3f317217, v113
	v_mov_b32_e32 v105, v121
	v_min_f32_e32 v104, 0, v111
	v_rcp_f32_e32 v111, v116
	v_mov_b32_e32 v113, v122
	v_mov_b32_e32 v112, v105
	v_mov_b32_e32 v119, v117
	v_pk_add_f32 v[108:109], v[108:109], v[112:113] neg_lo:[0,1] neg_hi:[0,1]
	v_log_f32_e32 v119, v119
	v_add_f32_e32 v118, 1.0, v115
	s_mov_b64 s[0:1], 0
	v_mul_f32_e32 v123, 0x3f317217, v119
	v_fma_f32 v123, v119, s75, -v123
	v_fmac_f32_e32 v123, 0x3377d1cf, v119
	v_fmac_f32_e32 v123, 0x3f317217, v119
	s_waitcnt vmcnt(0)
	v_pk_add_f32 v[108:109], v[108:109], v[88:89]
	s_nop 0
	v_pk_add_f32 v[88:89], v[108:109], v[84:85] neg_lo:[0,1] neg_hi:[0,1]
	v_max_f32_e32 v105, v84, v84
	v_mul_f32_e64 v84, |v88|, s69
	v_max_f32_e32 v112, v85, v85
	v_mul_f32_e64 v85, |v89|, s69
	v_exp_f32_e32 v113, v84
	v_exp_f32_e32 v116, v85
	v_max_f32_e32 v84, v108, v105
	v_mov_b32_e32 v119, v123
	v_add_f32_e32 v105, 1.0, v113
	v_add_f32_e32 v108, 1.0, v116
	v_max_f32_e32 v85, v109, v112
	v_log_f32_e32 v105, v105
	v_log_f32_e32 v108, v108
	v_mul_f32_e32 v113, 0x3f317217, v105
	v_mul_f32_e32 v116, 0x3f317217, v108
	v_fma_f32 v113, v105, s75, -v113
	v_fma_f32 v116, v108, s75, -v116
	v_fmac_f32_e32 v113, 0x3377d1cf, v105
	v_fmac_f32_e32 v116, 0x3377d1cf, v108
	v_fmac_f32_e32 v113, 0x3f317217, v105
	v_fmac_f32_e32 v116, 0x3f317217, v108
	v_pk_mul_f32 v[92:93], v[106:107], v[92:93]
	v_mov_b32_e32 v105, v113
	v_mov_b32_e32 v113, v105
	v_pk_mul_f32 v[92:93], v[110:111], v[92:93]
	v_mov_b32_e32 v108, v116
	v_mov_b32_e32 v112, v108
	v_mov_b32_e32 v108, v119
	v_mov_b32_e32 v105, v118
	v_log_f32_e32 v109, v105
	v_max_f32_e32 v105, v103, v103
	v_min_f32_e32 v105, 0, v105
	v_rcp_f32_e32 v106, v117
	v_mul_f32_e32 v116, 0x3f317217, v109
	v_fma_f32 v116, v109, s75, -v116
	v_fmac_f32_e32 v116, 0x3377d1cf, v109
	v_fmac_f32_e32 v116, 0x3f317217, v109
	s_nop 1
	v_mov_b32_e32 v109, v116
	v_pk_add_f32 v[104:105], v[104:105], v[108:109] neg_lo:[0,1] neg_hi:[0,1]
	s_nop 0
	v_pk_add_f32 v[90:91], v[104:105], v[90:91]
	s_nop 0
	v_pk_add_f32 v[104:105], v[90:91], v[86:87] neg_lo:[0,1] neg_hi:[0,1]
	v_mul_f32_e64 v108, |v104|, s69
	v_exp_f32_e32 v108, v108
	v_mul_f32_e64 v109, |v105|, s69
	v_exp_f32_e32 v109, v109
	v_max_f32_e32 v86, v90, v86
	v_add_f32_e32 v107, 1.0, v108
	v_add_f32_e32 v109, 1.0, v109
	s_nop 0
	v_log_f32_e32 v108, v107
	v_max_f32_e32 v87, v91, v87
	v_rcp_f32_e32 v107, v118
	v_mul_f32_e32 v90, 0x3f317217, v108
	v_fma_f32 v90, v108, s75, -v90
	v_fmac_f32_e32 v90, 0x3377d1cf, v108
	v_fmac_f32_e32 v90, 0x3f317217, v108
	s_nop 1
	s_nop 0
	v_log_f32_e32 v109, v109
	v_cmp_lt_f32_e64 vcc, |v89|, s49
	v_mul_f32_e32 v91, 0x3f317217, v109
	v_fma_f32 v91, v109, s75, -v91
	v_fmac_f32_e32 v91, 0x3377d1cf, v109
	v_fmac_f32_e32 v91, 0x3f317217, v109
	v_cndmask_b32_e32 v89, 0, v112, vcc
	v_cmp_lt_f32_e64 vcc, |v88|, s49
	s_nop 1
	v_cndmask_b32_e32 v88, 0, v113, vcc
	v_cmp_lt_f32_e64 vcc, |v105|, s49
	v_pk_add_f32 v[84:85], v[84:85], v[88:89]
	s_nop 0
	v_cndmask_b32_e32 v91, 0, v91, vcc
	v_cmp_lt_f32_e64 vcc, |v104|, s49
	s_nop 1
	v_cndmask_b32_e32 v90, 0, v90, vcc
	v_cmp_lt_f32_e32 vcc, 0, v103
	v_pk_add_f32 v[86:87], v[86:87], v[90:91]
	v_lshl_add_u64 v[90:91], v[132:133], 2, s[94:95]
	v_cndmask_b32_e32 v89, 1.0, v115, vcc
	v_cmp_lt_f32_e32 vcc, 0, v102
	global_store_dwordx4 v[90:91], v[84:87], off
	s_nop 0
	v_cndmask_b32_e32 v88, 1.0, v114, vcc
	v_pk_mul_f32 v[88:89], v[88:89], v[94:95]
	v_lshl_add_u64 v[84:85], v[132:133], 1, s[84:85]
	v_pk_mul_f32 v[88:89], v[106:107], v[88:89]
	v_cvt_pk_bf16_f32 v86, v92, v93
	v_cvt_pk_bf16_f32 v87, v88, v89
	global_store_dwordx2 v[84:85], v[86:87], off

.LBB0_1321:
	s_and_b64 vcc, exec, s[0:1]
	s_cbranch_vccz .LBB0_1338
	s_and_b64 vcc, exec, s[10:11]
	s_mov_b64 s[0:1], -1
	s_cbranch_vccnz .LBB0_1324
	v_lshlrev_b32_e32 v68, 2, v194
	global_load_dwordx4 v[100:103], v68, s[86:87]
	global_load_dwordx4 v[96:99], v68, s[66:67]
	global_load_dwordx4 v[104:107], v68, s[56:57]
	v_mul_f32_e64 v69, |v92|, s69
	v_max_f32_e32 v72, v92, v92
	v_mul_f32_e64 v73, |v93|, s69
	v_exp_f32_e32 v86, v69
	v_min_f32_e32 v68, 0, v72
	v_exp_f32_e32 v72, v73
	v_mul_f32_e64 v83, |v95|, s69
	v_cmp_lt_f32_e32 vcc, 0, v93
	v_max_f32_e32 v76, v93, v93
	v_mul_f32_e64 v77, |v94|, s69
	v_max_f32_e32 v82, v94, v94
	v_exp_f32_e32 v91, v83
	v_add_f32_e32 v73, 1.0, v86
	v_cndmask_b32_e32 v83, 1.0, v72, vcc
	v_cmp_lt_f32_e32 vcc, 0, v92
	v_min_f32_e32 v69, 0, v76
	v_exp_f32_e32 v90, v77
	v_min_f32_e32 v76, 0, v82
	v_add_f32_e32 v77, 1.0, v72
	v_cndmask_b32_e32 v82, 1.0, v86, vcc
	v_rcp_f32_e32 v87, v77
	v_mov_b32_e32 v72, v73
	v_log_f32_e32 v72, v72
	v_log_f32_e32 v77, v77
	v_rcp_f32_e32 v86, v73
	v_mul_f32_e32 v118, 0x3f317217, v72
	v_mul_f32_e32 v119, 0x3f317217, v77
	v_fma_f32 v118, v72, s75, -v118
	v_fma_f32 v119, v77, s75, -v119
	v_fmac_f32_e32 v118, 0x3377d1cf, v72
	v_fmac_f32_e32 v119, 0x3377d1cf, v77
	v_fmac_f32_e32 v118, 0x3f317217, v72
	v_add_f32_e32 v108, 1.0, v90
	v_fmac_f32_e32 v119, 0x3f317217, v77
	v_mov_b32_e32 v72, v118
	v_mov_b32_e32 v77, v119
	v_mov_b32_e32 v73, v77
	v_mov_b32_e32 v111, v108
	v_pk_add_f32 v[68:69], v[68:69], v[72:73] neg_lo:[0,1] neg_hi:[0,1]
	v_log_f32_e32 v111, v111
	v_add_f32_e32 v109, 1.0, v91
	s_mov_b64 s[0:1], 0
	v_mul_f32_e32 v120, 0x3f317217, v111
	v_fma_f32 v120, v111, s75, -v120
	v_fmac_f32_e32 v120, 0x3377d1cf, v111
	v_fmac_f32_e32 v120, 0x3f317217, v111
	s_waitcnt vmcnt(0)
	v_pk_add_f32 v[68:69], v[68:69], v[100:101]
	s_nop 0
	v_pk_add_f32 v[72:73], v[68:69], v[96:97] neg_lo:[0,1] neg_hi:[0,1]
	v_max_f32_e32 v77, v96, v96
	v_mul_f32_e64 v96, |v72|, s69
	v_max_f32_e32 v100, v97, v97
	v_mul_f32_e64 v97, |v73|, s69
	v_exp_f32_e32 v96, v96
	v_exp_f32_e32 v97, v97
	v_max_f32_e32 v68, v68, v77
	v_mov_b32_e32 v111, v120
	v_add_f32_e32 v77, 1.0, v96
	v_add_f32_e32 v96, 1.0, v97
	v_max_f32_e32 v69, v69, v100
	v_log_f32_e32 v77, v77
	v_log_f32_e32 v96, v96
	v_mul_f32_e32 v101, 0x3f317217, v77
	v_mul_f32_e32 v110, 0x3f317217, v96
	v_fma_f32 v101, v77, s75, -v101
	v_fma_f32 v110, v96, s75, -v110
	v_fmac_f32_e32 v101, 0x3377d1cf, v77
	v_fmac_f32_e32 v110, 0x3377d1cf, v96
	v_fmac_f32_e32 v101, 0x3f317217, v77
	v_fmac_f32_e32 v110, 0x3f317217, v96
	s_nop 0
	v_mov_b32_e32 v77, v101
	s_nop 1
	v_mov_b32_e32 v96, v110
	v_mov_b32_e32 v110, v77
	v_mov_b32_e32 v118, v96
	v_mov_b32_e32 v77, v109
	v_log_f32_e32 v97, v77
	v_max_f32_e32 v77, v95, v95
	v_mov_b32_e32 v96, v111
	v_min_f32_e32 v77, 0, v77
	v_mul_f32_e32 v100, 0x3f317217, v97
	v_fma_f32 v100, v97, s75, -v100
	v_fmac_f32_e32 v100, 0x3377d1cf, v97
	v_fmac_f32_e32 v100, 0x3f317217, v97
	s_nop 1
	v_mov_b32_e32 v97, v100
	v_pk_add_f32 v[76:77], v[76:77], v[96:97] neg_lo:[0,1] neg_hi:[0,1]
	s_nop 0
	v_pk_add_f32 v[96:97], v[76:77], v[102:103]
	s_nop 0
	v_pk_add_f32 v[100:101], v[96:97], v[98:99] neg_lo:[0,1] neg_hi:[0,1]
	s_nop 0
	v_mul_f32_e64 v76, |v100|, s69
	v_exp_f32_e32 v102, v76
	v_pk_mul_f32 v[76:77], v[82:83], v[104:105]
	v_rcp_f32_e32 v82, v108
	v_pk_mul_f32 v[76:77], v[86:87], v[76:77]
	v_add_f32_e32 v83, 1.0, v102
	s_nop 1
	v_log_f32_e32 v87, v83
	v_max_f32_e32 v86, v98, v98
	v_mul_f32_e64 v98, |v101|, s69
	v_exp_f32_e32 v98, v98
	v_max_f32_e32 v86, v96, v86
	v_mul_f32_e32 v96, 0x3f317217, v87
	v_fma_f32 v96, v87, s75, -v96
	v_fmac_f32_e32 v96, 0x3377d1cf, v87
	v_fmac_f32_e32 v96, 0x3f317217, v87
	v_add_f32_e32 v98, 1.0, v98
	v_rcp_f32_e32 v83, v109
	v_mov_b32_e32 v87, v96
	v_mov_b32_e32 v96, v87
	s_nop 0
	v_log_f32_e32 v98, v98
	v_max_f32_e32 v87, v97, v99
	v_mul_f32_e32 v97, 0x3f317217, v98
	v_fma_f32 v97, v98, s75, -v97
	v_fmac_f32_e32 v97, 0x3377d1cf, v98
	v_fmac_f32_e32 v97, 0x3f317217, v98
	s_nop 1
	v_cmp_lt_f32_e64 vcc, |v73|, s49
	s_nop 0
	s_nop 0
	v_cndmask_b32_e32 v73, 0, v118, vcc
	v_cmp_lt_f32_e64 vcc, |v72|, s49
	s_nop 1
	v_cndmask_b32_e32 v72, 0, v110, vcc
	v_cmp_lt_f32_e64 vcc, |v101|, s49
	s_nop 1
	v_cndmask_b32_e32 v97, 0, v97, vcc
	v_cmp_lt_f32_e64 vcc, |v100|, s49
	s_nop 1
	v_cndmask_b32_e32 v96, 0, v96, vcc
	v_cmp_lt_f32_e32 vcc, 0, v95
	v_pk_add_f32 v[98:99], v[86:87], v[96:97]
	v_pk_add_f32 v[96:97], v[68:69], v[72:73]
	v_cndmask_b32_e32 v69, 1.0, v91, vcc
	v_cmp_lt_f32_e32 vcc, 0, v94
	v_lshl_add_u64 v[72:73], v[116:117], 2, s[94:95]
	global_store_dwordx4 v[72:73], v[96:99], off
	v_cndmask_b32_e32 v68, 1.0, v90, vcc
	v_pk_mul_f32 v[68:69], v[68:69], v[106:107]
	s_nop 0
	v_pk_mul_f32 v[68:69], v[82:83], v[68:69]

.LBB0_1326:
	s_add_u32 s0, s22, s0
	s_addc_u32 s1, s23, s1
	v_mov_b32_e32 v115, v114
	v_lshl_add_u64 v[72:73], v[116:117], 1, s[0:1]
	v_cvt_pk_bf16_f32 v76, v76, v77
	v_cvt_pk_bf16_f32 v77, v68, v69
	v_pk_mul_f32 v[68:69], v[78:79], v[114:115]
	s_and_b64 vcc, exec, s[10:11]
	s_mov_b64 s[0:1], -1
	global_store_dwordx2 v[72:73], v[76:77], off
	s_cbranch_vccnz .LBB0_1328
	v_lshlrev_b32_e32 v72, 2, v194
	v_lshlrev_b32_e32 v82, 2, v170
	global_load_dwordx4 v[90:93], v72, s[86:87] offset:16
	global_load_dwordx4 v[76:79], v82, s[66:67]
	global_load_dwordx4 v[94:97], v82, s[56:57]
	v_mul_f32_e64 v83, |v88|, s69
	v_mul_f32_e64 v87, |v89|, s69
	v_exp_f32_e32 v104, v83
	v_exp_f32_e32 v87, v87
	v_mul_f32_e64 v99, |v68|, s69
	v_cmp_lt_f32_e32 vcc, 0, v89
	v_max_f32_e32 v98, v89, v89
	v_exp_f32_e32 v102, v99
	v_add_f32_e32 v105, 1.0, v104
	v_cndmask_b32_e32 v99, 1.0, v87, vcc
	v_cmp_lt_f32_e32 vcc, 0, v88
	v_min_f32_e32 v83, 0, v98
	v_add_f32_e32 v106, 1.0, v87
	v_cndmask_b32_e32 v98, 1.0, v104, vcc
	v_max_f32_e32 v86, v88, v88
	v_mov_b32_e32 v87, v105
	v_mov_b32_e32 v104, v106
	v_log_f32_e32 v87, v87
	v_log_f32_e32 v104, v104
	v_max_f32_e32 v100, v68, v68
	v_add_f32_e32 v107, 1.0, v102
	v_mul_f32_e32 v109, 0x3f317217, v87
	v_mul_f32_e32 v110, 0x3f317217, v104
	v_fma_f32 v109, v87, s75, -v109
	v_fma_f32 v110, v104, s75, -v110
	v_fmac_f32_e32 v109, 0x3377d1cf, v87
	v_min_f32_e32 v82, 0, v86
	v_min_f32_e32 v86, 0, v100
	v_rcp_f32_e32 v100, v105
	v_fmac_f32_e32 v110, 0x3377d1cf, v104
	v_fmac_f32_e32 v109, 0x3f317217, v87
	v_mul_f32_e64 v101, |v69|, s69
	v_fmac_f32_e32 v110, 0x3f317217, v104
	v_mov_b32_e32 v87, v109
	v_exp_f32_e32 v103, v101
	v_rcp_f32_e32 v101, v106
	v_mov_b32_e32 v106, v107
	v_mov_b32_e32 v109, v110
	v_mov_b32_e32 v104, v87
	v_mov_b32_e32 v105, v109
	v_pk_add_f32 v[82:83], v[82:83], v[104:105] neg_lo:[0,1] neg_hi:[0,1]
	v_log_f32_e32 v106, v106
	v_or_b32_e32 v72, v112, v170
	v_mov_b32_e32 v73, v113
	v_lshl_add_u64 v[72:73], v[72:73], 2, s[94:95]
	v_mul_f32_e32 v111, 0x3f317217, v106
	v_fma_f32 v111, v106, s75, -v111
	v_fmac_f32_e32 v111, 0x3377d1cf, v106
	v_fmac_f32_e32 v111, 0x3f317217, v106
	s_mov_b64 s[0:1], 0
	s_waitcnt vmcnt(0)
	v_pk_add_f32 v[90:91], v[82:83], v[90:91]
	s_nop 0
	v_pk_add_f32 v[82:83], v[90:91], v[76:77] neg_lo:[0,1] neg_hi:[0,1]
	v_max_f32_e32 v87, v76, v76
	v_mul_f32_e64 v76, |v82|, s69
	v_max_f32_e32 v104, v77, v77
	v_mul_f32_e64 v77, |v83|, s69
	v_exp_f32_e32 v105, v76
	v_exp_f32_e32 v108, v77
	v_max_f32_e32 v76, v90, v87
	v_mov_b32_e32 v106, v111
	v_add_f32_e32 v87, 1.0, v105
	v_add_f32_e32 v90, 1.0, v108
	v_max_f32_e32 v77, v91, v104
	v_log_f32_e32 v87, v87
	v_log_f32_e32 v90, v90
	v_mul_f32_e32 v105, 0x3f317217, v87
	v_mul_f32_e32 v108, 0x3f317217, v90
	v_fma_f32 v105, v87, s75, -v105
	v_fma_f32 v108, v90, s75, -v108
	v_fmac_f32_e32 v105, 0x3377d1cf, v87
	v_fmac_f32_e32 v108, 0x3377d1cf, v90
	v_fmac_f32_e32 v105, 0x3f317217, v87
	v_fmac_f32_e32 v108, 0x3f317217, v90
	s_nop 0
	v_mov_b32_e32 v87, v105
	v_mov_b32_e32 v105, v87
	v_mov_b32_e32 v90, v108
	v_add_f32_e32 v108, 1.0, v103
	v_mov_b32_e32 v104, v90
	s_nop 0
	v_mov_b32_e32 v90, v108
	v_log_f32_e32 v91, v90
	v_mov_b32_e32 v90, v106
	v_max_f32_e32 v87, v69, v69
	v_min_f32_e32 v87, 0, v87
	v_mul_f32_e32 v106, 0x3f317217, v91
	v_fma_f32 v106, v91, s75, -v106
	v_fmac_f32_e32 v106, 0x3377d1cf, v91
	v_fmac_f32_e32 v106, 0x3f317217, v91
	s_nop 1
	v_mov_b32_e32 v91, v106
	v_pk_add_f32 v[86:87], v[86:87], v[90:91] neg_lo:[0,1] neg_hi:[0,1]
	s_nop 0
	v_pk_add_f32 v[90:91], v[86:87], v[92:93]
	s_nop 0
	v_pk_add_f32 v[92:93], v[90:91], v[78:79] neg_lo:[0,1] neg_hi:[0,1]
	v_mul_f32_e64 v86, |v92|, s69
	v_exp_f32_e32 v106, v86
	v_pk_mul_f32 v[86:87], v[98:99], v[94:95]
	v_mul_f32_e64 v99, |v93|, s69
	v_exp_f32_e32 v99, v99
	v_add_f32_e32 v95, 1.0, v106
	v_max_f32_e32 v78, v90, v78
	v_add_f32_e32 v99, 1.0, v99
	v_log_f32_e32 v98, v95
	v_pk_mul_f32 v[86:87], v[100:101], v[86:87]
	v_max_f32_e32 v79, v91, v79
	v_mul_f32_e32 v90, 0x3f317217, v98
	v_fma_f32 v90, v98, s75, -v90
	v_fmac_f32_e32 v90, 0x3377d1cf, v98
	v_fmac_f32_e32 v90, 0x3f317217, v98
	v_rcp_f32_e32 v94, v107
	v_rcp_f32_e32 v95, v108
	s_nop 0
	v_log_f32_e32 v99, v99
	v_cmp_lt_f32_e64 vcc, |v83|, s49
	v_mul_f32_e32 v91, 0x3f317217, v99
	v_fma_f32 v91, v99, s75, -v91
	v_fmac_f32_e32 v91, 0x3377d1cf, v99
	v_fmac_f32_e32 v91, 0x3f317217, v99
	v_cndmask_b32_e32 v83, 0, v104, vcc
	v_cmp_lt_f32_e64 vcc, |v82|, s49
	s_nop 1
	v_cndmask_b32_e32 v82, 0, v105, vcc
	v_cmp_lt_f32_e64 vcc, |v93|, s49
	s_nop 1
	v_cndmask_b32_e32 v91, 0, v91, vcc
	v_cmp_lt_f32_e64 vcc, |v92|, s49
	s_nop 1
	v_cndmask_b32_e32 v90, 0, v90, vcc
	v_cmp_lt_f32_e32 vcc, 0, v69
	v_pk_add_f32 v[92:93], v[78:79], v[90:91]
	v_pk_add_f32 v[90:91], v[76:77], v[82:83]
	v_cndmask_b32_e32 v77, 1.0, v103, vcc
	v_cmp_lt_f32_e32 vcc, 0, v68
	global_store_dwordx4 v[72:73], v[90:93], off
	s_nop 0
	v_cndmask_b32_e32 v76, 1.0, v102, vcc
	v_pk_mul_f32 v[76:77], v[76:77], v[96:97]
	s_nop 0
	v_pk_mul_f32 v[76:77], v[94:95], v[76:77]

.LBB0_1330:
	s_add_u32 s0, s22, s0
	s_addc_u32 s1, s23, s1
	v_lshl_add_u64 v[68:69], v[112:113], 0, v[194:195]
	v_mov_b32_e32 v115, v114
	v_lshl_add_u64 v[72:73], v[68:69], 1, s[0:1]
	v_cvt_pk_bf16_f32 v78, v86, v87
	v_cvt_pk_bf16_f32 v79, v76, v77
	v_pk_mul_f32 v[82:83], v[74:75], v[114:115]
	s_and_b64 vcc, exec, s[10:11]
	s_mov_b64 s[0:1], -1
	global_store_dwordx2 v[72:73], v[78:79], off offset:8
	s_cbranch_vccnz .LBB0_1332
	v_lshlrev_b32_e32 v72, 2, v194
	v_lshlrev_b32_e32 v86, 2, v169
	global_load_dwordx4 v[76:79], v72, s[86:87] offset:32
	s_nop 0
	global_load_dwordx4 v[72:75], v86, s[66:67]
	v_mul_f32_e64 v92, |v84|, s69
	global_load_dwordx4 v[86:89], v86, s[56:57]
	v_max_f32_e32 v93, v84, v84
	v_mul_f32_e64 v94, |v85|, s69
	v_exp_f32_e32 v101, v92
	v_min_f32_e32 v96, 0, v93
	v_exp_f32_e32 v93, v94
	v_mul_f32_e64 v100, |v83|, s69
	v_exp_f32_e32 v103, v100
	v_add_f32_e32 v100, 1.0, v101
	v_max_f32_e32 v95, v85, v85
	v_add_f32_e32 v104, 1.0, v93
	v_cmp_lt_f32_e32 vcc, 0, v85
	v_min_f32_e32 v97, 0, v95
	s_nop 0
	v_cndmask_b32_e32 v95, 1.0, v93, vcc
	v_cmp_lt_f32_e32 vcc, 0, v84
	s_nop 1
	v_cndmask_b32_e32 v94, 1.0, v101, vcc
	v_mov_b32_e32 v93, v100
	v_mov_b32_e32 v101, v104
	v_log_f32_e32 v93, v93
	v_mul_f32_e64 v98, |v82|, s69
	v_log_f32_e32 v101, v101
	v_exp_f32_e32 v102, v98
	v_mul_f32_e32 v107, 0x3f317217, v93
	v_fma_f32 v107, v93, s75, -v107
	v_mul_f32_e32 v108, 0x3f317217, v101
	v_add_f32_e32 v105, 1.0, v102
	v_fma_f32 v108, v101, s75, -v108
	v_fmac_f32_e32 v107, 0x3377d1cf, v93
	v_rcp_f32_e32 v98, v100
	v_fmac_f32_e32 v108, 0x3377d1cf, v101
	v_fmac_f32_e32 v107, 0x3f317217, v93
	v_max_f32_e32 v99, v82, v82
	v_fmac_f32_e32 v108, 0x3f317217, v101
	v_mov_b32_e32 v93, v107
	v_min_f32_e32 v92, 0, v99
	v_rcp_f32_e32 v99, v104
	v_mov_b32_e32 v104, v105
	v_mov_b32_e32 v101, v108
	v_mov_b32_e32 v100, v93
	v_pk_add_f32 v[96:97], v[96:97], v[100:101] neg_lo:[0,1] neg_hi:[0,1]
	v_log_f32_e32 v104, v104
	v_or_b32_e32 v90, v112, v169
	v_mov_b32_e32 v91, v113
	s_mov_b64 s[0:1], 0
	v_mul_f32_e32 v109, 0x3f317217, v104
	v_fma_f32 v109, v104, s75, -v109
	v_fmac_f32_e32 v109, 0x3377d1cf, v104
	v_fmac_f32_e32 v109, 0x3f317217, v104
	s_waitcnt vmcnt(0)
	v_pk_add_f32 v[76:77], v[96:97], v[76:77]
	s_nop 0
	v_pk_add_f32 v[96:97], v[76:77], v[72:73] neg_lo:[0,1] neg_hi:[0,1]
	v_max_f32_e32 v93, v72, v72
	v_mul_f32_e64 v72, |v96|, s69
	v_max_f32_e32 v100, v73, v73
	v_mul_f32_e64 v73, |v97|, s69
	v_exp_f32_e32 v72, v72
	v_exp_f32_e32 v73, v73
	v_mov_b32_e32 v104, v109
	v_max_f32_e32 v76, v76, v93
	v_add_f32_e32 v72, 1.0, v72
	v_add_f32_e32 v73, 1.0, v73
	v_max_f32_e32 v77, v77, v100
	v_log_f32_e32 v72, v72
	v_log_f32_e32 v73, v73
	v_mul_f32_e32 v101, 0x3f317217, v72
	v_mul_f32_e32 v106, 0x3f317217, v73
	v_fma_f32 v101, v72, s75, -v101
	v_fma_f32 v106, v73, s75, -v106
	v_fmac_f32_e32 v101, 0x3377d1cf, v72
	v_fmac_f32_e32 v106, 0x3377d1cf, v73
	v_fmac_f32_e32 v101, 0x3f317217, v72
	v_fmac_f32_e32 v106, 0x3f317217, v73
	s_nop 0
	v_mov_b32_e32 v72, v101
	v_mov_b32_e32 v101, v72
	v_mov_b32_e32 v73, v106
	v_add_f32_e32 v106, 1.0, v103
	v_mov_b32_e32 v100, v73
	v_mov_b32_e32 v72, v104
	v_mov_b32_e32 v73, v106
	v_log_f32_e32 v73, v73
	v_max_f32_e32 v93, v83, v83
	v_min_f32_e32 v93, 0, v93
	v_mul_f32_e32 v104, 0x3f317217, v73
	v_fma_f32 v104, v73, s75, -v104
	v_fmac_f32_e32 v104, 0x3377d1cf, v73
	v_fmac_f32_e32 v104, 0x3f317217, v73
	s_nop 1
	v_mov_b32_e32 v73, v104
	v_pk_add_f32 v[72:73], v[92:93], v[72:73] neg_lo:[0,1] neg_hi:[0,1]
	s_nop 0
	v_pk_add_f32 v[78:79], v[72:73], v[78:79]
	s_nop 0
	v_pk_add_f32 v[92:93], v[78:79], v[74:75] neg_lo:[0,1] neg_hi:[0,1]
	v_mul_f32_e64 v72, |v92|, s69
	v_exp_f32_e32 v104, v72
	v_pk_mul_f32 v[72:73], v[94:95], v[86:87]
	v_mul_f32_e64 v95, |v93|, s69
	v_exp_f32_e32 v95, v95
	v_add_f32_e32 v87, 1.0, v104
	v_max_f32_e32 v74, v78, v74
	v_add_f32_e32 v95, 1.0, v95
	v_log_f32_e32 v94, v87
	v_pk_mul_f32 v[72:73], v[98:99], v[72:73]
	v_max_f32_e32 v75, v79, v75
	v_mul_f32_e32 v78, 0x3f317217, v94
	v_fma_f32 v78, v94, s75, -v78
	v_fmac_f32_e32 v78, 0x3377d1cf, v94
	v_fmac_f32_e32 v78, 0x3f317217, v94
	v_rcp_f32_e32 v86, v105
	v_rcp_f32_e32 v87, v106
	s_nop 0
	v_log_f32_e32 v95, v95
	v_cmp_lt_f32_e64 vcc, |v97|, s49
	v_mul_f32_e32 v79, 0x3f317217, v95
	v_fma_f32 v79, v95, s75, -v79
	v_fmac_f32_e32 v79, 0x3377d1cf, v95
	v_fmac_f32_e32 v79, 0x3f317217, v95
	s_nop 1
	v_cndmask_b32_e32 v95, 0, v100, vcc
	v_cmp_lt_f32_e64 vcc, |v96|, s49
	s_nop 0
	s_nop 0
	v_cndmask_b32_e32 v94, 0, v101, vcc
	v_cmp_lt_f32_e64 vcc, |v93|, s49
	v_pk_add_f32 v[76:77], v[76:77], v[94:95]
	s_nop 0
	v_cndmask_b32_e32 v79, 0, v79, vcc
	v_cmp_lt_f32_e64 vcc, |v92|, s49
	s_nop 1
	v_cndmask_b32_e32 v78, 0, v78, vcc
	v_cmp_lt_f32_e32 vcc, 0, v83
	v_pk_add_f32 v[78:79], v[74:75], v[78:79]
	s_nop 0
	v_cndmask_b32_e32 v75, 1.0, v103, vcc
	v_cmp_lt_f32_e32 vcc, 0, v82
	s_nop 1
	v_cndmask_b32_e32 v74, 1.0, v102, vcc
	v_pk_mul_f32 v[74:75], v[74:75], v[88:89]
	s_nop 0
	v_pk_mul_f32 v[74:75], v[86:87], v[74:75]
	v_lshl_add_u64 v[86:87], v[90:91], 2, s[94:95]
	global_store_dwordx4 v[86:87], v[76:79], off

.LBB0_1334:
	s_add_u32 s0, s22, s0
	s_addc_u32 s1, s23, s1
	v_mov_b32_e32 v115, v114
	v_lshl_add_u64 v[68:69], v[68:69], 1, s[0:1]
	v_cvt_pk_bf16_f32 v72, v72, v73
	v_cvt_pk_bf16_f32 v73, v74, v75
	v_or_b32_e32 v112, v112, v168
	v_pk_mul_f32 v[82:83], v[70:71], v[114:115]
	s_and_b64 vcc, exec, s[10:11]
	s_mov_b64 s[0:1], -1
	global_store_dwordx2 v[68:69], v[72:73], off offset:16
	s_cbranch_vccnz .LBB0_1336
	v_lshlrev_b32_e32 v68, 2, v194
	v_lshlrev_b32_e32 v76, 2, v168
	global_load_dwordx4 v[72:75], v68, s[86:87] offset:48
	s_nop 0
	global_load_dwordx4 v[68:71], v76, s[66:67]
	v_mul_f32_e64 v84, |v80|, s69
	global_load_dwordx4 v[76:79], v76, s[56:57]
	v_max_f32_e32 v85, v80, v80
	v_mul_f32_e64 v86, |v81|, s69
	v_exp_f32_e32 v93, v84
	v_min_f32_e32 v88, 0, v85
	v_exp_f32_e32 v85, v86
	v_max_f32_e32 v87, v81, v81
	v_mul_f32_e64 v92, |v83|, s69
	v_cmp_lt_f32_e32 vcc, 0, v81
	v_min_f32_e32 v89, 0, v87
	v_exp_f32_e32 v95, v92
	v_add_f32_e32 v92, 1.0, v93
	v_cndmask_b32_e32 v87, 1.0, v85, vcc
	v_cmp_lt_f32_e32 vcc, 0, v80
	v_add_f32_e32 v96, 1.0, v85
	s_nop 0
	v_cndmask_b32_e32 v86, 1.0, v93, vcc
	v_mov_b32_e32 v93, v96
	v_mov_b32_e32 v85, v92
	v_log_f32_e32 v85, v85
	v_log_f32_e32 v93, v93
	v_mul_f32_e64 v90, |v82|, s69
	v_exp_f32_e32 v94, v90
	v_mul_f32_e32 v101, 0x3f317217, v85
	v_mul_f32_e32 v102, 0x3f317217, v93
	v_fma_f32 v101, v85, s75, -v101
	v_fma_f32 v102, v93, s75, -v102
	v_fmac_f32_e32 v101, 0x3377d1cf, v85
	v_rcp_f32_e32 v90, v92
	v_fmac_f32_e32 v102, 0x3377d1cf, v93
	v_fmac_f32_e32 v101, 0x3f317217, v85
	v_max_f32_e32 v91, v82, v82
	v_add_f32_e32 v97, 1.0, v94
	v_fmac_f32_e32 v102, 0x3f317217, v93
	v_mov_b32_e32 v85, v101
	v_min_f32_e32 v84, 0, v91
	v_rcp_f32_e32 v91, v96
	v_mov_b32_e32 v93, v102
	v_mov_b32_e32 v92, v85
	v_mov_b32_e32 v99, v97
	v_pk_add_f32 v[88:89], v[88:89], v[92:93] neg_lo:[0,1] neg_hi:[0,1]
	v_log_f32_e32 v99, v99
	v_add_f32_e32 v98, 1.0, v95
	s_mov_b64 s[0:1], 0
	v_mul_f32_e32 v103, 0x3f317217, v99
	v_fma_f32 v103, v99, s75, -v103
	v_fmac_f32_e32 v103, 0x3377d1cf, v99
	v_fmac_f32_e32 v103, 0x3f317217, v99
	s_waitcnt vmcnt(0)
	v_pk_add_f32 v[88:89], v[88:89], v[72:73]
	s_nop 0
	v_pk_add_f32 v[72:73], v[88:89], v[68:69] neg_lo:[0,1] neg_hi:[0,1]
	v_max_f32_e32 v85, v68, v68
	v_mul_f32_e64 v68, |v72|, s69
	v_max_f32_e32 v92, v69, v69
	v_mul_f32_e64 v69, |v73|, s69
	v_exp_f32_e32 v93, v68
	v_exp_f32_e32 v96, v69
	v_max_f32_e32 v68, v88, v85
	v_mov_b32_e32 v99, v103
	v_add_f32_e32 v85, 1.0, v93
	v_add_f32_e32 v88, 1.0, v96
	v_max_f32_e32 v69, v89, v92
	v_log_f32_e32 v85, v85
	v_log_f32_e32 v88, v88
	v_mul_f32_e32 v93, 0x3f317217, v85
	v_mul_f32_e32 v96, 0x3f317217, v88
	v_fma_f32 v93, v85, s75, -v93
	v_fma_f32 v96, v88, s75, -v96
	v_fmac_f32_e32 v93, 0x3377d1cf, v85
	v_fmac_f32_e32 v96, 0x3377d1cf, v88
	v_fmac_f32_e32 v93, 0x3f317217, v85
	v_fmac_f32_e32 v96, 0x3f317217, v88
	v_pk_mul_f32 v[76:77], v[86:87], v[76:77]
	v_mov_b32_e32 v85, v93
	v_mov_b32_e32 v93, v85
	v_pk_mul_f32 v[76:77], v[90:91], v[76:77]
	v_mov_b32_e32 v88, v96
	v_mov_b32_e32 v92, v88
	v_mov_b32_e32 v88, v99
	v_mov_b32_e32 v85, v98
	v_log_f32_e32 v89, v85
	v_max_f32_e32 v85, v83, v83
	v_min_f32_e32 v85, 0, v85
	v_rcp_f32_e32 v86, v97
	v_mul_f32_e32 v96, 0x3f317217, v89
	v_fma_f32 v96, v89, s75, -v96
	v_fmac_f32_e32 v96, 0x3377d1cf, v89
	v_fmac_f32_e32 v96, 0x3f317217, v89
	s_nop 1
	v_mov_b32_e32 v89, v96
	v_pk_add_f32 v[84:85], v[84:85], v[88:89] neg_lo:[0,1] neg_hi:[0,1]
	s_nop 0
	v_pk_add_f32 v[74:75], v[84:85], v[74:75]
	s_nop 0
	v_pk_add_f32 v[84:85], v[74:75], v[70:71] neg_lo:[0,1] neg_hi:[0,1]
	v_mul_f32_e64 v88, |v84|, s69
	v_exp_f32_e32 v88, v88
	v_mul_f32_e64 v89, |v85|, s69
	v_exp_f32_e32 v89, v89
	v_max_f32_e32 v70, v74, v70
	v_add_f32_e32 v87, 1.0, v88
	v_add_f32_e32 v89, 1.0, v89
	s_nop 0
	v_log_f32_e32 v88, v87
	v_max_f32_e32 v71, v75, v71
	v_rcp_f32_e32 v87, v98
	v_mul_f32_e32 v74, 0x3f317217, v88
	v_fma_f32 v74, v88, s75, -v74
	v_fmac_f32_e32 v74, 0x3377d1cf, v88
	v_fmac_f32_e32 v74, 0x3f317217, v88
	s_nop 1
	s_nop 0
	v_log_f32_e32 v89, v89
	v_cmp_lt_f32_e64 vcc, |v73|, s49
	v_mul_f32_e32 v75, 0x3f317217, v89
	v_fma_f32 v75, v89, s75, -v75
	v_fmac_f32_e32 v75, 0x3377d1cf, v89
	v_fmac_f32_e32 v75, 0x3f317217, v89
	v_cndmask_b32_e32 v73, 0, v92, vcc
	v_cmp_lt_f32_e64 vcc, |v72|, s49
	s_nop 1
	v_cndmask_b32_e32 v72, 0, v93, vcc
	v_cmp_lt_f32_e64 vcc, |v85|, s49
	v_pk_add_f32 v[68:69], v[68:69], v[72:73]
	s_nop 0
	v_cndmask_b32_e32 v75, 0, v75, vcc
	v_cmp_lt_f32_e64 vcc, |v84|, s49
	s_nop 1
	v_cndmask_b32_e32 v74, 0, v74, vcc
	v_cmp_lt_f32_e32 vcc, 0, v83
	v_pk_add_f32 v[70:71], v[70:71], v[74:75]
	v_lshl_add_u64 v[74:75], v[112:113], 2, s[94:95]
	v_cndmask_b32_e32 v73, 1.0, v95, vcc
	v_cmp_lt_f32_e32 vcc, 0, v82
	global_store_dwordx4 v[74:75], v[68:71], off
	s_nop 0
	v_cndmask_b32_e32 v72, 1.0, v94, vcc
	v_pk_mul_f32 v[72:73], v[72:73], v[78:79]
	v_lshl_add_u64 v[68:69], v[112:113], 1, s[84:85]
	v_pk_mul_f32 v[72:73], v[86:87], v[72:73]
	v_cvt_pk_bf16_f32 v70, v76, v77
	v_cvt_pk_bf16_f32 v71, v72, v73
	global_store_dwordx2 v[68:69], v[70:71], off

.LBB0_1373:
	s_and_b64 vcc, exec, s[0:1]
	s_cbranch_vccz .LBB0_1390
	s_and_b64 vcc, exec, s[10:11]
	s_mov_b64 s[0:1], -1
	s_cbranch_vccnz .LBB0_1376
	v_lshlrev_b32_e32 v52, 2, v194
	global_load_dwordx4 v[96:99], v52, s[86:87]
	global_load_dwordx4 v[92:95], v52, s[66:67]
	global_load_dwordx4 v[100:103], v52, s[56:57]
	v_mul_f32_e64 v53, |v88|, s69
	v_max_f32_e32 v56, v88, v88
	v_mul_f32_e64 v57, |v89|, s69
	v_exp_f32_e32 v82, v53
	v_min_f32_e32 v52, 0, v56
	v_exp_f32_e32 v56, v57
	v_mul_f32_e64 v67, |v91|, s69
	v_cmp_lt_f32_e32 vcc, 0, v89
	v_max_f32_e32 v60, v89, v89
	v_mul_f32_e64 v61, |v90|, s69
	v_max_f32_e32 v66, v90, v90
	v_exp_f32_e32 v87, v67
	v_add_f32_e32 v57, 1.0, v82
	v_cndmask_b32_e32 v67, 1.0, v56, vcc
	v_cmp_lt_f32_e32 vcc, 0, v88
	v_min_f32_e32 v53, 0, v60
	v_exp_f32_e32 v86, v61
	v_min_f32_e32 v60, 0, v66
	v_add_f32_e32 v61, 1.0, v56
	v_cndmask_b32_e32 v66, 1.0, v82, vcc
	v_rcp_f32_e32 v83, v61
	v_mov_b32_e32 v56, v57
	v_log_f32_e32 v56, v56
	v_log_f32_e32 v61, v61
	v_rcp_f32_e32 v82, v57
	v_mul_f32_e32 v114, 0x3f317217, v56
	v_mul_f32_e32 v115, 0x3f317217, v61
	v_fma_f32 v114, v56, s75, -v114
	v_fma_f32 v115, v61, s75, -v115
	v_fmac_f32_e32 v114, 0x3377d1cf, v56
	v_fmac_f32_e32 v115, 0x3377d1cf, v61
	v_fmac_f32_e32 v114, 0x3f317217, v56
	v_add_f32_e32 v104, 1.0, v86
	v_fmac_f32_e32 v115, 0x3f317217, v61
	v_mov_b32_e32 v56, v114
	v_mov_b32_e32 v61, v115
	v_mov_b32_e32 v57, v61
	v_mov_b32_e32 v107, v104
	v_pk_add_f32 v[52:53], v[52:53], v[56:57] neg_lo:[0,1] neg_hi:[0,1]
	v_log_f32_e32 v107, v107
	v_add_f32_e32 v105, 1.0, v87
	s_mov_b64 s[0:1], 0
	v_mul_f32_e32 v116, 0x3f317217, v107
	v_fma_f32 v116, v107, s75, -v116
	v_fmac_f32_e32 v116, 0x3377d1cf, v107
	v_fmac_f32_e32 v116, 0x3f317217, v107
	s_waitcnt vmcnt(0)
	v_pk_add_f32 v[52:53], v[52:53], v[96:97]
	s_nop 0
	v_pk_add_f32 v[56:57], v[52:53], v[92:93] neg_lo:[0,1] neg_hi:[0,1]
	v_max_f32_e32 v61, v92, v92
	v_mul_f32_e64 v92, |v56|, s69
	v_max_f32_e32 v96, v93, v93
	v_mul_f32_e64 v93, |v57|, s69
	v_exp_f32_e32 v92, v92
	v_exp_f32_e32 v93, v93
	v_max_f32_e32 v52, v52, v61
	v_mov_b32_e32 v107, v116
	v_add_f32_e32 v61, 1.0, v92
	v_add_f32_e32 v92, 1.0, v93
	v_max_f32_e32 v53, v53, v96
	v_log_f32_e32 v61, v61
	v_log_f32_e32 v92, v92
	v_mul_f32_e32 v97, 0x3f317217, v61
	v_mul_f32_e32 v106, 0x3f317217, v92
	v_fma_f32 v97, v61, s75, -v97
	v_fma_f32 v106, v92, s75, -v106
	v_fmac_f32_e32 v97, 0x3377d1cf, v61
	v_fmac_f32_e32 v106, 0x3377d1cf, v92
	v_fmac_f32_e32 v97, 0x3f317217, v61
	v_fmac_f32_e32 v106, 0x3f317217, v92
	s_nop 0
	v_mov_b32_e32 v61, v97
	s_nop 1
	v_mov_b32_e32 v92, v106
	v_mov_b32_e32 v106, v61
	v_mov_b32_e32 v114, v92
	v_mov_b32_e32 v61, v105
	v_log_f32_e32 v93, v61
	v_max_f32_e32 v61, v91, v91
	v_mov_b32_e32 v92, v107
	v_min_f32_e32 v61, 0, v61
	v_mul_f32_e32 v96, 0x3f317217, v93
	v_fma_f32 v96, v93, s75, -v96
	v_fmac_f32_e32 v96, 0x3377d1cf, v93
	v_fmac_f32_e32 v96, 0x3f317217, v93
	s_nop 1
	v_mov_b32_e32 v93, v96
	v_pk_add_f32 v[60:61], v[60:61], v[92:93] neg_lo:[0,1] neg_hi:[0,1]
	s_nop 0
	v_pk_add_f32 v[92:93], v[60:61], v[98:99]
	s_nop 0
	v_pk_add_f32 v[96:97], v[92:93], v[94:95] neg_lo:[0,1] neg_hi:[0,1]
	s_nop 0
	v_mul_f32_e64 v60, |v96|, s69
	v_exp_f32_e32 v98, v60
	v_pk_mul_f32 v[60:61], v[66:67], v[100:101]
	v_rcp_f32_e32 v66, v104
	v_pk_mul_f32 v[60:61], v[82:83], v[60:61]
	v_add_f32_e32 v67, 1.0, v98
	s_nop 1
	v_log_f32_e32 v83, v67
	v_max_f32_e32 v82, v94, v94
	v_mul_f32_e64 v94, |v97|, s69
	v_exp_f32_e32 v94, v94
	v_max_f32_e32 v82, v92, v82
	v_mul_f32_e32 v92, 0x3f317217, v83
	v_fma_f32 v92, v83, s75, -v92
	v_fmac_f32_e32 v92, 0x3377d1cf, v83
	v_fmac_f32_e32 v92, 0x3f317217, v83
	v_add_f32_e32 v94, 1.0, v94
	v_rcp_f32_e32 v67, v105
	v_mov_b32_e32 v83, v92
	v_mov_b32_e32 v92, v83
	s_nop 0
	v_mov_b32_e32 v98, 0
	v_log_f32_e32 v94, v94
	v_max_f32_e32 v83, v93, v95
	v_mul_f32_e32 v93, 0x3f317217, v94
	v_fma_f32 v93, v94, s75, -v93
	v_fmac_f32_e32 v93, 0x3377d1cf, v94
	v_fmac_f32_e32 v93, 0x3f317217, v94
	s_nop 1
	v_cmp_lt_f32_e64 vcc, |v57|, s49
	s_nop 0
	s_nop 0
	v_cndmask_b32_e32 v57, 0, v114, vcc
	v_cmp_lt_f32_e64 vcc, |v56|, s49
	s_nop 1
	v_cndmask_b32_e32 v56, 0, v106, vcc
	v_cmp_lt_f32_e64 vcc, |v97|, s49
	s_nop 1
	v_cndmask_b32_e32 v93, 0, v93, vcc
	v_cmp_lt_f32_e64 vcc, |v96|, s49
	s_nop 1
	v_cndmask_b32_e32 v92, 0, v92, vcc
	v_cmp_lt_f32_e32 vcc, 0, v91
	v_pk_add_f32 v[94:95], v[82:83], v[92:93]
	v_pk_add_f32 v[92:93], v[52:53], v[56:57]
	v_cndmask_b32_e32 v53, 1.0, v87, vcc
	v_cmp_lt_f32_e32 vcc, 0, v90
	v_lshl_add_u64 v[56:57], v[112:113], 2, s[94:95]
	global_store_dwordx4 v[56:57], v[92:95], off
	v_cndmask_b32_e32 v52, 1.0, v86, vcc
	v_pk_mul_f32 v[52:53], v[52:53], v[102:103]
	s_nop 0
	v_pk_mul_f32 v[52:53], v[66:67], v[52:53]

.LBB0_1378:
	s_add_u32 s0, s22, s0
	s_addc_u32 s1, s23, s1
	v_mov_b32_e32 v111, v110
	v_lshl_add_u64 v[56:57], v[112:113], 1, s[0:1]
	v_cvt_pk_bf16_f32 v60, v60, v61
	v_cvt_pk_bf16_f32 v61, v52, v53
	v_pk_mul_f32 v[52:53], v[62:63], v[110:111]
	s_and_b64 vcc, exec, s[10:11]
	s_mov_b64 s[0:1], -1
	global_store_dwordx2 v[56:57], v[60:61], off
	s_cbranch_vccnz .LBB0_1380
	v_lshlrev_b32_e32 v56, 2, v194
	v_lshlrev_b32_e32 v66, 2, v170
	global_load_dwordx4 v[86:89], v56, s[86:87] offset:16
	global_load_dwordx4 v[60:63], v66, s[66:67]
	global_load_dwordx4 v[90:93], v66, s[56:57]
	v_mul_f32_e64 v67, |v84|, s69
	v_max_f32_e32 v82, v84, v84
	v_mul_f32_e64 v83, |v85|, s69
	v_exp_f32_e32 v67, v67
	v_min_f32_e32 v94, 0, v82
	v_exp_f32_e32 v82, v83
	v_mul_f32_e64 v98, |v53|, s69
	v_exp_f32_e32 v101, v98
	v_add_f32_e32 v98, 1.0, v67
	v_cmp_lt_f32_e32 vcc, 0, v85
	v_add_f32_e32 v99, 1.0, v82
	s_nop 0
	v_cndmask_b32_e32 v83, 1.0, v82, vcc
	v_cmp_lt_f32_e32 vcc, 0, v84
	v_max_f32_e32 v97, v52, v52
	s_nop 0
	v_cndmask_b32_e32 v82, 1.0, v67, vcc
	v_mov_b32_e32 v67, v98
	v_min_f32_e32 v66, 0, v97
	v_rcp_f32_e32 v97, v99
	v_log_f32_e32 v67, v67
	v_mul_f32_e64 v96, |v52|, s69
	v_log_f32_e32 v99, v99
	v_exp_f32_e32 v100, v96
	v_mul_f32_e32 v105, 0x3f317217, v67
	v_fma_f32 v105, v67, s75, -v105
	v_mul_f32_e32 v106, 0x3f317217, v99
	v_add_f32_e32 v102, 1.0, v100
	v_fma_f32 v106, v99, s75, -v106
	v_fmac_f32_e32 v105, 0x3377d1cf, v67
	v_rcp_f32_e32 v96, v98
	v_fmac_f32_e32 v106, 0x3377d1cf, v99
	v_fmac_f32_e32 v105, 0x3f317217, v67
	v_fmac_f32_e32 v106, 0x3f317217, v99
	v_mov_b32_e32 v67, v105
	v_max_f32_e32 v95, v85, v85
	v_mov_b32_e32 v103, v102
	v_mov_b32_e32 v99, v106
	v_min_f32_e32 v95, 0, v95
	v_mov_b32_e32 v98, v67
	v_pk_add_f32 v[94:95], v[94:95], v[98:99] neg_lo:[0,1] neg_hi:[0,1]
	v_log_f32_e32 v103, v103
	v_or_b32_e32 v56, v108, v170
	v_mov_b32_e32 v57, v109
	v_lshl_add_u64 v[56:57], v[56:57], 2, s[94:95]
	v_mul_f32_e32 v107, 0x3f317217, v103
	v_fma_f32 v107, v103, s75, -v107
	v_fmac_f32_e32 v107, 0x3377d1cf, v103
	v_fmac_f32_e32 v107, 0x3f317217, v103
	s_mov_b64 s[0:1], 0
	s_waitcnt vmcnt(0)
	v_pk_add_f32 v[86:87], v[94:95], v[86:87]
	s_nop 0
	v_pk_add_f32 v[94:95], v[86:87], v[60:61] neg_lo:[0,1] neg_hi:[0,1]
	v_max_f32_e32 v67, v60, v60
	v_mul_f32_e64 v60, |v94|, s69
	v_max_f32_e32 v98, v61, v61
	v_mul_f32_e64 v61, |v95|, s69
	v_exp_f32_e32 v60, v60
	v_exp_f32_e32 v61, v61
	v_mov_b32_e32 v103, v107
	v_max_f32_e32 v86, v86, v67
	v_add_f32_e32 v60, 1.0, v60
	v_add_f32_e32 v61, 1.0, v61
	v_max_f32_e32 v87, v87, v98
	v_log_f32_e32 v60, v60
	v_log_f32_e32 v61, v61
	v_mul_f32_e32 v99, 0x3f317217, v60
	v_mul_f32_e32 v104, 0x3f317217, v61
	v_fma_f32 v99, v60, s75, -v99
	v_fma_f32 v104, v61, s75, -v104
	v_fmac_f32_e32 v99, 0x3377d1cf, v60
	v_fmac_f32_e32 v104, 0x3377d1cf, v61
	v_fmac_f32_e32 v99, 0x3f317217, v60
	v_fmac_f32_e32 v104, 0x3f317217, v61
	s_nop 0
	v_mov_b32_e32 v60, v99
	v_mov_b32_e32 v99, v60
	v_mov_b32_e32 v61, v104
	v_add_f32_e32 v104, 1.0, v101
	v_mov_b32_e32 v98, v61
	v_mov_b32_e32 v60, v103
	v_mov_b32_e32 v61, v104
	v_log_f32_e32 v61, v61
	v_max_f32_e32 v67, v53, v53
	v_min_f32_e32 v67, 0, v67
	v_mul_f32_e32 v103, 0x3f317217, v61
	v_fma_f32 v103, v61, s75, -v103
	v_fmac_f32_e32 v103, 0x3377d1cf, v61
	v_fmac_f32_e32 v103, 0x3f317217, v61
	s_nop 1
	v_mov_b32_e32 v61, v103
	v_pk_add_f32 v[60:61], v[66:67], v[60:61] neg_lo:[0,1] neg_hi:[0,1]
	s_nop 0
	v_pk_add_f32 v[66:67], v[60:61], v[88:89]
	s_nop 0
	v_pk_add_f32 v[88:89], v[66:67], v[62:63] neg_lo:[0,1] neg_hi:[0,1]
	v_mul_f32_e64 v60, |v88|, s69
	v_exp_f32_e32 v103, v60
	v_pk_mul_f32 v[60:61], v[82:83], v[90:91]
	v_mul_f32_e64 v91, |v89|, s69
	v_exp_f32_e32 v91, v91
	v_add_f32_e32 v83, 1.0, v103
	v_max_f32_e32 v62, v66, v62
	v_add_f32_e32 v91, 1.0, v91
	v_log_f32_e32 v90, v83
	v_pk_mul_f32 v[60:61], v[96:97], v[60:61]
	v_max_f32_e32 v63, v67, v63
	v_mul_f32_e32 v66, 0x3f317217, v90
	v_fma_f32 v66, v90, s75, -v66
	v_fmac_f32_e32 v66, 0x3377d1cf, v90
	v_fmac_f32_e32 v66, 0x3f317217, v90
	v_rcp_f32_e32 v82, v102
	v_rcp_f32_e32 v83, v104
	v_mov_b32_e32 v90, v66
	s_nop 0
	v_mov_b32_e32 v96, 0
	v_log_f32_e32 v91, v91
	v_cmp_lt_f32_e64 vcc, |v95|, s49
	v_mul_f32_e32 v66, 0x3f317217, v91
	v_fma_f32 v66, v91, s75, -v66
	v_fmac_f32_e32 v66, 0x3377d1cf, v91
	v_fmac_f32_e32 v66, 0x3f317217, v91
	s_nop 1
	v_mov_b32_e32 v91, v66
	v_cndmask_b32_e32 v67, 0, v98, vcc
	v_cmp_lt_f32_e64 vcc, |v94|, s49
	s_nop 1
	v_cndmask_b32_e32 v66, 0, v99, vcc
	v_cmp_lt_f32_e64 vcc, |v89|, s49
	v_pk_add_f32 v[86:87], v[86:87], v[66:67]
	s_nop 0
	v_cndmask_b32_e32 v89, 0, v91, vcc
	v_cmp_lt_f32_e64 vcc, |v88|, s49
	s_nop 1
	v_cndmask_b32_e32 v88, 0, v90, vcc
	v_cmp_lt_f32_e32 vcc, 0, v53
	v_pk_add_f32 v[88:89], v[62:63], v[88:89]
	global_store_dwordx4 v[56:57], v[86:89], off
	v_cndmask_b32_e32 v63, 1.0, v101, vcc
	v_cmp_lt_f32_e32 vcc, 0, v52
	s_nop 1
	v_cndmask_b32_e32 v62, 1.0, v100, vcc
	v_pk_mul_f32 v[62:63], v[62:63], v[92:93]
	s_nop 0
	v_pk_mul_f32 v[62:63], v[82:83], v[62:63]

.LBB0_1382:
	s_add_u32 s0, s22, s0
	s_addc_u32 s1, s23, s1
	v_lshl_add_u64 v[52:53], v[108:109], 0, v[194:195]
	v_mov_b32_e32 v111, v110
	v_lshl_add_u64 v[56:57], v[52:53], 1, s[0:1]
	v_cvt_pk_bf16_f32 v60, v60, v61
	v_cvt_pk_bf16_f32 v61, v62, v63
	v_pk_mul_f32 v[66:67], v[58:59], v[110:111]
	s_and_b64 vcc, exec, s[10:11]
	s_mov_b64 s[0:1], -1
	global_store_dwordx2 v[56:57], v[60:61], off offset:8
	s_cbranch_vccnz .LBB0_1384
	v_lshlrev_b32_e32 v56, 2, v194
	v_lshlrev_b32_e32 v82, 2, v169
	global_load_dwordx4 v[60:63], v56, s[86:87] offset:32
	s_nop 0
	global_load_dwordx4 v[56:59], v82, s[66:67]
	v_mul_f32_e64 v88, |v80|, s69
	global_load_dwordx4 v[82:85], v82, s[56:57]
	v_max_f32_e32 v89, v80, v80
	v_mul_f32_e64 v90, |v81|, s69
	v_exp_f32_e32 v97, v88
	v_min_f32_e32 v92, 0, v89
	v_exp_f32_e32 v89, v90
	v_mul_f32_e64 v96, |v67|, s69
	v_exp_f32_e32 v99, v96
	v_add_f32_e32 v96, 1.0, v97
	v_max_f32_e32 v91, v81, v81
	v_add_f32_e32 v100, 1.0, v89
	v_cmp_lt_f32_e32 vcc, 0, v81
	v_min_f32_e32 v93, 0, v91
	s_nop 0
	v_cndmask_b32_e32 v91, 1.0, v89, vcc
	v_cmp_lt_f32_e32 vcc, 0, v80
	s_nop 1
	v_cndmask_b32_e32 v90, 1.0, v97, vcc
	v_mov_b32_e32 v89, v96
	v_mov_b32_e32 v97, v100
	v_log_f32_e32 v89, v89
	v_mul_f32_e64 v94, |v66|, s69
	v_log_f32_e32 v97, v97
	v_exp_f32_e32 v98, v94
	v_mul_f32_e32 v103, 0x3f317217, v89
	v_fma_f32 v103, v89, s75, -v103
	v_mul_f32_e32 v104, 0x3f317217, v97
	v_add_f32_e32 v101, 1.0, v98
	v_fma_f32 v104, v97, s75, -v104
	v_fmac_f32_e32 v103, 0x3377d1cf, v89
	v_rcp_f32_e32 v94, v96
	v_fmac_f32_e32 v104, 0x3377d1cf, v97
	v_fmac_f32_e32 v103, 0x3f317217, v89
	v_max_f32_e32 v95, v66, v66
	v_fmac_f32_e32 v104, 0x3f317217, v97
	v_mov_b32_e32 v89, v103
	v_min_f32_e32 v88, 0, v95
	v_rcp_f32_e32 v95, v100
	v_mov_b32_e32 v100, v101
	v_mov_b32_e32 v97, v104
	v_mov_b32_e32 v96, v89
	v_pk_add_f32 v[92:93], v[92:93], v[96:97] neg_lo:[0,1] neg_hi:[0,1]
	v_log_f32_e32 v100, v100
	v_or_b32_e32 v86, v108, v169
	v_mov_b32_e32 v87, v109
	s_mov_b64 s[0:1], 0
	v_mul_f32_e32 v105, 0x3f317217, v100
	v_fma_f32 v105, v100, s75, -v105
	v_fmac_f32_e32 v105, 0x3377d1cf, v100
	v_fmac_f32_e32 v105, 0x3f317217, v100
	s_waitcnt vmcnt(0)
	v_pk_add_f32 v[60:61], v[92:93], v[60:61]
	s_nop 0
	v_pk_add_f32 v[92:93], v[60:61], v[56:57] neg_lo:[0,1] neg_hi:[0,1]
	v_max_f32_e32 v89, v56, v56
	v_mul_f32_e64 v56, |v92|, s69
	v_max_f32_e32 v96, v57, v57
	v_mul_f32_e64 v57, |v93|, s69
	v_exp_f32_e32 v56, v56
	v_exp_f32_e32 v57, v57
	v_mov_b32_e32 v100, v105
	v_max_f32_e32 v60, v60, v89
	v_add_f32_e32 v56, 1.0, v56
	v_add_f32_e32 v57, 1.0, v57
	v_max_f32_e32 v61, v61, v96
	v_log_f32_e32 v56, v56
	v_log_f32_e32 v57, v57
	v_mul_f32_e32 v97, 0x3f317217, v56
	v_mul_f32_e32 v102, 0x3f317217, v57
	v_fma_f32 v97, v56, s75, -v97
	v_fma_f32 v102, v57, s75, -v102
	v_fmac_f32_e32 v97, 0x3377d1cf, v56
	v_fmac_f32_e32 v102, 0x3377d1cf, v57
	v_fmac_f32_e32 v97, 0x3f317217, v56
	v_fmac_f32_e32 v102, 0x3f317217, v57
	s_nop 0
	v_mov_b32_e32 v56, v97
	v_mov_b32_e32 v97, v56
	v_mov_b32_e32 v57, v102
	v_add_f32_e32 v102, 1.0, v99
	v_mov_b32_e32 v96, v57
	v_mov_b32_e32 v56, v100
	v_mov_b32_e32 v57, v102
	v_log_f32_e32 v57, v57
	v_max_f32_e32 v89, v67, v67
	v_min_f32_e32 v89, 0, v89
	v_mul_f32_e32 v100, 0x3f317217, v57
	v_fma_f32 v100, v57, s75, -v100
	v_fmac_f32_e32 v100, 0x3377d1cf, v57
	v_fmac_f32_e32 v100, 0x3f317217, v57
	s_nop 1
	v_mov_b32_e32 v57, v100
	v_pk_add_f32 v[56:57], v[88:89], v[56:57] neg_lo:[0,1] neg_hi:[0,1]
	s_nop 0
	v_pk_add_f32 v[62:63], v[56:57], v[62:63]
	s_nop 0
	v_pk_add_f32 v[88:89], v[62:63], v[58:59] neg_lo:[0,1] neg_hi:[0,1]
	v_mul_f32_e64 v56, |v88|, s69
	v_exp_f32_e32 v100, v56
	v_pk_mul_f32 v[56:57], v[90:91], v[82:83]
	v_mul_f32_e64 v91, |v89|, s69
	v_exp_f32_e32 v91, v91
	v_add_f32_e32 v83, 1.0, v100
	v_max_f32_e32 v58, v62, v58
	v_add_f32_e32 v91, 1.0, v91
	v_log_f32_e32 v90, v83
	v_pk_mul_f32 v[56:57], v[94:95], v[56:57]
	v_max_f32_e32 v59, v63, v59
	v_mul_f32_e32 v62, 0x3f317217, v90
	v_fma_f32 v62, v90, s75, -v62
	v_fmac_f32_e32 v62, 0x3377d1cf, v90
	v_fmac_f32_e32 v62, 0x3f317217, v90
	v_rcp_f32_e32 v82, v101
	v_rcp_f32_e32 v83, v102
	s_nop 0
	v_log_f32_e32 v91, v91
	v_cmp_lt_f32_e64 vcc, |v93|, s49
	v_mul_f32_e32 v63, 0x3f317217, v91
	v_fma_f32 v63, v91, s75, -v63
	v_fmac_f32_e32 v63, 0x3377d1cf, v91
	v_fmac_f32_e32 v63, 0x3f317217, v91
	s_nop 1
	v_cndmask_b32_e32 v91, 0, v96, vcc
	v_cmp_lt_f32_e64 vcc, |v92|, s49
	s_nop 0
	s_nop 0
	v_cndmask_b32_e32 v90, 0, v97, vcc
	v_cmp_lt_f32_e64 vcc, |v89|, s49
	v_pk_add_f32 v[60:61], v[60:61], v[90:91]
	s_nop 0
	v_cndmask_b32_e32 v63, 0, v63, vcc
	v_cmp_lt_f32_e64 vcc, |v88|, s49
	s_nop 1
	v_cndmask_b32_e32 v62, 0, v62, vcc
	v_cmp_lt_f32_e32 vcc, 0, v67
	v_pk_add_f32 v[62:63], v[58:59], v[62:63]
	s_nop 0
	v_cndmask_b32_e32 v59, 1.0, v99, vcc
	v_cmp_lt_f32_e32 vcc, 0, v66
	s_nop 1
	v_cndmask_b32_e32 v58, 1.0, v98, vcc
	v_pk_mul_f32 v[58:59], v[58:59], v[84:85]
	s_nop 0
	v_pk_mul_f32 v[58:59], v[82:83], v[58:59]
	v_lshl_add_u64 v[82:83], v[86:87], 2, s[94:95]
	global_store_dwordx4 v[82:83], v[60:63], off

.LBB0_1386:
	s_add_u32 s0, s22, s0
	s_addc_u32 s1, s23, s1
	v_mov_b32_e32 v111, v110
	v_lshl_add_u64 v[52:53], v[52:53], 1, s[0:1]
	v_cvt_pk_bf16_f32 v56, v56, v57
	v_cvt_pk_bf16_f32 v57, v58, v59
	v_or_b32_e32 v108, v108, v168
	v_pk_mul_f32 v[66:67], v[54:55], v[110:111]
	s_and_b64 vcc, exec, s[10:11]
	s_mov_b64 s[0:1], -1
	global_store_dwordx2 v[52:53], v[56:57], off offset:16
	s_cbranch_vccnz .LBB0_1388
	v_lshlrev_b32_e32 v52, 2, v194
	v_lshlrev_b32_e32 v60, 2, v168
	global_load_dwordx4 v[56:59], v52, s[86:87] offset:48
	s_nop 0
	global_load_dwordx4 v[52:55], v60, s[66:67]
	v_mul_f32_e64 v80, |v64|, s69
	global_load_dwordx4 v[60:63], v60, s[56:57]
	v_max_f32_e32 v81, v64, v64
	v_mul_f32_e64 v82, |v65|, s69
	v_exp_f32_e32 v89, v80
	v_min_f32_e32 v84, 0, v81
	v_exp_f32_e32 v81, v82
	v_max_f32_e32 v83, v65, v65
	v_mul_f32_e64 v88, |v67|, s69
	v_cmp_lt_f32_e32 vcc, 0, v65
	v_min_f32_e32 v85, 0, v83
	v_exp_f32_e32 v91, v88
	v_add_f32_e32 v88, 1.0, v89
	v_cndmask_b32_e32 v83, 1.0, v81, vcc
	v_cmp_lt_f32_e32 vcc, 0, v64
	v_add_f32_e32 v92, 1.0, v81
	s_nop 0
	v_cndmask_b32_e32 v82, 1.0, v89, vcc
	v_mov_b32_e32 v89, v92
	v_mov_b32_e32 v81, v88
	v_log_f32_e32 v81, v81
	v_log_f32_e32 v89, v89
	v_mul_f32_e64 v86, |v66|, s69
	v_exp_f32_e32 v90, v86
	v_mul_f32_e32 v97, 0x3f317217, v81
	v_mul_f32_e32 v98, 0x3f317217, v89
	v_fma_f32 v97, v81, s75, -v97
	v_fma_f32 v98, v89, s75, -v98
	v_fmac_f32_e32 v97, 0x3377d1cf, v81
	v_rcp_f32_e32 v86, v88
	v_fmac_f32_e32 v98, 0x3377d1cf, v89
	v_fmac_f32_e32 v97, 0x3f317217, v81
	v_max_f32_e32 v87, v66, v66
	v_add_f32_e32 v93, 1.0, v90
	v_fmac_f32_e32 v98, 0x3f317217, v89
	v_mov_b32_e32 v81, v97
	v_min_f32_e32 v80, 0, v87
	v_rcp_f32_e32 v87, v92
	v_mov_b32_e32 v89, v98
	v_mov_b32_e32 v88, v81
	v_mov_b32_e32 v95, v93
	v_pk_add_f32 v[84:85], v[84:85], v[88:89] neg_lo:[0,1] neg_hi:[0,1]
	v_log_f32_e32 v95, v95
	v_add_f32_e32 v94, 1.0, v91
	v_mov_b32_e32 v96, 0
	s_mov_b64 s[0:1], 0
	v_mul_f32_e32 v99, 0x3f317217, v95
	v_fma_f32 v99, v95, s75, -v99
	v_fmac_f32_e32 v99, 0x3377d1cf, v95
	v_fmac_f32_e32 v99, 0x3f317217, v95
	s_waitcnt vmcnt(0)
	v_pk_add_f32 v[84:85], v[84:85], v[56:57]
	s_nop 0
	v_pk_add_f32 v[56:57], v[84:85], v[52:53] neg_lo:[0,1] neg_hi:[0,1]
	v_max_f32_e32 v81, v52, v52
	v_mul_f32_e64 v52, |v56|, s69
	v_max_f32_e32 v88, v53, v53
	v_mul_f32_e64 v53, |v57|, s69
	v_exp_f32_e32 v89, v52
	v_exp_f32_e32 v92, v53
	v_max_f32_e32 v52, v84, v81
	v_mov_b32_e32 v95, v99
	v_add_f32_e32 v81, 1.0, v89
	v_add_f32_e32 v84, 1.0, v92
	v_max_f32_e32 v53, v85, v88
	v_log_f32_e32 v81, v81
	v_log_f32_e32 v84, v84
	v_mul_f32_e32 v89, 0x3f317217, v81
	v_mul_f32_e32 v92, 0x3f317217, v84
	v_fma_f32 v89, v81, s75, -v89
	v_fma_f32 v92, v84, s75, -v92
	v_fmac_f32_e32 v89, 0x3377d1cf, v81
	v_fmac_f32_e32 v92, 0x3377d1cf, v84
	v_fmac_f32_e32 v89, 0x3f317217, v81
	v_fmac_f32_e32 v92, 0x3f317217, v84
	v_pk_mul_f32 v[60:61], v[82:83], v[60:61]
	v_mov_b32_e32 v81, v89
	v_mov_b32_e32 v89, v81
	v_pk_mul_f32 v[60:61], v[86:87], v[60:61]
	v_mov_b32_e32 v84, v92
	v_mov_b32_e32 v88, v84
	v_mov_b32_e32 v84, v95
	v_mov_b32_e32 v81, v94
	v_log_f32_e32 v85, v81
	v_max_f32_e32 v81, v67, v67
	v_min_f32_e32 v81, 0, v81
	v_rcp_f32_e32 v82, v93
	v_mul_f32_e32 v92, 0x3f317217, v85
	v_fma_f32 v92, v85, s75, -v92
	v_fmac_f32_e32 v92, 0x3377d1cf, v85
	v_fmac_f32_e32 v92, 0x3f317217, v85
	s_nop 1
	v_mov_b32_e32 v85, v92
	v_pk_add_f32 v[80:81], v[80:81], v[84:85] neg_lo:[0,1] neg_hi:[0,1]
	s_nop 0
	v_pk_add_f32 v[58:59], v[80:81], v[58:59]
	s_nop 0
	v_pk_add_f32 v[80:81], v[58:59], v[54:55] neg_lo:[0,1] neg_hi:[0,1]
	v_mul_f32_e64 v84, |v80|, s69
	v_exp_f32_e32 v84, v84
	v_mul_f32_e64 v85, |v81|, s69
	v_exp_f32_e32 v85, v85
	v_max_f32_e32 v54, v58, v54
	v_add_f32_e32 v83, 1.0, v84
	v_add_f32_e32 v85, 1.0, v85
	s_nop 0
	v_log_f32_e32 v84, v83
	v_max_f32_e32 v55, v59, v55
	v_rcp_f32_e32 v83, v94
	v_mul_f32_e32 v58, 0x3f317217, v84
	v_fma_f32 v58, v84, s75, -v58
	v_fmac_f32_e32 v58, 0x3377d1cf, v84
	v_fmac_f32_e32 v58, 0x3f317217, v84
	s_nop 1
	s_nop 0
	v_mov_b32_e32 v86, 0
	v_log_f32_e32 v85, v85
	v_mov_b32_e32 v84, 0
	v_cmp_lt_f32_e64 vcc, |v57|, s49
	v_mul_f32_e32 v59, 0x3f317217, v85
	v_fma_f32 v59, v85, s75, -v59
	v_fmac_f32_e32 v59, 0x3377d1cf, v85
	v_fmac_f32_e32 v59, 0x3f317217, v85
	v_cndmask_b32_e32 v57, 0, v88, vcc
	v_cmp_lt_f32_e64 vcc, |v56|, s49
	s_nop 1
	v_cndmask_b32_e32 v56, 0, v89, vcc
	v_cmp_lt_f32_e64 vcc, |v81|, s49
	v_pk_add_f32 v[52:53], v[52:53], v[56:57]
	s_nop 0
	v_cndmask_b32_e32 v59, 0, v59, vcc
	v_cmp_lt_f32_e64 vcc, |v80|, s49
	s_nop 1
	v_cndmask_b32_e32 v58, 0, v58, vcc
	v_cmp_lt_f32_e32 vcc, 0, v67
	v_pk_add_f32 v[54:55], v[54:55], v[58:59]
	v_lshl_add_u64 v[58:59], v[108:109], 2, s[94:95]
	v_cndmask_b32_e32 v57, 1.0, v91, vcc
	v_cmp_lt_f32_e32 vcc, 0, v66
	global_store_dwordx4 v[58:59], v[52:55], off
	s_nop 0
	v_cndmask_b32_e32 v56, 1.0, v90, vcc
	v_pk_mul_f32 v[56:57], v[56:57], v[62:63]
	v_lshl_add_u64 v[52:53], v[108:109], 1, s[84:85]
	v_pk_mul_f32 v[56:57], v[82:83], v[56:57]
	v_cvt_pk_bf16_f32 v54, v60, v61
	v_cvt_pk_bf16_f32 v55, v56, v57
	global_store_dwordx2 v[52:53], v[54:55], off

.LBB0_1409:
	s_and_b64 vcc, exec, s[0:1]
	s_cbranch_vccz .LBB0_1426
	s_and_b64 vcc, exec, s[10:11]
	s_mov_b64 s[0:1], -1
	s_cbranch_vccnz .LBB0_1412
	v_lshlrev_b32_e32 v36, 2, v194
	global_load_dwordx4 v[76:79], v36, s[86:87]
	global_load_dwordx4 v[64:67], v36, s[66:67]
	global_load_dwordx4 v[80:83], v36, s[56:57]
	v_mul_f32_e64 v37, |v60|, s69
	v_mul_f32_e64 v41, |v61|, s69
	v_exp_f32_e32 v37, v37
	v_exp_f32_e32 v54, v41
	v_mul_f32_e64 v45, |v62|, s69
	v_max_f32_e32 v50, v62, v62
	v_cmp_lt_f32_e32 vcc, 0, v61
	v_max_f32_e32 v44, v61, v61
	v_mul_f32_e64 v51, |v63|, s69
	v_exp_f32_e32 v84, v45
	v_min_f32_e32 v36, 0, v50
	v_add_f32_e32 v50, 1.0, v37
	v_cndmask_b32_e32 v45, 1.0, v54, vcc
	v_cmp_lt_f32_e32 vcc, 0, v60
	v_min_f32_e32 v41, 0, v44
	v_exp_f32_e32 v85, v51
	v_add_f32_e32 v51, 1.0, v54
	v_cndmask_b32_e32 v44, 1.0, v37, vcc
	v_rcp_f32_e32 v55, v51
	v_mov_b32_e32 v37, v50
	v_log_f32_e32 v37, v37
	v_log_f32_e32 v51, v51
	v_rcp_f32_e32 v54, v50
	v_mul_f32_e32 v94, 0x3f317217, v37
	v_mul_f32_e32 v95, 0x3f317217, v51
	v_fma_f32 v94, v37, s75, -v94
	v_fma_f32 v95, v51, s75, -v95
	v_fmac_f32_e32 v94, 0x3377d1cf, v37
	v_fmac_f32_e32 v95, 0x3377d1cf, v51
	v_fmac_f32_e32 v94, 0x3f317217, v37
	v_add_f32_e32 v86, 1.0, v84
	v_fmac_f32_e32 v95, 0x3f317217, v51
	v_mov_b32_e32 v37, v94
	v_max_f32_e32 v40, v60, v60
	v_mov_b32_e32 v51, v95
	v_min_f32_e32 v40, 0, v40
	v_mov_b32_e32 v50, v37
	v_mov_b32_e32 v59, v86
	v_pk_add_f32 v[40:41], v[40:41], v[50:51] neg_lo:[0,1] neg_hi:[0,1]
	v_log_f32_e32 v59, v59
	v_add_f32_e32 v87, 1.0, v85
	s_mov_b64 s[0:1], 0
	v_mul_f32_e32 v96, 0x3f317217, v59
	v_fma_f32 v96, v59, s75, -v96
	v_fmac_f32_e32 v96, 0x3377d1cf, v59
	v_fmac_f32_e32 v96, 0x3f317217, v59
	s_waitcnt vmcnt(0)
	v_pk_add_f32 v[40:41], v[40:41], v[76:77]
	s_nop 0
	v_pk_add_f32 v[50:51], v[40:41], v[64:65] neg_lo:[0,1] neg_hi:[0,1]
	v_max_f32_e32 v37, v64, v64
	v_mul_f32_e64 v64, |v50|, s69
	v_max_f32_e32 v58, v65, v65
	v_mul_f32_e64 v65, |v51|, s69
	v_exp_f32_e32 v64, v64
	v_exp_f32_e32 v65, v65
	v_max_f32_e32 v40, v40, v37
	v_mov_b32_e32 v59, v96
	v_add_f32_e32 v37, 1.0, v64
	v_max_f32_e32 v41, v41, v58
	v_add_f32_e32 v58, 1.0, v65
	s_nop 0
	v_log_f32_e32 v37, v37
	v_log_f32_e32 v58, v58
	v_mul_f32_e32 v76, 0x3f317217, v37
	v_mul_f32_e32 v77, 0x3f317217, v58
	v_fma_f32 v76, v37, s75, -v76
	v_fma_f32 v77, v58, s75, -v77
	v_fmac_f32_e32 v76, 0x3377d1cf, v37
	v_fmac_f32_e32 v77, 0x3377d1cf, v58
	v_fmac_f32_e32 v76, 0x3f317217, v37
	v_fmac_f32_e32 v77, 0x3f317217, v58
	s_nop 0
	v_mov_b32_e32 v37, v76
	v_mov_b32_e32 v76, v37
	s_nop 0
	v_mov_b32_e32 v58, v77
	v_mov_b32_e32 v77, v58
	v_mov_b32_e32 v58, v59
	v_mov_b32_e32 v37, v87
	v_log_f32_e32 v64, v37
	v_max_f32_e32 v37, v63, v63
	v_min_f32_e32 v37, 0, v37
	v_mul_f32_e32 v59, 0x3f317217, v64
	v_fma_f32 v59, v64, s75, -v59
	v_fmac_f32_e32 v59, 0x3377d1cf, v64
	v_fmac_f32_e32 v59, 0x3f317217, v64
	s_nop 1
	v_pk_add_f32 v[36:37], v[36:37], v[58:59] neg_lo:[0,1] neg_hi:[0,1]
	s_nop 0
	v_pk_add_f32 v[58:59], v[36:37], v[78:79]
	s_nop 0
	v_pk_add_f32 v[64:65], v[58:59], v[66:67] neg_lo:[0,1] neg_hi:[0,1]
	s_nop 0
	v_mul_f32_e64 v36, |v64|, s69
	v_exp_f32_e32 v78, v36
	v_pk_mul_f32 v[36:37], v[44:45], v[80:81]
	v_rcp_f32_e32 v44, v86
	v_pk_mul_f32 v[36:37], v[54:55], v[36:37]
	v_add_f32_e32 v45, 1.0, v78
	s_nop 1
	v_log_f32_e32 v55, v45
	v_max_f32_e32 v54, v66, v66
	v_mul_f32_e64 v66, |v65|, s69
	v_exp_f32_e32 v66, v66
	v_max_f32_e32 v54, v58, v54
	v_mul_f32_e32 v58, 0x3f317217, v55
	v_fma_f32 v58, v55, s75, -v58
	v_fmac_f32_e32 v58, 0x3377d1cf, v55
	v_fmac_f32_e32 v58, 0x3f317217, v55
	v_add_f32_e32 v66, 1.0, v66
	v_rcp_f32_e32 v45, v87
	v_mov_b32_e32 v55, v58
	v_mov_b32_e32 v58, v55
	s_nop 0
	v_log_f32_e32 v66, v66
	v_max_f32_e32 v55, v59, v67
	v_mul_f32_e32 v59, 0x3f317217, v66
	v_fma_f32 v59, v66, s75, -v59
	v_fmac_f32_e32 v59, 0x3377d1cf, v66
	v_fmac_f32_e32 v59, 0x3f317217, v66
	s_nop 1
	v_cmp_lt_f32_e64 vcc, |v51|, s49
	s_nop 0
	s_nop 0
	v_cndmask_b32_e32 v51, 0, v77, vcc
	v_cmp_lt_f32_e64 vcc, |v50|, s49
	s_nop 1
	v_cndmask_b32_e32 v50, 0, v76, vcc
	v_cmp_lt_f32_e64 vcc, |v65|, s49
	s_nop 1
	v_cndmask_b32_e32 v59, 0, v59, vcc
	v_cmp_lt_f32_e64 vcc, |v64|, s49
	v_pk_add_f32 v[64:65], v[40:41], v[50:51]
	s_nop 0
	v_cndmask_b32_e32 v58, 0, v58, vcc
	v_cmp_lt_f32_e32 vcc, 0, v63
	v_pk_add_f32 v[66:67], v[54:55], v[58:59]
	s_nop 0
	v_cndmask_b32_e32 v41, 1.0, v85, vcc
	v_cmp_lt_f32_e32 vcc, 0, v62
	s_nop 1
	v_cndmask_b32_e32 v40, 1.0, v84, vcc
	v_pk_mul_f32 v[40:41], v[40:41], v[82:83]
	s_nop 0
	v_pk_mul_f32 v[40:41], v[44:45], v[40:41]
	v_lshl_add_u64 v[44:45], v[92:93], 2, s[94:95]
	global_store_dwordx4 v[44:45], v[64:67], off

.LBB0_1414:
	s_add_u32 s0, s22, s0
	s_addc_u32 s1, s23, s1
	v_lshl_add_u64 v[44:45], v[92:93], 1, s[0:1]
	v_cvt_pk_bf16_f32 v36, v36, v37
	v_cvt_pk_bf16_f32 v37, v40, v41
	v_mov_b32_e32 v91, v90
	global_store_dwordx2 v[44:45], v[36:37], off
	v_pk_mul_f32 v[36:37], v[46:47], v[90:91]
	s_and_b64 vcc, exec, s[10:11]
	s_mov_b64 s[0:1], -1
	s_cbranch_vccnz .LBB0_1416
	v_lshlrev_b32_e32 v40, 2, v194
	v_lshlrev_b32_e32 v50, 2, v170
	global_load_dwordx4 v[58:61], v40, s[86:87] offset:16
	global_load_dwordx4 v[44:47], v50, s[66:67]
	global_load_dwordx4 v[62:65], v50, s[56:57]
	v_mul_f32_e64 v51, |v56|, s69
	v_max_f32_e32 v54, v56, v56
	v_mul_f32_e64 v55, |v57|, s69
	v_exp_f32_e32 v51, v51
	v_min_f32_e32 v66, 0, v54
	v_exp_f32_e32 v54, v55
	v_mul_f32_e64 v78, |v37|, s69
	v_exp_f32_e32 v81, v78
	v_add_f32_e32 v78, 1.0, v51
	v_cmp_lt_f32_e32 vcc, 0, v57
	v_add_f32_e32 v79, 1.0, v54
	s_nop 0
	v_cndmask_b32_e32 v55, 1.0, v54, vcc
	v_cmp_lt_f32_e32 vcc, 0, v56
	v_max_f32_e32 v77, v36, v36
	s_nop 0
	v_cndmask_b32_e32 v54, 1.0, v51, vcc
	v_mov_b32_e32 v51, v78
	v_min_f32_e32 v50, 0, v77
	v_rcp_f32_e32 v77, v79
	v_log_f32_e32 v51, v51
	v_mul_f32_e64 v76, |v36|, s69
	v_log_f32_e32 v79, v79
	v_exp_f32_e32 v80, v76
	v_mul_f32_e32 v85, 0x3f317217, v51
	v_fma_f32 v85, v51, s75, -v85
	v_mul_f32_e32 v86, 0x3f317217, v79
	v_add_f32_e32 v82, 1.0, v80
	v_fma_f32 v86, v79, s75, -v86
	v_fmac_f32_e32 v85, 0x3377d1cf, v51
	v_rcp_f32_e32 v76, v78
	v_fmac_f32_e32 v86, 0x3377d1cf, v79
	v_fmac_f32_e32 v85, 0x3f317217, v51
	v_fmac_f32_e32 v86, 0x3f317217, v79
	v_mov_b32_e32 v51, v85
	v_max_f32_e32 v67, v57, v57
	v_mov_b32_e32 v83, v82
	v_mov_b32_e32 v79, v86
	v_min_f32_e32 v67, 0, v67
	v_mov_b32_e32 v78, v51
	v_pk_add_f32 v[66:67], v[66:67], v[78:79] neg_lo:[0,1] neg_hi:[0,1]
	v_log_f32_e32 v83, v83
	v_or_b32_e32 v40, v88, v170
	v_mov_b32_e32 v41, v89
	v_lshl_add_u64 v[40:41], v[40:41], 2, s[94:95]
	v_mul_f32_e32 v87, 0x3f317217, v83
	v_fma_f32 v87, v83, s75, -v87
	v_fmac_f32_e32 v87, 0x3377d1cf, v83
	v_fmac_f32_e32 v87, 0x3f317217, v83
	s_mov_b64 s[0:1], 0
	s_waitcnt vmcnt(0)
	v_pk_add_f32 v[58:59], v[66:67], v[58:59]
	s_nop 0
	v_pk_add_f32 v[66:67], v[58:59], v[44:45] neg_lo:[0,1] neg_hi:[0,1]
	v_max_f32_e32 v51, v44, v44
	v_mul_f32_e64 v44, |v66|, s69
	v_max_f32_e32 v78, v45, v45
	v_mul_f32_e64 v45, |v67|, s69
	v_exp_f32_e32 v44, v44
	v_exp_f32_e32 v45, v45
	v_mov_b32_e32 v83, v87
	v_max_f32_e32 v58, v58, v51
	v_add_f32_e32 v44, 1.0, v44
	v_add_f32_e32 v45, 1.0, v45
	v_max_f32_e32 v59, v59, v78
	v_log_f32_e32 v44, v44
	v_log_f32_e32 v45, v45
	v_mul_f32_e32 v79, 0x3f317217, v44
	v_mul_f32_e32 v84, 0x3f317217, v45
	v_fma_f32 v79, v44, s75, -v79
	v_fma_f32 v84, v45, s75, -v84
	v_fmac_f32_e32 v79, 0x3377d1cf, v44
	v_fmac_f32_e32 v84, 0x3377d1cf, v45
	v_fmac_f32_e32 v79, 0x3f317217, v44
	v_fmac_f32_e32 v84, 0x3f317217, v45
	s_nop 0
	v_mov_b32_e32 v44, v79
	v_mov_b32_e32 v79, v44
	v_mov_b32_e32 v45, v84
	v_add_f32_e32 v84, 1.0, v81
	v_mov_b32_e32 v78, v45
	v_mov_b32_e32 v44, v83
	v_mov_b32_e32 v45, v84
	v_log_f32_e32 v45, v45
	v_max_f32_e32 v51, v37, v37
	v_min_f32_e32 v51, 0, v51
	v_mul_f32_e32 v83, 0x3f317217, v45
	v_fma_f32 v83, v45, s75, -v83
	v_fmac_f32_e32 v83, 0x3377d1cf, v45
	v_fmac_f32_e32 v83, 0x3f317217, v45
	s_nop 1
	v_mov_b32_e32 v45, v83
	v_pk_add_f32 v[44:45], v[50:51], v[44:45] neg_lo:[0,1] neg_hi:[0,1]
	s_nop 0
	v_pk_add_f32 v[50:51], v[44:45], v[60:61]
	s_nop 0
	v_pk_add_f32 v[60:61], v[50:51], v[46:47] neg_lo:[0,1] neg_hi:[0,1]
	v_mul_f32_e64 v44, |v60|, s69
	v_exp_f32_e32 v83, v44
	v_pk_mul_f32 v[44:45], v[54:55], v[62:63]
	v_mul_f32_e64 v63, |v61|, s69
	v_exp_f32_e32 v63, v63
	v_add_f32_e32 v55, 1.0, v83
	v_max_f32_e32 v46, v50, v46
	v_add_f32_e32 v63, 1.0, v63
	v_log_f32_e32 v62, v55
	v_pk_mul_f32 v[44:45], v[76:77], v[44:45]
	v_max_f32_e32 v47, v51, v47
	v_mul_f32_e32 v50, 0x3f317217, v62
	v_fma_f32 v50, v62, s75, -v50
	v_fmac_f32_e32 v50, 0x3377d1cf, v62
	v_fmac_f32_e32 v50, 0x3f317217, v62
	v_rcp_f32_e32 v54, v82
	v_rcp_f32_e32 v55, v84
	v_mov_b32_e32 v62, v50
	s_nop 0
	v_log_f32_e32 v63, v63
	v_cmp_lt_f32_e64 vcc, |v67|, s49
	v_mul_f32_e32 v50, 0x3f317217, v63
	v_fma_f32 v50, v63, s75, -v50
	v_fmac_f32_e32 v50, 0x3377d1cf, v63
	v_fmac_f32_e32 v50, 0x3f317217, v63
	s_nop 1
	v_mov_b32_e32 v63, v50
	v_cndmask_b32_e32 v51, 0, v78, vcc
	v_cmp_lt_f32_e64 vcc, |v66|, s49
	s_nop 1
	v_cndmask_b32_e32 v50, 0, v79, vcc
	v_cmp_lt_f32_e64 vcc, |v61|, s49
	v_pk_add_f32 v[58:59], v[58:59], v[50:51]
	s_nop 0
	v_cndmask_b32_e32 v61, 0, v63, vcc
	v_cmp_lt_f32_e64 vcc, |v60|, s49
	s_nop 1
	v_cndmask_b32_e32 v60, 0, v62, vcc
	v_cmp_lt_f32_e32 vcc, 0, v37
	v_pk_add_f32 v[60:61], v[46:47], v[60:61]
	global_store_dwordx4 v[40:41], v[58:61], off
	v_cndmask_b32_e32 v47, 1.0, v81, vcc
	v_cmp_lt_f32_e32 vcc, 0, v36
	s_nop 1
	v_cndmask_b32_e32 v46, 1.0, v80, vcc
	v_pk_mul_f32 v[46:47], v[46:47], v[64:65]
	s_nop 0
	v_pk_mul_f32 v[46:47], v[54:55], v[46:47]

.LBB0_1418:
	s_add_u32 s0, s22, s0
	s_addc_u32 s1, s23, s1
	v_lshl_add_u64 v[36:37], v[88:89], 0, v[194:195]
	v_mov_b32_e32 v91, v90
	v_lshl_add_u64 v[40:41], v[36:37], 1, s[0:1]
	v_cvt_pk_bf16_f32 v44, v44, v45
	v_cvt_pk_bf16_f32 v45, v46, v47
	v_pk_mul_f32 v[50:51], v[42:43], v[90:91]
	s_and_b64 vcc, exec, s[10:11]
	s_mov_b64 s[0:1], -1
	global_store_dwordx2 v[40:41], v[44:45], off offset:8
	s_cbranch_vccnz .LBB0_1420
	v_lshlrev_b32_e32 v40, 2, v194
	v_lshlrev_b32_e32 v54, 2, v169
	global_load_dwordx4 v[44:47], v40, s[86:87] offset:32
	s_nop 0
	global_load_dwordx4 v[40:43], v54, s[66:67]
	v_mul_f32_e64 v60, |v52|, s69
	global_load_dwordx4 v[54:57], v54, s[56:57]
	v_max_f32_e32 v61, v52, v52
	v_mul_f32_e64 v62, |v53|, s69
	v_exp_f32_e32 v77, v60
	v_min_f32_e32 v64, 0, v61
	v_exp_f32_e32 v61, v62
	v_mul_f32_e64 v76, |v51|, s69
	v_exp_f32_e32 v79, v76
	v_add_f32_e32 v76, 1.0, v77
	v_max_f32_e32 v63, v53, v53
	v_add_f32_e32 v80, 1.0, v61
	v_cmp_lt_f32_e32 vcc, 0, v53
	v_min_f32_e32 v65, 0, v63
	s_nop 0
	v_cndmask_b32_e32 v63, 1.0, v61, vcc
	v_cmp_lt_f32_e32 vcc, 0, v52
	s_nop 1
	v_cndmask_b32_e32 v62, 1.0, v77, vcc
	v_mov_b32_e32 v61, v76
	v_mov_b32_e32 v77, v80
	v_log_f32_e32 v61, v61
	v_mul_f32_e64 v66, |v50|, s69
	v_log_f32_e32 v77, v77
	v_exp_f32_e32 v78, v66
	v_mul_f32_e32 v83, 0x3f317217, v61
	v_fma_f32 v83, v61, s75, -v83
	v_mul_f32_e32 v84, 0x3f317217, v77
	v_add_f32_e32 v81, 1.0, v78
	v_fma_f32 v84, v77, s75, -v84
	v_fmac_f32_e32 v83, 0x3377d1cf, v61
	v_rcp_f32_e32 v66, v76
	v_fmac_f32_e32 v84, 0x3377d1cf, v77
	v_fmac_f32_e32 v83, 0x3f317217, v61
	v_max_f32_e32 v67, v50, v50
	v_fmac_f32_e32 v84, 0x3f317217, v77
	v_mov_b32_e32 v61, v83
	v_min_f32_e32 v60, 0, v67
	v_rcp_f32_e32 v67, v80
	v_mov_b32_e32 v80, v81
	v_mov_b32_e32 v77, v84
	v_mov_b32_e32 v76, v61
	v_pk_add_f32 v[64:65], v[64:65], v[76:77] neg_lo:[0,1] neg_hi:[0,1]
	v_log_f32_e32 v80, v80
	v_or_b32_e32 v58, v88, v169
	v_mov_b32_e32 v59, v89
	s_mov_b64 s[0:1], 0
	v_mul_f32_e32 v85, 0x3f317217, v80
	v_fma_f32 v85, v80, s75, -v85
	v_fmac_f32_e32 v85, 0x3377d1cf, v80
	v_fmac_f32_e32 v85, 0x3f317217, v80
	s_waitcnt vmcnt(0)
	v_pk_add_f32 v[44:45], v[64:65], v[44:45]
	s_nop 0
	v_pk_add_f32 v[64:65], v[44:45], v[40:41] neg_lo:[0,1] neg_hi:[0,1]
	v_max_f32_e32 v61, v40, v40
	v_mul_f32_e64 v40, |v64|, s69
	v_max_f32_e32 v76, v41, v41
	v_mul_f32_e64 v41, |v65|, s69
	v_exp_f32_e32 v40, v40
	v_exp_f32_e32 v41, v41
	v_mov_b32_e32 v80, v85
	v_max_f32_e32 v44, v44, v61
	v_add_f32_e32 v40, 1.0, v40
	v_add_f32_e32 v41, 1.0, v41
	v_max_f32_e32 v45, v45, v76
	v_log_f32_e32 v40, v40
	v_log_f32_e32 v41, v41
	v_mul_f32_e32 v77, 0x3f317217, v40
	v_mul_f32_e32 v82, 0x3f317217, v41
	v_fma_f32 v77, v40, s75, -v77
	v_fma_f32 v82, v41, s75, -v82
	v_fmac_f32_e32 v77, 0x3377d1cf, v40
	v_fmac_f32_e32 v82, 0x3377d1cf, v41
	v_fmac_f32_e32 v77, 0x3f317217, v40
	v_fmac_f32_e32 v82, 0x3f317217, v41
	s_nop 0
	v_mov_b32_e32 v40, v77
	v_mov_b32_e32 v77, v40
	v_mov_b32_e32 v41, v82
	v_add_f32_e32 v82, 1.0, v79
	v_mov_b32_e32 v76, v41
	v_mov_b32_e32 v40, v80
	v_mov_b32_e32 v41, v82
	v_log_f32_e32 v41, v41
	v_max_f32_e32 v61, v51, v51
	v_min_f32_e32 v61, 0, v61
	v_mul_f32_e32 v80, 0x3f317217, v41
	v_fma_f32 v80, v41, s75, -v80
	v_fmac_f32_e32 v80, 0x3377d1cf, v41
	v_fmac_f32_e32 v80, 0x3f317217, v41
	s_nop 1
	v_mov_b32_e32 v41, v80
	v_pk_add_f32 v[40:41], v[60:61], v[40:41] neg_lo:[0,1] neg_hi:[0,1]
	s_nop 0
	v_pk_add_f32 v[46:47], v[40:41], v[46:47]
	s_nop 0
	v_pk_add_f32 v[60:61], v[46:47], v[42:43] neg_lo:[0,1] neg_hi:[0,1]
	v_mul_f32_e64 v40, |v60|, s69
	v_exp_f32_e32 v80, v40
	v_pk_mul_f32 v[40:41], v[62:63], v[54:55]
	v_mul_f32_e64 v63, |v61|, s69
	v_exp_f32_e32 v63, v63
	v_add_f32_e32 v55, 1.0, v80
	v_max_f32_e32 v42, v46, v42
	v_add_f32_e32 v63, 1.0, v63
	v_log_f32_e32 v62, v55
	v_pk_mul_f32 v[40:41], v[66:67], v[40:41]
	v_max_f32_e32 v43, v47, v43
	v_mul_f32_e32 v46, 0x3f317217, v62
	v_fma_f32 v46, v62, s75, -v46
	v_fmac_f32_e32 v46, 0x3377d1cf, v62
	v_fmac_f32_e32 v46, 0x3f317217, v62
	v_rcp_f32_e32 v54, v81
	v_rcp_f32_e32 v55, v82
	s_nop 0
	v_log_f32_e32 v63, v63
	v_cmp_lt_f32_e64 vcc, |v65|, s49
	v_mul_f32_e32 v47, 0x3f317217, v63
	v_fma_f32 v47, v63, s75, -v47
	v_fmac_f32_e32 v47, 0x3377d1cf, v63
	v_fmac_f32_e32 v47, 0x3f317217, v63
	s_nop 1
	v_cndmask_b32_e32 v63, 0, v76, vcc
	v_cmp_lt_f32_e64 vcc, |v64|, s49
	s_nop 0
	s_nop 0
	v_cndmask_b32_e32 v62, 0, v77, vcc
	v_cmp_lt_f32_e64 vcc, |v61|, s49
	v_pk_add_f32 v[44:45], v[44:45], v[62:63]
	s_nop 0
	v_cndmask_b32_e32 v47, 0, v47, vcc
	v_cmp_lt_f32_e64 vcc, |v60|, s49
	s_nop 1
	v_cndmask_b32_e32 v46, 0, v46, vcc
	v_cmp_lt_f32_e32 vcc, 0, v51
	v_pk_add_f32 v[46:47], v[42:43], v[46:47]
	s_nop 0
	v_cndmask_b32_e32 v43, 1.0, v79, vcc
	v_cmp_lt_f32_e32 vcc, 0, v50
	s_nop 1
	v_cndmask_b32_e32 v42, 1.0, v78, vcc
	v_pk_mul_f32 v[42:43], v[42:43], v[56:57]
	s_nop 0
	v_pk_mul_f32 v[42:43], v[54:55], v[42:43]
	v_lshl_add_u64 v[54:55], v[58:59], 2, s[94:95]
	global_store_dwordx4 v[54:55], v[44:47], off

.LBB0_1422:
	s_add_u32 s0, s22, s0
	s_addc_u32 s1, s23, s1
	v_mov_b32_e32 v91, v90
	v_lshl_add_u64 v[36:37], v[36:37], 1, s[0:1]
	v_cvt_pk_bf16_f32 v40, v40, v41
	v_cvt_pk_bf16_f32 v41, v42, v43
	v_or_b32_e32 v88, v88, v168
	v_pk_mul_f32 v[50:51], v[38:39], v[90:91]
	s_and_b64 vcc, exec, s[10:11]
	s_mov_b64 s[0:1], -1
	global_store_dwordx2 v[36:37], v[40:41], off offset:16
	s_cbranch_vccnz .LBB0_1424
	v_lshlrev_b32_e32 v36, 2, v194
	v_lshlrev_b32_e32 v44, 2, v168
	global_load_dwordx4 v[40:43], v36, s[86:87] offset:48
	s_nop 0
	global_load_dwordx4 v[36:39], v44, s[66:67]
	v_mul_f32_e64 v52, |v48|, s69
	global_load_dwordx4 v[44:47], v44, s[56:57]
	v_max_f32_e32 v53, v48, v48
	v_mul_f32_e64 v54, |v49|, s69
	v_exp_f32_e32 v62, v52
	v_min_f32_e32 v60, 0, v53
	v_exp_f32_e32 v53, v54
	v_max_f32_e32 v55, v49, v49
	v_cmp_lt_f32_e32 vcc, 0, v49
	v_min_f32_e32 v61, 0, v55
	v_add_f32_e32 v63, 1.0, v62
	v_cndmask_b32_e32 v55, 1.0, v53, vcc
	v_cmp_lt_f32_e32 vcc, 0, v48
	v_add_f32_e32 v64, 1.0, v53
	s_nop 0
	v_cndmask_b32_e32 v54, 1.0, v62, vcc
	v_mov_b32_e32 v62, v64
	v_mov_b32_e32 v53, v63
	v_log_f32_e32 v53, v53
	v_log_f32_e32 v62, v62
	v_mul_f32_e64 v56, |v50|, s69
	v_exp_f32_e32 v58, v56
	v_mul_f32_e32 v77, 0x3f317217, v53
	v_mul_f32_e32 v78, 0x3f317217, v62
	v_fma_f32 v77, v53, s75, -v77
	v_fma_f32 v78, v62, s75, -v78
	v_fmac_f32_e32 v77, 0x3377d1cf, v53
	v_rcp_f32_e32 v56, v63
	v_fmac_f32_e32 v78, 0x3377d1cf, v62
	v_fmac_f32_e32 v77, 0x3f317217, v53
	v_max_f32_e32 v57, v50, v50
	v_add_f32_e32 v65, 1.0, v58
	v_fmac_f32_e32 v78, 0x3f317217, v62
	v_mov_b32_e32 v53, v77
	v_min_f32_e32 v52, 0, v57
	v_rcp_f32_e32 v57, v64
	v_mov_b32_e32 v77, v78
	v_mov_b32_e32 v62, v53
	v_mov_b32_e32 v63, v77
	v_mov_b32_e32 v67, v65
	v_pk_add_f32 v[60:61], v[60:61], v[62:63] neg_lo:[0,1] neg_hi:[0,1]
	v_log_f32_e32 v67, v67
	v_mul_f32_e64 v59, |v51|, s69
	v_exp_f32_e32 v59, v59
	v_mul_f32_e32 v79, 0x3f317217, v67
	v_fma_f32 v79, v67, s75, -v79
	v_fmac_f32_e32 v79, 0x3377d1cf, v67
	v_fmac_f32_e32 v79, 0x3f317217, v67
	v_add_f32_e32 v66, 1.0, v59
	s_mov_b64 s[0:1], 0
	v_mov_b32_e32 v67, v79
	s_waitcnt vmcnt(0)
	v_pk_add_f32 v[60:61], v[60:61], v[40:41]
	s_nop 0
	v_pk_add_f32 v[40:41], v[60:61], v[36:37] neg_lo:[0,1] neg_hi:[0,1]
	v_max_f32_e32 v53, v36, v36
	v_mul_f32_e64 v36, |v40|, s69
	v_max_f32_e32 v62, v37, v37
	v_mul_f32_e64 v37, |v41|, s69
	v_exp_f32_e32 v63, v36
	v_exp_f32_e32 v64, v37
	v_max_f32_e32 v36, v60, v53
	v_max_f32_e32 v37, v61, v62
	v_add_f32_e32 v53, 1.0, v63
	v_add_f32_e32 v60, 1.0, v64
	v_pk_mul_f32 v[44:45], v[54:55], v[44:45]
	v_log_f32_e32 v53, v53
	v_log_f32_e32 v60, v60
	v_mul_f32_e32 v63, 0x3f317217, v53
	v_mul_f32_e32 v64, 0x3f317217, v60
	v_fma_f32 v63, v53, s75, -v63
	v_fma_f32 v64, v60, s75, -v64
	v_fmac_f32_e32 v63, 0x3377d1cf, v53
	v_fmac_f32_e32 v64, 0x3377d1cf, v60
	v_fmac_f32_e32 v63, 0x3f317217, v53
	v_fmac_f32_e32 v64, 0x3f317217, v60
	v_pk_mul_f32 v[44:45], v[56:57], v[44:45]
	v_mov_b32_e32 v53, v63
	v_mov_b32_e32 v63, v53
	v_rcp_f32_e32 v54, v65
	v_mov_b32_e32 v60, v64
	v_mov_b32_e32 v62, v60
	v_mov_b32_e32 v60, v67
	v_mov_b32_e32 v53, v66
	v_log_f32_e32 v61, v53
	v_max_f32_e32 v53, v51, v51
	v_min_f32_e32 v53, 0, v53
	v_mul_f32_e32 v64, 0x3f317217, v61
	v_fma_f32 v64, v61, s75, -v64
	v_fmac_f32_e32 v64, 0x3377d1cf, v61
	v_fmac_f32_e32 v64, 0x3f317217, v61
	s_nop 1
	v_mov_b32_e32 v61, v64
	v_pk_add_f32 v[52:53], v[52:53], v[60:61] neg_lo:[0,1] neg_hi:[0,1]
	s_nop 0
	v_pk_add_f32 v[42:43], v[52:53], v[42:43]
	s_nop 0
	v_pk_add_f32 v[52:53], v[42:43], v[38:39] neg_lo:[0,1] neg_hi:[0,1]
	v_mul_f32_e64 v60, |v52|, s69
	v_exp_f32_e32 v60, v60
	v_mul_f32_e64 v57, |v53|, s69
	v_exp_f32_e32 v57, v57
	v_max_f32_e32 v38, v42, v38
	v_add_f32_e32 v55, 1.0, v60
	v_add_f32_e32 v57, 1.0, v57
	s_nop 0
	v_log_f32_e32 v56, v55
	v_max_f32_e32 v39, v43, v39
	v_rcp_f32_e32 v55, v66
	v_mul_f32_e32 v42, 0x3f317217, v56
	v_fma_f32 v42, v56, s75, -v42
	v_fmac_f32_e32 v42, 0x3377d1cf, v56
	v_fmac_f32_e32 v42, 0x3f317217, v56
	s_nop 1
	s_nop 0
	v_log_f32_e32 v57, v57
	v_cmp_lt_f32_e64 vcc, |v41|, s49
	v_mul_f32_e32 v43, 0x3f317217, v57
	v_fma_f32 v43, v57, s75, -v43
	v_fmac_f32_e32 v43, 0x3377d1cf, v57
	v_fmac_f32_e32 v43, 0x3f317217, v57
	v_cndmask_b32_e32 v41, 0, v62, vcc
	v_cmp_lt_f32_e64 vcc, |v40|, s49
	s_nop 1
	v_cndmask_b32_e32 v40, 0, v63, vcc
	v_cmp_lt_f32_e64 vcc, |v53|, s49
	v_pk_add_f32 v[36:37], v[36:37], v[40:41]
	s_nop 0
	v_cndmask_b32_e32 v43, 0, v43, vcc
	v_cmp_lt_f32_e64 vcc, |v52|, s49
	s_nop 1
	v_cndmask_b32_e32 v42, 0, v42, vcc
	v_cmp_lt_f32_e32 vcc, 0, v51
	v_pk_add_f32 v[38:39], v[38:39], v[42:43]
	v_lshl_add_u64 v[42:43], v[88:89], 2, s[94:95]
	v_cndmask_b32_e32 v41, 1.0, v59, vcc
	v_cmp_lt_f32_e32 vcc, 0, v50
	global_store_dwordx4 v[42:43], v[36:39], off
	s_nop 0
	v_cndmask_b32_e32 v40, 1.0, v58, vcc
	v_pk_mul_f32 v[40:41], v[40:41], v[46:47]
	v_lshl_add_u64 v[36:37], v[88:89], 1, s[84:85]
	v_pk_mul_f32 v[40:41], v[54:55], v[40:41]
	v_cvt_pk_bf16_f32 v38, v44, v45
	v_cvt_pk_bf16_f32 v39, v40, v41
	global_store_dwordx2 v[36:37], v[38:39], off

.LBB0_1445:
	s_and_b64 vcc, exec, s[0:1]
	s_cbranch_vccz .LBB0_1462
	s_and_b64 vcc, exec, s[10:11]
	s_mov_b64 s[0:1], -1
	s_cbranch_vccnz .LBB0_1448
	v_lshlrev_b32_e32 v20, 2, v194
	global_load_dwordx4 v[52:55], v20, s[86:87]
	global_load_dwordx4 v[48:51], v20, s[66:67]
	global_load_dwordx4 v[56:59], v20, s[56:57]
	v_mul_f32_e64 v21, |v44|, s69
	v_max_f32_e32 v24, v44, v44
	v_mul_f32_e64 v25, |v45|, s69
	v_exp_f32_e32 v38, v21
	v_min_f32_e32 v20, 0, v24
	v_exp_f32_e32 v24, v25
	v_mul_f32_e64 v35, |v47|, s69
	v_cmp_lt_f32_e32 vcc, 0, v45
	v_max_f32_e32 v28, v45, v45
	v_mul_f32_e64 v29, |v46|, s69
	v_max_f32_e32 v34, v46, v46
	v_exp_f32_e32 v43, v35
	v_add_f32_e32 v25, 1.0, v38
	v_cndmask_b32_e32 v35, 1.0, v24, vcc
	v_cmp_lt_f32_e32 vcc, 0, v44
	v_min_f32_e32 v21, 0, v28
	v_exp_f32_e32 v42, v29
	v_min_f32_e32 v28, 0, v34
	v_add_f32_e32 v29, 1.0, v24
	v_cndmask_b32_e32 v34, 1.0, v38, vcc
	v_rcp_f32_e32 v39, v29
	v_mov_b32_e32 v24, v25
	v_log_f32_e32 v24, v24
	v_log_f32_e32 v29, v29
	v_rcp_f32_e32 v38, v25
	v_mul_f32_e32 v74, 0x3f317217, v24
	v_mul_f32_e32 v75, 0x3f317217, v29
	v_fma_f32 v74, v24, s75, -v74
	v_fma_f32 v75, v29, s75, -v75
	v_fmac_f32_e32 v74, 0x3377d1cf, v24
	v_fmac_f32_e32 v75, 0x3377d1cf, v29
	v_fmac_f32_e32 v74, 0x3f317217, v24
	v_add_f32_e32 v60, 1.0, v42
	v_fmac_f32_e32 v75, 0x3f317217, v29
	v_mov_b32_e32 v24, v74
	v_mov_b32_e32 v29, v75
	v_mov_b32_e32 v25, v29
	v_mov_b32_e32 v63, v60
	v_pk_add_f32 v[20:21], v[20:21], v[24:25] neg_lo:[0,1] neg_hi:[0,1]
	v_log_f32_e32 v63, v63
	v_add_f32_e32 v61, 1.0, v43
	s_mov_b64 s[0:1], 0
	v_mul_f32_e32 v76, 0x3f317217, v63
	v_fma_f32 v76, v63, s75, -v76
	v_fmac_f32_e32 v76, 0x3377d1cf, v63
	v_fmac_f32_e32 v76, 0x3f317217, v63
	s_waitcnt vmcnt(0)
	v_pk_add_f32 v[20:21], v[20:21], v[52:53]
	s_nop 0
	v_pk_add_f32 v[24:25], v[20:21], v[48:49] neg_lo:[0,1] neg_hi:[0,1]
	v_max_f32_e32 v29, v48, v48
	v_mul_f32_e64 v48, |v24|, s69
	v_max_f32_e32 v52, v49, v49
	v_mul_f32_e64 v49, |v25|, s69
	v_exp_f32_e32 v48, v48
	v_exp_f32_e32 v49, v49
	v_max_f32_e32 v20, v20, v29
	v_mov_b32_e32 v63, v76
	v_add_f32_e32 v29, 1.0, v48
	v_add_f32_e32 v48, 1.0, v49
	v_max_f32_e32 v21, v21, v52
	v_log_f32_e32 v29, v29
	v_log_f32_e32 v48, v48
	v_mul_f32_e32 v53, 0x3f317217, v29
	v_mul_f32_e32 v62, 0x3f317217, v48
	v_fma_f32 v53, v29, s75, -v53
	v_fma_f32 v62, v48, s75, -v62
	v_fmac_f32_e32 v53, 0x3377d1cf, v29
	v_fmac_f32_e32 v62, 0x3377d1cf, v48
	v_fmac_f32_e32 v53, 0x3f317217, v29
	v_fmac_f32_e32 v62, 0x3f317217, v48
	s_nop 0
	v_mov_b32_e32 v29, v53
	s_nop 1
	v_mov_b32_e32 v48, v62
	v_mov_b32_e32 v62, v29
	v_mov_b32_e32 v74, v48
	v_mov_b32_e32 v29, v61
	v_log_f32_e32 v49, v29
	v_max_f32_e32 v29, v47, v47
	v_mov_b32_e32 v48, v63
	v_min_f32_e32 v29, 0, v29
	v_mul_f32_e32 v52, 0x3f317217, v49
	v_fma_f32 v52, v49, s75, -v52
	v_fmac_f32_e32 v52, 0x3377d1cf, v49
	v_fmac_f32_e32 v52, 0x3f317217, v49
	s_nop 1
	v_mov_b32_e32 v49, v52
	v_pk_add_f32 v[28:29], v[28:29], v[48:49] neg_lo:[0,1] neg_hi:[0,1]
	s_nop 0
	v_pk_add_f32 v[48:49], v[28:29], v[54:55]
	s_nop 0
	v_pk_add_f32 v[52:53], v[48:49], v[50:51] neg_lo:[0,1] neg_hi:[0,1]
	s_nop 0
	v_mul_f32_e64 v28, |v52|, s69
	v_exp_f32_e32 v54, v28
	v_pk_mul_f32 v[28:29], v[34:35], v[56:57]
	v_rcp_f32_e32 v34, v60
	v_pk_mul_f32 v[28:29], v[38:39], v[28:29]
	v_add_f32_e32 v35, 1.0, v54
	s_nop 1
	v_log_f32_e32 v39, v35
	v_max_f32_e32 v38, v50, v50
	v_mul_f32_e64 v50, |v53|, s69
	v_exp_f32_e32 v50, v50
	v_max_f32_e32 v38, v48, v38
	v_mul_f32_e32 v48, 0x3f317217, v39
	v_fma_f32 v48, v39, s75, -v48
	v_fmac_f32_e32 v48, 0x3377d1cf, v39
	v_fmac_f32_e32 v48, 0x3f317217, v39
	v_add_f32_e32 v50, 1.0, v50
	v_rcp_f32_e32 v35, v61
	v_mov_b32_e32 v39, v48
	v_mov_b32_e32 v48, v39
	s_nop 0
	v_log_f32_e32 v50, v50
	v_max_f32_e32 v39, v49, v51
	v_mul_f32_e32 v49, 0x3f317217, v50
	v_fma_f32 v49, v50, s75, -v49
	v_fmac_f32_e32 v49, 0x3377d1cf, v50
	v_fmac_f32_e32 v49, 0x3f317217, v50
	s_nop 1
	v_cmp_lt_f32_e64 vcc, |v25|, s49
	s_nop 0
	s_nop 0
	v_cndmask_b32_e32 v25, 0, v74, vcc
	v_cmp_lt_f32_e64 vcc, |v24|, s49
	s_nop 1
	v_cndmask_b32_e32 v24, 0, v62, vcc
	v_cmp_lt_f32_e64 vcc, |v53|, s49
	s_nop 1
	v_cndmask_b32_e32 v49, 0, v49, vcc
	v_cmp_lt_f32_e64 vcc, |v52|, s49
	s_nop 1
	v_cndmask_b32_e32 v48, 0, v48, vcc
	v_cmp_lt_f32_e32 vcc, 0, v47
	v_pk_add_f32 v[50:51], v[38:39], v[48:49]
	v_pk_add_f32 v[48:49], v[20:21], v[24:25]
	v_cndmask_b32_e32 v21, 1.0, v43, vcc
	v_cmp_lt_f32_e32 vcc, 0, v46
	v_lshl_add_u64 v[24:25], v[72:73], 2, s[94:95]
	global_store_dwordx4 v[24:25], v[48:51], off
	v_cndmask_b32_e32 v20, 1.0, v42, vcc
	v_pk_mul_f32 v[20:21], v[20:21], v[58:59]
	s_nop 0
	v_pk_mul_f32 v[20:21], v[34:35], v[20:21]

.LBB0_1450:
	s_add_u32 s0, s22, s0
	s_addc_u32 s1, s23, s1
	v_mov_b32_e32 v67, v66
	v_lshl_add_u64 v[24:25], v[72:73], 1, s[0:1]
	v_cvt_pk_bf16_f32 v28, v28, v29
	v_cvt_pk_bf16_f32 v29, v20, v21
	v_pk_mul_f32 v[20:21], v[30:31], v[66:67]
	s_and_b64 vcc, exec, s[10:11]
	s_mov_b64 s[0:1], -1
	global_store_dwordx2 v[24:25], v[28:29], off
	s_cbranch_vccnz .LBB0_1452
	v_lshlrev_b32_e32 v24, 2, v194
	v_lshlrev_b32_e32 v34, 2, v170
	global_load_dwordx4 v[42:45], v24, s[86:87] offset:16
	global_load_dwordx4 v[28:31], v34, s[66:67]
	global_load_dwordx4 v[46:49], v34, s[56:57]
	v_mul_f32_e64 v35, |v40|, s69
	v_max_f32_e32 v38, v40, v40
	v_mul_f32_e64 v39, |v41|, s69
	v_exp_f32_e32 v35, v35
	v_min_f32_e32 v50, 0, v38
	v_exp_f32_e32 v38, v39
	v_mul_f32_e64 v54, |v21|, s69
	v_exp_f32_e32 v57, v54
	v_add_f32_e32 v54, 1.0, v35
	v_cmp_lt_f32_e32 vcc, 0, v41
	v_add_f32_e32 v55, 1.0, v38
	s_nop 0
	v_cndmask_b32_e32 v39, 1.0, v38, vcc
	v_cmp_lt_f32_e32 vcc, 0, v40
	v_max_f32_e32 v53, v20, v20
	s_nop 0
	v_cndmask_b32_e32 v38, 1.0, v35, vcc
	v_mov_b32_e32 v35, v54
	v_min_f32_e32 v34, 0, v53
	v_rcp_f32_e32 v53, v55
	v_log_f32_e32 v35, v35
	v_mul_f32_e64 v52, |v20|, s69
	v_log_f32_e32 v55, v55
	v_exp_f32_e32 v56, v52
	v_mul_f32_e32 v61, 0x3f317217, v35
	v_fma_f32 v61, v35, s75, -v61
	v_mul_f32_e32 v62, 0x3f317217, v55
	v_add_f32_e32 v58, 1.0, v56
	v_fma_f32 v62, v55, s75, -v62
	v_fmac_f32_e32 v61, 0x3377d1cf, v35
	v_rcp_f32_e32 v52, v54
	v_fmac_f32_e32 v62, 0x3377d1cf, v55
	v_fmac_f32_e32 v61, 0x3f317217, v35
	v_fmac_f32_e32 v62, 0x3f317217, v55
	v_mov_b32_e32 v35, v61
	v_max_f32_e32 v51, v41, v41
	v_mov_b32_e32 v59, v58
	v_mov_b32_e32 v55, v62
	v_min_f32_e32 v51, 0, v51
	v_mov_b32_e32 v54, v35
	v_pk_add_f32 v[50:51], v[50:51], v[54:55] neg_lo:[0,1] neg_hi:[0,1]
	v_log_f32_e32 v59, v59
	v_or_b32_e32 v24, v64, v170
	v_mov_b32_e32 v25, v65
	v_lshl_add_u64 v[24:25], v[24:25], 2, s[94:95]
	v_mul_f32_e32 v63, 0x3f317217, v59
	v_fma_f32 v63, v59, s75, -v63
	v_fmac_f32_e32 v63, 0x3377d1cf, v59
	v_fmac_f32_e32 v63, 0x3f317217, v59
	s_mov_b64 s[0:1], 0
	s_waitcnt vmcnt(0)
	v_pk_add_f32 v[42:43], v[50:51], v[42:43]
	s_nop 0
	v_pk_add_f32 v[50:51], v[42:43], v[28:29] neg_lo:[0,1] neg_hi:[0,1]
	v_max_f32_e32 v35, v28, v28
	v_mul_f32_e64 v28, |v50|, s69
	v_max_f32_e32 v54, v29, v29
	v_mul_f32_e64 v29, |v51|, s69
	v_exp_f32_e32 v28, v28
	v_exp_f32_e32 v29, v29
	v_mov_b32_e32 v59, v63
	v_max_f32_e32 v42, v42, v35
	v_add_f32_e32 v28, 1.0, v28
	v_add_f32_e32 v29, 1.0, v29
	v_max_f32_e32 v43, v43, v54
	v_log_f32_e32 v28, v28
	v_log_f32_e32 v29, v29
	v_mul_f32_e32 v55, 0x3f317217, v28
	v_mul_f32_e32 v60, 0x3f317217, v29
	v_fma_f32 v55, v28, s75, -v55
	v_fma_f32 v60, v29, s75, -v60
	v_fmac_f32_e32 v55, 0x3377d1cf, v28
	v_fmac_f32_e32 v60, 0x3377d1cf, v29
	v_fmac_f32_e32 v55, 0x3f317217, v28
	v_fmac_f32_e32 v60, 0x3f317217, v29
	s_nop 0
	v_mov_b32_e32 v28, v55
	v_mov_b32_e32 v55, v28
	v_mov_b32_e32 v29, v60
	v_add_f32_e32 v60, 1.0, v57
	v_mov_b32_e32 v54, v29
	v_mov_b32_e32 v28, v59
	v_mov_b32_e32 v29, v60
	v_log_f32_e32 v29, v29
	v_max_f32_e32 v35, v21, v21
	v_min_f32_e32 v35, 0, v35
	v_mul_f32_e32 v59, 0x3f317217, v29
	v_fma_f32 v59, v29, s75, -v59
	v_fmac_f32_e32 v59, 0x3377d1cf, v29
	v_fmac_f32_e32 v59, 0x3f317217, v29
	s_nop 1
	v_mov_b32_e32 v29, v59
	v_pk_add_f32 v[28:29], v[34:35], v[28:29] neg_lo:[0,1] neg_hi:[0,1]
	s_nop 0
	v_pk_add_f32 v[34:35], v[28:29], v[44:45]
	s_nop 0
	v_pk_add_f32 v[44:45], v[34:35], v[30:31] neg_lo:[0,1] neg_hi:[0,1]
	v_mul_f32_e64 v28, |v44|, s69
	v_exp_f32_e32 v59, v28
	v_pk_mul_f32 v[28:29], v[38:39], v[46:47]
	v_mul_f32_e64 v47, |v45|, s69
	v_exp_f32_e32 v47, v47
	v_add_f32_e32 v39, 1.0, v59
	v_max_f32_e32 v30, v34, v30
	v_add_f32_e32 v47, 1.0, v47
	v_log_f32_e32 v46, v39
	v_pk_mul_f32 v[28:29], v[52:53], v[28:29]
	v_max_f32_e32 v31, v35, v31
	v_mul_f32_e32 v34, 0x3f317217, v46
	v_fma_f32 v34, v46, s75, -v34
	v_fmac_f32_e32 v34, 0x3377d1cf, v46
	v_fmac_f32_e32 v34, 0x3f317217, v46
	v_rcp_f32_e32 v38, v58
	v_rcp_f32_e32 v39, v60
	v_mov_b32_e32 v46, v34
	s_nop 0
	v_log_f32_e32 v47, v47
	v_cmp_lt_f32_e64 vcc, |v51|, s49
	v_mul_f32_e32 v34, 0x3f317217, v47
	v_fma_f32 v34, v47, s75, -v34
	v_fmac_f32_e32 v34, 0x3377d1cf, v47
	v_fmac_f32_e32 v34, 0x3f317217, v47
	s_nop 1
	v_mov_b32_e32 v47, v34
	v_cndmask_b32_e32 v35, 0, v54, vcc
	v_cmp_lt_f32_e64 vcc, |v50|, s49
	s_nop 1
	v_cndmask_b32_e32 v34, 0, v55, vcc
	v_cmp_lt_f32_e64 vcc, |v45|, s49
	v_pk_add_f32 v[42:43], v[42:43], v[34:35]
	s_nop 0
	v_cndmask_b32_e32 v45, 0, v47, vcc
	v_cmp_lt_f32_e64 vcc, |v44|, s49
	s_nop 1
	v_cndmask_b32_e32 v44, 0, v46, vcc
	v_cmp_lt_f32_e32 vcc, 0, v21
	v_pk_add_f32 v[44:45], v[30:31], v[44:45]
	global_store_dwordx4 v[24:25], v[42:45], off
	v_cndmask_b32_e32 v31, 1.0, v57, vcc
	v_cmp_lt_f32_e32 vcc, 0, v20
	s_nop 1
	v_cndmask_b32_e32 v30, 1.0, v56, vcc
	v_pk_mul_f32 v[30:31], v[30:31], v[48:49]
	s_nop 0
	v_pk_mul_f32 v[30:31], v[38:39], v[30:31]

.LBB0_1454:
	s_add_u32 s0, s22, s0
	s_addc_u32 s1, s23, s1
	v_lshl_add_u64 v[20:21], v[64:65], 0, v[194:195]
	v_mov_b32_e32 v67, v66
	v_lshl_add_u64 v[24:25], v[20:21], 1, s[0:1]
	v_cvt_pk_bf16_f32 v28, v28, v29
	v_cvt_pk_bf16_f32 v29, v30, v31
	v_pk_mul_f32 v[34:35], v[26:27], v[66:67]
	s_and_b64 vcc, exec, s[10:11]
	s_mov_b64 s[0:1], -1
	global_store_dwordx2 v[24:25], v[28:29], off offset:8
	s_cbranch_vccnz .LBB0_1456
	v_lshlrev_b32_e32 v24, 2, v194
	v_lshlrev_b32_e32 v38, 2, v169
	global_load_dwordx4 v[28:31], v24, s[86:87] offset:32
	s_nop 0
	global_load_dwordx4 v[24:27], v38, s[66:67]
	v_mul_f32_e64 v44, |v36|, s69
	global_load_dwordx4 v[38:41], v38, s[56:57]
	v_max_f32_e32 v45, v36, v36
	v_mul_f32_e64 v46, |v37|, s69
	v_exp_f32_e32 v53, v44
	v_min_f32_e32 v48, 0, v45
	v_exp_f32_e32 v45, v46
	v_mul_f32_e64 v52, |v35|, s69
	v_exp_f32_e32 v55, v52
	v_add_f32_e32 v52, 1.0, v53
	v_max_f32_e32 v47, v37, v37
	v_add_f32_e32 v56, 1.0, v45
	v_cmp_lt_f32_e32 vcc, 0, v37
	v_min_f32_e32 v49, 0, v47
	s_nop 0
	v_cndmask_b32_e32 v47, 1.0, v45, vcc
	v_cmp_lt_f32_e32 vcc, 0, v36
	s_nop 1
	v_cndmask_b32_e32 v46, 1.0, v53, vcc
	v_mov_b32_e32 v45, v52
	v_mov_b32_e32 v53, v56
	v_log_f32_e32 v45, v45
	v_mul_f32_e64 v50, |v34|, s69
	v_log_f32_e32 v53, v53
	v_exp_f32_e32 v54, v50
	v_mul_f32_e32 v59, 0x3f317217, v45
	v_fma_f32 v59, v45, s75, -v59
	v_mul_f32_e32 v60, 0x3f317217, v53
	v_add_f32_e32 v57, 1.0, v54
	v_fma_f32 v60, v53, s75, -v60
	v_fmac_f32_e32 v59, 0x3377d1cf, v45
	v_rcp_f32_e32 v50, v52
	v_fmac_f32_e32 v60, 0x3377d1cf, v53
	v_fmac_f32_e32 v59, 0x3f317217, v45
	v_max_f32_e32 v51, v34, v34
	v_fmac_f32_e32 v60, 0x3f317217, v53
	v_mov_b32_e32 v45, v59
	v_min_f32_e32 v44, 0, v51
	v_rcp_f32_e32 v51, v56
	v_mov_b32_e32 v56, v57
	v_mov_b32_e32 v53, v60
	v_mov_b32_e32 v52, v45
	v_pk_add_f32 v[48:49], v[48:49], v[52:53] neg_lo:[0,1] neg_hi:[0,1]
	v_log_f32_e32 v56, v56
	v_or_b32_e32 v42, v64, v169
	v_mov_b32_e32 v43, v65
	s_mov_b64 s[0:1], 0
	v_mul_f32_e32 v61, 0x3f317217, v56
	v_fma_f32 v61, v56, s75, -v61
	v_fmac_f32_e32 v61, 0x3377d1cf, v56
	v_fmac_f32_e32 v61, 0x3f317217, v56
	s_waitcnt vmcnt(0)
	v_pk_add_f32 v[28:29], v[48:49], v[28:29]
	s_nop 0
	v_pk_add_f32 v[48:49], v[28:29], v[24:25] neg_lo:[0,1] neg_hi:[0,1]
	v_max_f32_e32 v45, v24, v24
	v_mul_f32_e64 v24, |v48|, s69
	v_max_f32_e32 v52, v25, v25
	v_mul_f32_e64 v25, |v49|, s69
	v_exp_f32_e32 v24, v24
	v_exp_f32_e32 v25, v25
	v_mov_b32_e32 v56, v61
	v_max_f32_e32 v28, v28, v45
	v_add_f32_e32 v24, 1.0, v24
	v_add_f32_e32 v25, 1.0, v25
	v_max_f32_e32 v29, v29, v52
	v_log_f32_e32 v24, v24
	v_log_f32_e32 v25, v25
	v_mul_f32_e32 v53, 0x3f317217, v24
	v_mul_f32_e32 v58, 0x3f317217, v25
	v_fma_f32 v53, v24, s75, -v53
	v_fma_f32 v58, v25, s75, -v58
	v_fmac_f32_e32 v53, 0x3377d1cf, v24
	v_fmac_f32_e32 v58, 0x3377d1cf, v25
	v_fmac_f32_e32 v53, 0x3f317217, v24
	v_fmac_f32_e32 v58, 0x3f317217, v25
	s_nop 0
	v_mov_b32_e32 v24, v53
	v_mov_b32_e32 v53, v24
	v_mov_b32_e32 v25, v58
	v_add_f32_e32 v58, 1.0, v55
	v_mov_b32_e32 v52, v25
	v_mov_b32_e32 v24, v56
	v_mov_b32_e32 v25, v58
	v_log_f32_e32 v25, v25
	v_max_f32_e32 v45, v35, v35
	v_min_f32_e32 v45, 0, v45
	v_mul_f32_e32 v56, 0x3f317217, v25
	v_fma_f32 v56, v25, s75, -v56
	v_fmac_f32_e32 v56, 0x3377d1cf, v25
	v_fmac_f32_e32 v56, 0x3f317217, v25
	s_nop 1
	v_mov_b32_e32 v25, v56
	v_pk_add_f32 v[24:25], v[44:45], v[24:25] neg_lo:[0,1] neg_hi:[0,1]
	s_nop 0
	v_pk_add_f32 v[30:31], v[24:25], v[30:31]
	s_nop 0
	v_pk_add_f32 v[44:45], v[30:31], v[26:27] neg_lo:[0,1] neg_hi:[0,1]
	v_mul_f32_e64 v24, |v44|, s69
	v_exp_f32_e32 v56, v24
	v_pk_mul_f32 v[24:25], v[46:47], v[38:39]
	v_mul_f32_e64 v47, |v45|, s69
	v_exp_f32_e32 v47, v47
	v_add_f32_e32 v39, 1.0, v56
	v_max_f32_e32 v26, v30, v26
	v_add_f32_e32 v47, 1.0, v47
	v_log_f32_e32 v46, v39
	v_pk_mul_f32 v[24:25], v[50:51], v[24:25]
	v_max_f32_e32 v27, v31, v27
	v_mul_f32_e32 v30, 0x3f317217, v46
	v_fma_f32 v30, v46, s75, -v30
	v_fmac_f32_e32 v30, 0x3377d1cf, v46
	v_fmac_f32_e32 v30, 0x3f317217, v46
	v_rcp_f32_e32 v38, v57
	v_rcp_f32_e32 v39, v58
	s_nop 0
	v_log_f32_e32 v47, v47
	v_cmp_lt_f32_e64 vcc, |v49|, s49
	v_mul_f32_e32 v31, 0x3f317217, v47
	v_fma_f32 v31, v47, s75, -v31
	v_fmac_f32_e32 v31, 0x3377d1cf, v47
	v_fmac_f32_e32 v31, 0x3f317217, v47
	s_nop 1
	v_cndmask_b32_e32 v47, 0, v52, vcc
	v_cmp_lt_f32_e64 vcc, |v48|, s49
	s_nop 0
	s_nop 0
	v_cndmask_b32_e32 v46, 0, v53, vcc
	v_cmp_lt_f32_e64 vcc, |v45|, s49
	v_pk_add_f32 v[28:29], v[28:29], v[46:47]
	s_nop 0
	v_cndmask_b32_e32 v31, 0, v31, vcc
	v_cmp_lt_f32_e64 vcc, |v44|, s49
	s_nop 1
	v_cndmask_b32_e32 v30, 0, v30, vcc
	v_cmp_lt_f32_e32 vcc, 0, v35
	v_pk_add_f32 v[30:31], v[26:27], v[30:31]
	s_nop 0
	v_cndmask_b32_e32 v27, 1.0, v55, vcc
	v_cmp_lt_f32_e32 vcc, 0, v34
	s_nop 1
	v_cndmask_b32_e32 v26, 1.0, v54, vcc
	v_pk_mul_f32 v[26:27], v[26:27], v[40:41]
	s_nop 0
	v_pk_mul_f32 v[26:27], v[38:39], v[26:27]
	v_lshl_add_u64 v[38:39], v[42:43], 2, s[94:95]
	global_store_dwordx4 v[38:39], v[28:31], off

.LBB0_1458:
	s_add_u32 s0, s22, s0
	s_addc_u32 s1, s23, s1
	v_mov_b32_e32 v67, v66
	v_lshl_add_u64 v[20:21], v[20:21], 1, s[0:1]
	v_cvt_pk_bf16_f32 v24, v24, v25
	v_cvt_pk_bf16_f32 v25, v26, v27
	v_or_b32_e32 v64, v64, v168
	v_pk_mul_f32 v[34:35], v[22:23], v[66:67]
	s_and_b64 vcc, exec, s[10:11]
	s_mov_b64 s[0:1], -1
	global_store_dwordx2 v[20:21], v[24:25], off offset:16
	s_cbranch_vccnz .LBB0_1460
	v_lshlrev_b32_e32 v20, 2, v194
	v_lshlrev_b32_e32 v28, 2, v168
	global_load_dwordx4 v[24:27], v20, s[86:87] offset:48
	s_nop 0
	global_load_dwordx4 v[20:23], v28, s[66:67]
	v_mul_f32_e64 v36, |v32|, s69
	global_load_dwordx4 v[28:31], v28, s[56:57]
	v_max_f32_e32 v37, v32, v32
	v_mul_f32_e64 v38, |v33|, s69
	v_exp_f32_e32 v45, v36
	v_min_f32_e32 v40, 0, v37
	v_exp_f32_e32 v37, v38
	v_max_f32_e32 v39, v33, v33
	v_mul_f32_e64 v44, |v35|, s69
	v_cmp_lt_f32_e32 vcc, 0, v33
	v_min_f32_e32 v41, 0, v39
	v_exp_f32_e32 v47, v44
	v_add_f32_e32 v44, 1.0, v45
	v_cndmask_b32_e32 v39, 1.0, v37, vcc
	v_cmp_lt_f32_e32 vcc, 0, v32
	v_add_f32_e32 v48, 1.0, v37
	s_nop 0
	v_cndmask_b32_e32 v38, 1.0, v45, vcc
	v_mov_b32_e32 v45, v48
	v_mov_b32_e32 v37, v44
	v_log_f32_e32 v37, v37
	v_log_f32_e32 v45, v45
	v_mul_f32_e64 v42, |v34|, s69
	v_exp_f32_e32 v46, v42
	v_mul_f32_e32 v53, 0x3f317217, v37
	v_mul_f32_e32 v54, 0x3f317217, v45
	v_fma_f32 v53, v37, s75, -v53
	v_fma_f32 v54, v45, s75, -v54
	v_fmac_f32_e32 v53, 0x3377d1cf, v37
	v_rcp_f32_e32 v42, v44
	v_fmac_f32_e32 v54, 0x3377d1cf, v45
	v_fmac_f32_e32 v53, 0x3f317217, v37
	v_max_f32_e32 v43, v34, v34
	v_add_f32_e32 v49, 1.0, v46
	v_fmac_f32_e32 v54, 0x3f317217, v45
	v_mov_b32_e32 v37, v53
	v_min_f32_e32 v36, 0, v43
	v_rcp_f32_e32 v43, v48
	v_mov_b32_e32 v45, v54
	v_mov_b32_e32 v44, v37
	v_mov_b32_e32 v51, v49
	v_pk_add_f32 v[40:41], v[40:41], v[44:45] neg_lo:[0,1] neg_hi:[0,1]
	v_log_f32_e32 v51, v51
	v_add_f32_e32 v50, 1.0, v47
	s_mov_b64 s[0:1], 0
	v_mul_f32_e32 v55, 0x3f317217, v51
	v_fma_f32 v55, v51, s75, -v55
	v_fmac_f32_e32 v55, 0x3377d1cf, v51
	v_fmac_f32_e32 v55, 0x3f317217, v51
	s_waitcnt vmcnt(0)
	v_pk_add_f32 v[40:41], v[40:41], v[24:25]
	s_nop 0
	v_pk_add_f32 v[24:25], v[40:41], v[20:21] neg_lo:[0,1] neg_hi:[0,1]
	v_max_f32_e32 v37, v20, v20
	v_mul_f32_e64 v20, |v24|, s69
	v_max_f32_e32 v44, v21, v21
	v_mul_f32_e64 v21, |v25|, s69
	v_exp_f32_e32 v45, v20
	v_exp_f32_e32 v48, v21
	v_max_f32_e32 v20, v40, v37
	v_mov_b32_e32 v51, v55
	v_add_f32_e32 v37, 1.0, v45
	v_add_f32_e32 v40, 1.0, v48
	v_max_f32_e32 v21, v41, v44
	v_log_f32_e32 v37, v37
	v_log_f32_e32 v40, v40
	v_mul_f32_e32 v45, 0x3f317217, v37
	v_mul_f32_e32 v48, 0x3f317217, v40
	v_fma_f32 v45, v37, s75, -v45
	v_fma_f32 v48, v40, s75, -v48
	v_fmac_f32_e32 v45, 0x3377d1cf, v37
	v_fmac_f32_e32 v48, 0x3377d1cf, v40
	v_fmac_f32_e32 v45, 0x3f317217, v37
	v_fmac_f32_e32 v48, 0x3f317217, v40
	v_pk_mul_f32 v[28:29], v[38:39], v[28:29]
	v_mov_b32_e32 v37, v45
	v_mov_b32_e32 v45, v37
	v_pk_mul_f32 v[28:29], v[42:43], v[28:29]
	v_mov_b32_e32 v40, v48
	v_mov_b32_e32 v44, v40
	v_mov_b32_e32 v40, v51
	v_mov_b32_e32 v37, v50
	v_log_f32_e32 v41, v37
	v_max_f32_e32 v37, v35, v35
	v_min_f32_e32 v37, 0, v37
	v_rcp_f32_e32 v38, v49
	v_mul_f32_e32 v48, 0x3f317217, v41
	v_fma_f32 v48, v41, s75, -v48
	v_fmac_f32_e32 v48, 0x3377d1cf, v41
	v_fmac_f32_e32 v48, 0x3f317217, v41
	s_nop 1
	v_mov_b32_e32 v41, v48
	v_pk_add_f32 v[36:37], v[36:37], v[40:41] neg_lo:[0,1] neg_hi:[0,1]
	s_nop 0
	v_pk_add_f32 v[26:27], v[36:37], v[26:27]
	s_nop 0
	v_pk_add_f32 v[36:37], v[26:27], v[22:23] neg_lo:[0,1] neg_hi:[0,1]
	v_mul_f32_e64 v40, |v36|, s69
	v_exp_f32_e32 v40, v40
	v_mul_f32_e64 v41, |v37|, s69
	v_exp_f32_e32 v41, v41
	v_max_f32_e32 v22, v26, v22
	v_add_f32_e32 v39, 1.0, v40
	v_add_f32_e32 v41, 1.0, v41
	s_nop 0
	v_log_f32_e32 v40, v39
	v_max_f32_e32 v23, v27, v23
	v_rcp_f32_e32 v39, v50
	v_mul_f32_e32 v26, 0x3f317217, v40
	v_fma_f32 v26, v40, s75, -v26
	v_fmac_f32_e32 v26, 0x3377d1cf, v40
	v_fmac_f32_e32 v26, 0x3f317217, v40
	s_nop 1
	s_nop 0
	v_log_f32_e32 v41, v41
	v_cmp_lt_f32_e64 vcc, |v25|, s49
	v_mul_f32_e32 v27, 0x3f317217, v41
	v_fma_f32 v27, v41, s75, -v27
	v_fmac_f32_e32 v27, 0x3377d1cf, v41
	v_fmac_f32_e32 v27, 0x3f317217, v41
	v_cndmask_b32_e32 v25, 0, v44, vcc
	v_cmp_lt_f32_e64 vcc, |v24|, s49
	s_nop 1
	v_cndmask_b32_e32 v24, 0, v45, vcc
	v_cmp_lt_f32_e64 vcc, |v37|, s49
	v_pk_add_f32 v[20:21], v[20:21], v[24:25]
	s_nop 0
	v_cndmask_b32_e32 v27, 0, v27, vcc
	v_cmp_lt_f32_e64 vcc, |v36|, s49
	s_nop 1
	v_cndmask_b32_e32 v26, 0, v26, vcc
	v_cmp_lt_f32_e32 vcc, 0, v35
	v_pk_add_f32 v[22:23], v[22:23], v[26:27]
	v_lshl_add_u64 v[26:27], v[64:65], 2, s[94:95]
	v_cndmask_b32_e32 v25, 1.0, v47, vcc
	v_cmp_lt_f32_e32 vcc, 0, v34
	global_store_dwordx4 v[26:27], v[20:23], off
	s_nop 0
	v_cndmask_b32_e32 v24, 1.0, v46, vcc
	v_pk_mul_f32 v[24:25], v[24:25], v[30:31]
	v_lshl_add_u64 v[20:21], v[64:65], 1, s[84:85]
	v_pk_mul_f32 v[24:25], v[38:39], v[24:25]
	v_cvt_pk_bf16_f32 v22, v28, v29
	v_cvt_pk_bf16_f32 v23, v24, v25
	global_store_dwordx2 v[20:21], v[22:23], off

.LBB0_1481:
	s_and_b64 vcc, exec, s[0:1]
	s_cbranch_vccz .LBB0_1498
	s_mov_b64 s[0:1], -1
	s_and_b64 vcc, exec, s[10:11]
	v_lshlrev_b32_e32 v44, 2, v194
	s_cbranch_vccnz .LBB0_1484
	global_load_dwordx4 v[40:43], v44, s[86:87]
	global_load_dwordx4 v[36:39], v44, s[66:67]
	global_load_dwordx4 v[32:35], v44, s[56:57]
	v_mul_f32_e64 v4, |v28|, s69
	v_max_f32_e32 v5, v28, v28
	v_mul_f32_e64 v9, |v29|, s69
	v_exp_f32_e32 v22, v4
	v_min_f32_e32 v8, 0, v5
	v_exp_f32_e32 v5, v9
	v_mul_f32_e64 v13, |v30|, s69
	v_max_f32_e32 v18, v30, v30
	v_cmp_lt_f32_e32 vcc, 0, v29
	v_max_f32_e32 v12, v29, v29
	v_mul_f32_e64 v19, |v31|, s69
	v_exp_f32_e32 v45, v13
	v_min_f32_e32 v4, 0, v18
	v_add_f32_e32 v18, 1.0, v22
	v_cndmask_b32_e32 v13, 1.0, v5, vcc
	v_cmp_lt_f32_e32 vcc, 0, v28
	v_min_f32_e32 v9, 0, v12
	v_exp_f32_e32 v46, v19
	v_add_f32_e32 v19, 1.0, v5
	v_cndmask_b32_e32 v12, 1.0, v22, vcc
	v_rcp_f32_e32 v23, v19
	v_mov_b32_e32 v5, v18
	v_log_f32_e32 v5, v5
	v_log_f32_e32 v19, v19
	v_rcp_f32_e32 v22, v18
	v_mul_f32_e32 v55, 0x3f317217, v5
	v_mul_f32_e32 v56, 0x3f317217, v19
	v_fma_f32 v55, v5, s75, -v55
	v_fma_f32 v56, v19, s75, -v56
	v_fmac_f32_e32 v55, 0x3377d1cf, v5
	v_fmac_f32_e32 v56, 0x3377d1cf, v19
	v_fmac_f32_e32 v55, 0x3f317217, v5
	v_add_f32_e32 v47, 1.0, v45
	v_fmac_f32_e32 v56, 0x3f317217, v19
	v_mov_b32_e32 v5, v55
	v_mov_b32_e32 v19, v56
	v_mov_b32_e32 v18, v5
	v_mov_b32_e32 v27, v47
	v_pk_add_f32 v[8:9], v[8:9], v[18:19] neg_lo:[0,1] neg_hi:[0,1]
	v_log_f32_e32 v27, v27
	v_add_f32_e32 v51, 1.0, v46
	s_mov_b64 s[0:1], 0
	v_mul_f32_e32 v57, 0x3f317217, v27
	v_fma_f32 v57, v27, s75, -v57
	v_fmac_f32_e32 v57, 0x3377d1cf, v27
	v_fmac_f32_e32 v57, 0x3f317217, v27
	s_waitcnt vmcnt(0)
	v_pk_add_f32 v[8:9], v[8:9], v[40:41]
	s_nop 0
	v_pk_add_f32 v[18:19], v[8:9], v[36:37] neg_lo:[0,1] neg_hi:[0,1]
	v_max_f32_e32 v5, v36, v36
	v_mul_f32_e64 v36, |v18|, s69
	v_max_f32_e32 v26, v37, v37
	v_mul_f32_e64 v37, |v19|, s69
	v_exp_f32_e32 v36, v36
	v_exp_f32_e32 v37, v37
	v_max_f32_e32 v8, v8, v5
	v_mov_b32_e32 v27, v57
	v_add_f32_e32 v5, 1.0, v36
	v_max_f32_e32 v9, v9, v26
	v_add_f32_e32 v26, 1.0, v37
	s_nop 0
	v_log_f32_e32 v5, v5
	v_log_f32_e32 v26, v26
	v_mul_f32_e32 v40, 0x3f317217, v5
	v_mul_f32_e32 v41, 0x3f317217, v26
	v_fma_f32 v40, v5, s75, -v40
	v_fma_f32 v41, v26, s75, -v41
	v_fmac_f32_e32 v40, 0x3377d1cf, v5
	v_fmac_f32_e32 v41, 0x3377d1cf, v26
	v_fmac_f32_e32 v40, 0x3f317217, v5
	v_fmac_f32_e32 v41, 0x3f317217, v26
	s_nop 0
	v_mov_b32_e32 v5, v40
	v_mov_b32_e32 v40, v5
	s_nop 0
	v_mov_b32_e32 v26, v41
	v_mov_b32_e32 v41, v26
	v_mov_b32_e32 v26, v27
	v_mov_b32_e32 v5, v51
	v_log_f32_e32 v36, v5
	v_max_f32_e32 v5, v31, v31
	v_min_f32_e32 v5, 0, v5
	v_mul_f32_e32 v27, 0x3f317217, v36
	v_fma_f32 v27, v36, s75, -v27
	v_fmac_f32_e32 v27, 0x3377d1cf, v36
	v_fmac_f32_e32 v27, 0x3f317217, v36
	s_nop 1
	v_pk_add_f32 v[4:5], v[4:5], v[26:27] neg_lo:[0,1] neg_hi:[0,1]
	s_nop 0
	v_pk_add_f32 v[26:27], v[4:5], v[42:43]
	s_nop 0
	v_pk_add_f32 v[36:37], v[26:27], v[38:39] neg_lo:[0,1] neg_hi:[0,1]
	s_nop 0
	v_mul_f32_e64 v4, |v36|, s69
	v_exp_f32_e32 v42, v4
	v_pk_mul_f32 v[4:5], v[12:13], v[32:33]
	v_mul_f32_e64 v32, |v37|, s69
	v_pk_mul_f32 v[4:5], v[22:23], v[4:5]
	v_add_f32_e32 v13, 1.0, v42
	v_exp_f32_e32 v32, v32
	v_rcp_f32_e32 v12, v47
	v_log_f32_e32 v23, v13
	v_max_f32_e32 v22, v26, v38
	v_add_f32_e32 v32, 1.0, v32
	v_mul_f32_e32 v26, 0x3f317217, v23
	v_fma_f32 v26, v23, s75, -v26
	v_fmac_f32_e32 v26, 0x3377d1cf, v23
	v_fmac_f32_e32 v26, 0x3f317217, v23
	v_rcp_f32_e32 v13, v51
	s_nop 0
	v_mov_b32_e32 v23, v26
	v_mov_b32_e32 v26, v23
	s_nop 0
	v_log_f32_e32 v32, v32
	v_max_f32_e32 v23, v27, v39
	v_mul_f32_e32 v27, 0x3f317217, v32
	v_fma_f32 v27, v32, s75, -v27
	v_fmac_f32_e32 v27, 0x3377d1cf, v32
	v_fmac_f32_e32 v27, 0x3f317217, v32
	s_nop 1
	v_cmp_lt_f32_e64 vcc, |v19|, s49
	s_nop 0
	s_nop 0
	v_cndmask_b32_e32 v19, 0, v41, vcc
	v_cmp_lt_f32_e64 vcc, |v18|, s49
	s_nop 1
	v_cndmask_b32_e32 v18, 0, v40, vcc
	v_cmp_lt_f32_e64 vcc, |v37|, s49
	s_nop 1
	v_cndmask_b32_e32 v27, 0, v27, vcc
	v_cmp_lt_f32_e64 vcc, |v36|, s49
	v_pk_add_f32 v[36:37], v[8:9], v[18:19]
	s_nop 0
	v_cndmask_b32_e32 v26, 0, v26, vcc
	v_cmp_lt_f32_e32 vcc, 0, v31
	v_pk_add_f32 v[38:39], v[22:23], v[26:27]
	s_nop 0
	v_cndmask_b32_e32 v9, 1.0, v46, vcc
	v_cmp_lt_f32_e32 vcc, 0, v30
	s_nop 1
	v_cndmask_b32_e32 v8, 1.0, v45, vcc
	v_pk_mul_f32 v[8:9], v[8:9], v[34:35]
	s_nop 0
	v_pk_mul_f32 v[8:9], v[12:13], v[8:9]
	v_lshl_add_u64 v[12:13], v[52:53], 2, s[94:95]
	global_store_dwordx4 v[12:13], v[36:39], off

.LBB0_1486:
	s_add_u32 s0, s22, s0
	s_addc_u32 s1, s23, s1
	v_lshl_add_u64 v[12:13], v[52:53], 1, s[0:1]
	v_cvt_pk_bf16_f32 v4, v4, v5
	v_cvt_pk_bf16_f32 v5, v8, v9
	v_mov_b32_e32 v51, v50
	global_store_dwordx2 v[12:13], v[4:5], off
	v_pk_mul_f32 v[4:5], v[14:15], v[50:51]
	s_and_b64 vcc, exec, s[10:11]
	s_mov_b64 s[0:1], -1
	s_cbranch_vccnz .LBB0_1488
	global_load_dwordx4 v[26:29], v44, s[86:87] offset:16
	v_lshlrev_b32_e32 v18, 2, v170
	global_load_dwordx4 v[12:15], v18, s[66:67]
	global_load_dwordx4 v[30:33], v18, s[56:57]
	v_mul_f32_e64 v19, |v24|, s69
	v_mul_f32_e64 v23, |v25|, s69
	v_exp_f32_e32 v40, v19
	v_exp_f32_e32 v23, v23
	v_mul_f32_e64 v35, |v4|, s69
	v_cmp_lt_f32_e32 vcc, 0, v25
	v_max_f32_e32 v34, v25, v25
	v_exp_f32_e32 v38, v35
	v_add_f32_e32 v41, 1.0, v40
	v_cndmask_b32_e32 v35, 1.0, v23, vcc
	v_cmp_lt_f32_e32 vcc, 0, v24
	v_min_f32_e32 v19, 0, v34
	v_add_f32_e32 v42, 1.0, v23
	v_cndmask_b32_e32 v34, 1.0, v40, vcc
	v_max_f32_e32 v22, v24, v24
	v_mov_b32_e32 v23, v41
	v_mov_b32_e32 v40, v42
	v_log_f32_e32 v23, v23
	v_log_f32_e32 v40, v40
	v_max_f32_e32 v36, v4, v4
	v_add_f32_e32 v43, 1.0, v38
	v_mul_f32_e32 v46, 0x3f317217, v23
	v_mul_f32_e32 v47, 0x3f317217, v40
	v_fma_f32 v46, v23, s75, -v46
	v_fma_f32 v47, v40, s75, -v47
	v_fmac_f32_e32 v46, 0x3377d1cf, v23
	v_min_f32_e32 v18, 0, v22
	v_min_f32_e32 v22, 0, v36
	v_rcp_f32_e32 v36, v41
	v_fmac_f32_e32 v47, 0x3377d1cf, v40
	v_fmac_f32_e32 v46, 0x3f317217, v23
	v_mul_f32_e64 v37, |v5|, s69
	v_fmac_f32_e32 v47, 0x3f317217, v40
	v_mov_b32_e32 v23, v46
	v_exp_f32_e32 v39, v37
	v_rcp_f32_e32 v37, v42
	v_mov_b32_e32 v42, v43
	v_mov_b32_e32 v46, v47
	v_mov_b32_e32 v40, v23
	v_mov_b32_e32 v41, v46
	v_pk_add_f32 v[18:19], v[18:19], v[40:41] neg_lo:[0,1] neg_hi:[0,1]
	v_log_f32_e32 v42, v42
	v_or_b32_e32 v8, v48, v170
	v_mov_b32_e32 v9, v49
	v_lshl_add_u64 v[8:9], v[8:9], 2, s[94:95]
	v_mul_f32_e32 v51, 0x3f317217, v42
	v_fma_f32 v51, v42, s75, -v51
	v_fmac_f32_e32 v51, 0x3377d1cf, v42
	v_fmac_f32_e32 v51, 0x3f317217, v42
	s_mov_b64 s[0:1], 0
	s_waitcnt vmcnt(0)
	v_pk_add_f32 v[26:27], v[18:19], v[26:27]
	v_mov_b32_e32 v42, v51
	v_pk_add_f32 v[18:19], v[26:27], v[12:13] neg_lo:[0,1] neg_hi:[0,1]
	v_max_f32_e32 v23, v12, v12
	v_mul_f32_e64 v12, |v18|, s69
	v_mul_f32_e64 v40, |v19|, s69
	v_exp_f32_e32 v41, v12
	v_exp_f32_e32 v40, v40
	v_max_f32_e32 v12, v26, v23
	v_add_f32_e32 v23, 1.0, v41
	v_add_f32_e32 v26, 1.0, v40
	v_max_f32_e32 v13, v27, v13
	v_log_f32_e32 v23, v23
	v_log_f32_e32 v26, v26
	v_mul_f32_e32 v41, 0x3f317217, v23
	v_mul_f32_e32 v45, 0x3f317217, v26
	v_fma_f32 v41, v23, s75, -v41
	v_fma_f32 v45, v26, s75, -v45
	v_fmac_f32_e32 v41, 0x3377d1cf, v23
	v_fmac_f32_e32 v45, 0x3377d1cf, v26
	v_fmac_f32_e32 v41, 0x3f317217, v23
	v_fmac_f32_e32 v45, 0x3f317217, v26
	s_nop 0
	v_mov_b32_e32 v23, v41
	v_mov_b32_e32 v41, v23
	v_mov_b32_e32 v26, v45
	v_add_f32_e32 v45, 1.0, v39
	v_mov_b32_e32 v40, v26
	s_nop 0
	v_mov_b32_e32 v26, v45
	v_log_f32_e32 v27, v26
	v_mov_b32_e32 v26, v42
	v_max_f32_e32 v23, v5, v5
	v_min_f32_e32 v23, 0, v23
	v_mul_f32_e32 v42, 0x3f317217, v27
	v_fma_f32 v42, v27, s75, -v42
	v_fmac_f32_e32 v42, 0x3377d1cf, v27
	v_fmac_f32_e32 v42, 0x3f317217, v27
	s_nop 1
	v_mov_b32_e32 v27, v42
	v_pk_add_f32 v[22:23], v[22:23], v[26:27] neg_lo:[0,1] neg_hi:[0,1]
	s_nop 0
	v_pk_add_f32 v[26:27], v[22:23], v[28:29]
	s_nop 0
	v_pk_add_f32 v[28:29], v[26:27], v[14:15] neg_lo:[0,1] neg_hi:[0,1]
	v_mul_f32_e64 v22, |v28|, s69
	v_exp_f32_e32 v42, v22
	v_pk_mul_f32 v[22:23], v[34:35], v[30:31]
	v_mul_f32_e64 v35, |v29|, s69
	v_exp_f32_e32 v35, v35
	v_add_f32_e32 v31, 1.0, v42
	v_max_f32_e32 v14, v26, v14
	v_add_f32_e32 v35, 1.0, v35
	v_log_f32_e32 v34, v31
	v_pk_mul_f32 v[22:23], v[36:37], v[22:23]
	v_max_f32_e32 v15, v27, v15
	v_mul_f32_e32 v26, 0x3f317217, v34
	v_fma_f32 v26, v34, s75, -v26
	v_fmac_f32_e32 v26, 0x3377d1cf, v34
	v_fmac_f32_e32 v26, 0x3f317217, v34
	v_rcp_f32_e32 v30, v43
	v_rcp_f32_e32 v31, v45
	s_nop 0
	v_log_f32_e32 v35, v35
	v_cmp_lt_f32_e64 vcc, |v19|, s49
	v_mul_f32_e32 v27, 0x3f317217, v35
	v_fma_f32 v27, v35, s75, -v27
	v_fmac_f32_e32 v27, 0x3377d1cf, v35
	v_fmac_f32_e32 v27, 0x3f317217, v35
	v_cndmask_b32_e32 v19, 0, v40, vcc
	v_cmp_lt_f32_e64 vcc, |v18|, s49
	s_nop 1
	v_cndmask_b32_e32 v18, 0, v41, vcc
	v_cmp_lt_f32_e64 vcc, |v29|, s49
	s_nop 1
	v_cndmask_b32_e32 v27, 0, v27, vcc
	v_cmp_lt_f32_e64 vcc, |v28|, s49
	s_nop 1
	v_cndmask_b32_e32 v26, 0, v26, vcc
	v_cmp_lt_f32_e32 vcc, 0, v5
	v_pk_add_f32 v[28:29], v[14:15], v[26:27]
	v_pk_add_f32 v[26:27], v[12:13], v[18:19]
	v_cndmask_b32_e32 v13, 1.0, v39, vcc
	v_cmp_lt_f32_e32 vcc, 0, v4
	global_store_dwordx4 v[8:9], v[26:29], off
	s_nop 0
	v_cndmask_b32_e32 v12, 1.0, v38, vcc
	v_pk_mul_f32 v[12:13], v[12:13], v[32:33]
	s_nop 0
	v_pk_mul_f32 v[12:13], v[30:31], v[12:13]

.LBB0_1490:
	s_add_u32 s0, s22, s0
	s_addc_u32 s1, s23, s1
	v_lshl_add_u64 v[4:5], v[48:49], 0, v[194:195]
	v_mov_b32_e32 v51, v50
	v_lshl_add_u64 v[8:9], v[4:5], 1, s[0:1]
	v_cvt_pk_bf16_f32 v14, v22, v23
	v_cvt_pk_bf16_f32 v15, v12, v13
	v_pk_mul_f32 v[18:19], v[10:11], v[50:51]
	s_and_b64 vcc, exec, s[10:11]
	s_mov_b64 s[0:1], -1
	global_store_dwordx2 v[8:9], v[14:15], off offset:8
	s_cbranch_vccnz .LBB0_1492
	global_load_dwordx4 v[22:25], v44, s[86:87] offset:32
	v_lshlrev_b32_e32 v8, 2, v169
	global_load_dwordx4 v[12:15], v8, s[66:67]
	s_nop 0
	global_load_dwordx4 v[8:11], v8, s[56:57]
	v_mul_f32_e64 v28, |v20|, s69
	v_exp_f32_e32 v36, v28
	v_max_f32_e32 v28, v20, v20
	v_min_f32_e32 v28, 0, v28
	v_or_b32_e32 v26, v48, v169
	v_add_f32_e32 v29, 1.0, v36
	v_rcp_f32_e32 v30, v29
	v_mov_b32_e32 v27, v49
	v_log_f32_e32 v29, v29
	s_mov_b64 s[0:1], 0
	v_mul_f32_e32 v31, 0x3f317217, v29
	v_fma_f32 v31, v29, s75, -v31
	v_fmac_f32_e32 v31, 0x3377d1cf, v29
	v_fmac_f32_e32 v31, 0x3f317217, v29
	s_nop 1
	v_mov_b32_e32 v29, v31
	v_mov_b32_e32 v32, v29
	v_mul_f32_e64 v29, |v21|, s69
	v_exp_f32_e32 v37, v29
	v_max_f32_e32 v29, v21, v21
	v_min_f32_e32 v29, 0, v29
	v_add_f32_e32 v33, 1.0, v37
	v_rcp_f32_e32 v31, v33
	s_nop 0
	v_log_f32_e32 v33, v33
	s_nop 0
	v_mul_f32_e32 v34, 0x3f317217, v33
	v_fma_f32 v34, v33, s75, -v34
	v_fmac_f32_e32 v34, 0x3377d1cf, v33
	v_fmac_f32_e32 v34, 0x3f317217, v33
	s_nop 1
	v_mov_b32_e32 v33, v34
	v_pk_add_f32 v[28:29], v[28:29], v[32:33] neg_lo:[0,1] neg_hi:[0,1]
	s_waitcnt vmcnt(0)
	v_pk_add_f32 v[32:33], v[28:29], v[22:23]
	s_nop 0
	v_pk_add_f32 v[28:29], v[32:33], v[12:13] neg_lo:[0,1] neg_hi:[0,1]
	v_max_f32_e32 v22, v12, v12
	v_mul_f32_e64 v12, |v28|, s69
	v_exp_f32_e32 v12, v12
	v_max_f32_e32 v22, v32, v22
	v_cmp_lt_f32_e64 s[8:9], |v28|, s49
	v_cmp_lt_f32_e64 s[12:13], |v29|, s49
	v_add_f32_e32 v12, 1.0, v12
	s_nop 1
	v_log_f32_e32 v12, v12
	s_nop 0
	v_mul_f32_e32 v23, 0x3f317217, v12
	v_fma_f32 v23, v12, s75, -v23
	v_fmac_f32_e32 v23, 0x3377d1cf, v12
	v_fmac_f32_e32 v23, 0x3f317217, v12
	s_nop 1
	v_mov_b32_e32 v12, v23
	v_mov_b32_e32 v34, v12
	v_max_f32_e32 v23, v33, v13
	v_mul_f32_e64 v12, |v29|, s69
	v_exp_f32_e32 v12, v12
	s_nop 0
	v_add_f32_e32 v12, 1.0, v12
	s_nop 1
	v_log_f32_e32 v12, v12
	s_nop 0
	v_mul_f32_e32 v13, 0x3f317217, v12
	v_fma_f32 v13, v12, s75, -v13
	v_fmac_f32_e32 v13, 0x3377d1cf, v12
	v_fmac_f32_e32 v13, 0x3f317217, v12
	s_nop 1
	v_mov_b32_e32 v12, v13
	v_cmp_lt_f32_e32 vcc, 0, v20
	v_cmp_lt_f32_e64 s[6:7], 0, v21
	v_mov_b32_e32 v35, v12
	v_cndmask_b32_e32 v12, 1.0, v36, vcc
	v_cndmask_b32_e64 v13, 1.0, v37, s[6:7]
	v_pk_mul_f32 v[8:9], v[12:13], v[8:9]
	v_mul_f32_e64 v12, |v18|, s69
	v_exp_f32_e32 v36, v12
	v_pk_mul_f32 v[8:9], v[30:31], v[8:9]
	v_max_f32_e32 v30, v18, v18
	v_min_f32_e32 v30, 0, v30
	v_add_f32_e32 v13, 1.0, v36
	v_rcp_f32_e32 v12, v13
	s_nop 0
	v_log_f32_e32 v13, v13
	s_nop 0
	v_mul_f32_e32 v31, 0x3f317217, v13
	v_fma_f32 v31, v13, s75, -v31
	v_fmac_f32_e32 v31, 0x3377d1cf, v13
	v_fmac_f32_e32 v31, 0x3f317217, v13
	s_nop 1
	v_mov_b32_e32 v13, v31
	v_mov_b32_e32 v32, v13
	v_mul_f32_e64 v13, |v19|, s69
	v_exp_f32_e32 v37, v13
	v_max_f32_e32 v31, v19, v19
	v_min_f32_e32 v31, 0, v31
	v_add_f32_e32 v33, 1.0, v37
	v_rcp_f32_e32 v13, v33
	s_nop 0
	v_log_f32_e32 v33, v33
	s_nop 0
	v_mul_f32_e32 v38, 0x3f317217, v33
	v_fma_f32 v38, v33, s75, -v38
	v_fmac_f32_e32 v38, 0x3377d1cf, v33
	v_fmac_f32_e32 v38, 0x3f317217, v33
	s_nop 1
	v_mov_b32_e32 v33, v38
	v_pk_add_f32 v[30:31], v[30:31], v[32:33] neg_lo:[0,1] neg_hi:[0,1]
	s_nop 0
	v_pk_add_f32 v[24:25], v[30:31], v[24:25]
	v_pk_add_f32 v[32:33], v[24:25], v[14:15] neg_lo:[0,1] neg_hi:[0,1]
	v_max_f32_e32 v30, v24, v14
	v_mul_f32_e64 v14, |v32|, s69
	v_exp_f32_e32 v14, v14
	s_nop 0
	v_add_f32_e32 v14, 1.0, v14
	s_nop 1
	v_log_f32_e32 v14, v14
	s_nop 0
	v_mul_f32_e32 v24, 0x3f317217, v14
	v_fma_f32 v24, v14, s75, -v24
	v_fmac_f32_e32 v24, 0x3377d1cf, v14
	v_fmac_f32_e32 v24, 0x3f317217, v14
	s_nop 1
	v_mov_b32_e32 v14, v24
	v_mov_b32_e32 v24, v14
	v_max_f32_e32 v31, v25, v15
	v_mul_f32_e64 v14, |v33|, s69
	v_exp_f32_e32 v14, v14
	s_nop 0
	v_add_f32_e32 v14, 1.0, v14
	s_nop 1
	v_log_f32_e32 v14, v14
	s_nop 0
	v_mul_f32_e32 v15, 0x3f317217, v14
	v_fma_f32 v15, v14, s75, -v15
	v_fmac_f32_e32 v15, 0x3377d1cf, v14
	v_fmac_f32_e32 v15, 0x3f317217, v14
	s_nop 1
	v_mov_b32_e32 v14, v15
	v_mov_b32_e32 v25, v14
	v_cmp_lt_f32_e64 vcc, |v32|, s49
	v_cmp_lt_f32_e64 s[6:7], |v33|, s49
	v_cndmask_b32_e64 v15, 0, v35, s[12:13]
	v_cndmask_b32_e64 v14, 0, v34, s[8:9]
	v_cndmask_b32_e64 v25, 0, v25, s[6:7]
	v_cndmask_b32_e32 v24, 0, v24, vcc
	v_cmp_lt_f32_e32 vcc, 0, v18
	v_cmp_lt_f32_e64 s[6:7], 0, v19
	v_pk_add_f32 v[22:23], v[22:23], v[14:15]
	v_cndmask_b32_e32 v14, 1.0, v36, vcc
	v_cndmask_b32_e64 v15, 1.0, v37, s[6:7]
	v_pk_mul_f32 v[10:11], v[14:15], v[10:11]
	v_pk_add_f32 v[24:25], v[30:31], v[24:25]
	v_pk_mul_f32 v[10:11], v[12:13], v[10:11]
	v_lshl_add_u64 v[12:13], v[26:27], 2, s[94:95]
	global_store_dwordx4 v[12:13], v[22:25], off

.LBB0_1494:
	s_add_u32 s0, s22, s0
	s_addc_u32 s1, s23, s1
	v_mov_b32_e32 v51, v50
	v_lshl_add_u64 v[4:5], v[4:5], 1, s[0:1]
	v_cvt_pk_bf16_f32 v8, v8, v9
	v_cvt_pk_bf16_f32 v9, v10, v11
	v_or_b32_e32 v48, v48, v168
	v_pk_mul_f32 v[18:19], v[6:7], v[50:51]
	s_and_b64 vcc, exec, s[10:11]
	s_mov_b64 s[0:1], -1
	global_store_dwordx2 v[4:5], v[8:9], off offset:16
	s_cbranch_vccnz .LBB0_1496
	global_load_dwordx4 v[12:15], v44, s[86:87] offset:48
	v_lshlrev_b32_e32 v4, 2, v168
	global_load_dwordx4 v[8:11], v4, s[66:67]
	s_nop 0
	global_load_dwordx4 v[4:7], v4, s[56:57]
	v_mul_f32_e64 v20, |v16|, s69
	v_exp_f32_e32 v28, v20
	v_max_f32_e32 v20, v16, v16
	v_min_f32_e32 v20, 0, v20
	s_mov_b64 s[0:1], 0
	v_add_f32_e32 v21, 1.0, v28
	v_rcp_f32_e32 v22, v21
	s_nop 0
	v_log_f32_e32 v21, v21
	s_nop 0
	v_mul_f32_e32 v23, 0x3f317217, v21
	v_fma_f32 v23, v21, s75, -v23
	v_fmac_f32_e32 v23, 0x3377d1cf, v21
	v_fmac_f32_e32 v23, 0x3f317217, v21
	s_nop 1
	v_mov_b32_e32 v21, v23
	v_mov_b32_e32 v24, v21
	v_mul_f32_e64 v21, |v17|, s69
	v_exp_f32_e32 v29, v21
	v_max_f32_e32 v21, v17, v17
	v_min_f32_e32 v21, 0, v21
	v_add_f32_e32 v25, 1.0, v29
	v_rcp_f32_e32 v23, v25
	s_nop 0
	v_log_f32_e32 v25, v25
	s_nop 0
	v_mul_f32_e32 v26, 0x3f317217, v25
	v_fma_f32 v26, v25, s75, -v26
	v_fmac_f32_e32 v26, 0x3377d1cf, v25
	v_fmac_f32_e32 v26, 0x3f317217, v25
	s_nop 1
	v_mov_b32_e32 v25, v26
	v_pk_add_f32 v[20:21], v[20:21], v[24:25] neg_lo:[0,1] neg_hi:[0,1]
	s_waitcnt vmcnt(0)
	v_pk_add_f32 v[24:25], v[20:21], v[12:13]
	s_nop 0
	v_pk_add_f32 v[20:21], v[24:25], v[8:9] neg_lo:[0,1] neg_hi:[0,1]
	v_max_f32_e32 v12, v8, v8
	v_mul_f32_e64 v8, |v20|, s69
	v_exp_f32_e32 v8, v8
	v_max_f32_e32 v12, v24, v12
	v_cmp_lt_f32_e64 s[8:9], |v20|, s49
	v_cmp_lt_f32_e64 s[10:11], |v21|, s49
	v_add_f32_e32 v8, 1.0, v8
	s_nop 1
	v_log_f32_e32 v8, v8
	s_nop 0
	v_mul_f32_e32 v13, 0x3f317217, v8
	v_fma_f32 v13, v8, s75, -v13
	v_fmac_f32_e32 v13, 0x3377d1cf, v8
	v_fmac_f32_e32 v13, 0x3f317217, v8
	s_nop 1
	v_mov_b32_e32 v8, v13
	v_mov_b32_e32 v26, v8
	v_max_f32_e32 v13, v25, v9
	v_mul_f32_e64 v8, |v21|, s69
	v_exp_f32_e32 v8, v8
	s_nop 0
	v_add_f32_e32 v8, 1.0, v8
	s_nop 1
	v_log_f32_e32 v8, v8
	s_nop 0
	v_mul_f32_e32 v9, 0x3f317217, v8
	v_fma_f32 v9, v8, s75, -v9
	v_fmac_f32_e32 v9, 0x3377d1cf, v8
	v_fmac_f32_e32 v9, 0x3f317217, v8
	s_nop 1
	v_mov_b32_e32 v8, v9
	v_cmp_lt_f32_e32 vcc, 0, v16
	v_cmp_lt_f32_e64 s[6:7], 0, v17
	v_mov_b32_e32 v27, v8
	v_cndmask_b32_e32 v8, 1.0, v28, vcc
	v_cndmask_b32_e64 v9, 1.0, v29, s[6:7]
	v_pk_mul_f32 v[4:5], v[8:9], v[4:5]
	v_mul_f32_e64 v8, |v18|, s69
	v_exp_f32_e32 v28, v8
	v_pk_mul_f32 v[4:5], v[22:23], v[4:5]
	v_max_f32_e32 v22, v18, v18
	v_min_f32_e32 v22, 0, v22
	v_add_f32_e32 v9, 1.0, v28
	v_rcp_f32_e32 v8, v9
	v_cvt_pk_bf16_f32 v4, v4, v5
	v_log_f32_e32 v9, v9
	s_nop 0
	v_mul_f32_e32 v23, 0x3f317217, v9
	v_fma_f32 v23, v9, s75, -v23
	v_fmac_f32_e32 v23, 0x3377d1cf, v9
	v_fmac_f32_e32 v23, 0x3f317217, v9
	s_nop 1
	v_mov_b32_e32 v9, v23
	v_mov_b32_e32 v24, v9
	v_mul_f32_e64 v9, |v19|, s69
	v_exp_f32_e32 v29, v9
	v_max_f32_e32 v23, v19, v19
	v_min_f32_e32 v23, 0, v23
	v_add_f32_e32 v25, 1.0, v29
	v_rcp_f32_e32 v9, v25
	s_nop 0
	v_log_f32_e32 v25, v25
	s_nop 0
	v_mul_f32_e32 v30, 0x3f317217, v25
	v_fma_f32 v30, v25, s75, -v30
	v_fmac_f32_e32 v30, 0x3377d1cf, v25
	v_fmac_f32_e32 v30, 0x3f317217, v25
	s_nop 1
	v_mov_b32_e32 v25, v30
	v_pk_add_f32 v[22:23], v[22:23], v[24:25] neg_lo:[0,1] neg_hi:[0,1]
	s_nop 0
	v_pk_add_f32 v[14:15], v[22:23], v[14:15]
	v_pk_add_f32 v[24:25], v[14:15], v[10:11] neg_lo:[0,1] neg_hi:[0,1]
	v_max_f32_e32 v22, v14, v10
	v_mul_f32_e64 v10, |v24|, s69
	v_exp_f32_e32 v10, v10
	s_nop 0
	v_add_f32_e32 v10, 1.0, v10
	s_nop 1
	v_log_f32_e32 v10, v10
	s_nop 0
	v_mul_f32_e32 v14, 0x3f317217, v10
	v_fma_f32 v14, v10, s75, -v14
	v_fmac_f32_e32 v14, 0x3377d1cf, v10
	v_fmac_f32_e32 v14, 0x3f317217, v10
	s_nop 1
	v_mov_b32_e32 v10, v14
	v_mov_b32_e32 v14, v10
	v_max_f32_e32 v23, v15, v11
	v_mul_f32_e64 v10, |v25|, s69
	v_exp_f32_e32 v10, v10
	s_nop 0
	v_add_f32_e32 v10, 1.0, v10
	s_nop 1
	v_log_f32_e32 v10, v10
	s_nop 0
	v_mul_f32_e32 v11, 0x3f317217, v10
	v_fma_f32 v11, v10, s75, -v11
	v_fmac_f32_e32 v11, 0x3377d1cf, v10
	v_fmac_f32_e32 v11, 0x3f317217, v10
	s_nop 1
	v_mov_b32_e32 v10, v11
	v_mov_b32_e32 v15, v10
	v_cmp_lt_f32_e64 vcc, |v24|, s49
	v_cmp_lt_f32_e64 s[6:7], |v25|, s49
	v_cndmask_b32_e64 v11, 0, v27, s[10:11]
	v_cndmask_b32_e64 v10, 0, v26, s[8:9]
	v_cndmask_b32_e64 v15, 0, v15, s[6:7]
	v_cndmask_b32_e32 v14, 0, v14, vcc
	v_cmp_lt_f32_e32 vcc, 0, v18
	v_cmp_lt_f32_e64 s[6:7], 0, v19
	v_pk_add_f32 v[12:13], v[12:13], v[10:11]
	v_cndmask_b32_e32 v10, 1.0, v28, vcc
	v_cndmask_b32_e64 v11, 1.0, v29, s[6:7]
	v_pk_mul_f32 v[6:7], v[10:11], v[6:7]
	v_pk_add_f32 v[14:15], v[22:23], v[14:15]
	v_pk_mul_f32 v[6:7], v[8:9], v[6:7]
	v_lshl_add_u64 v[8:9], v[48:49], 2, s[94:95]
	global_store_dwordx4 v[8:9], v[12:15], off
	v_lshl_add_u64 v[8:9], v[48:49], 1, s[84:85]
	v_cvt_pk_bf16_f32 v5, v6, v7
	global_store_dwordx2 v[8:9], v[4:5], off
